# GEMM K-loops: drop the per-phase s_setprio 1/0 flips (with the lighter load sections the flips starved the loading wave's DMA issue)
# speedup vs baseline: 1.0208x; 1.0149x over previous
; #define PG8_STAGE(bufoff, gbase, voff) do { _Pragma("unroll") for (int _i = 0; _i < 2; ++_i) \
;         __builtin_amdgcn_global_load_lds((const unsigned*)((const char*)(gbase) + (voff)[_i]), (LAS unsigned*)(lds + (bufoff) + ldsw + _i * 8192), 16, 0, 0); } while (0)
; #define PG8_LDA(dst, b, h) do { _Pragma("unroll") for (int m = 0; m < 4; ++m) _Pragma("unroll") for (int k = 0; k < 2; ++k) dst[m][k] = *(const LAS bf16x8*)(lds + PG8_SA(b, h) + aoff + m * 2048 + k * 1024); } while (0)
; #define PG8_LDB(dst, b, h) do { _Pragma("unroll") for (int n = 0; n < 2; ++n) _Pragma("unroll") for (int k = 0; k < 2; ++k) dst[n][k] = *(const LAS bf16x8*)(lds + PG8_SB(b, h) + boff + n * 2048 + k * 1024); } while (0)
; #define PG8_MMA(ai, bj, At, Bt) do { __builtin_amdgcn_s_setprio(1); _Pragma("unroll") for (int m = 0; m < 4; ++m) _Pragma("unroll") for (int n = 0; n < 2; ++n) _Pragma("unroll") for (int k = 0; k < 2; ++k) \
;         acc[ai][bj][m][n] = __builtin_amdgcn_mfma_f32_16x16x32_bf16(Bt[n][k], At[m][k], acc[ai][bj][m][n], 0, 0, 0); __builtin_amdgcn_s_setprio(0); } while (0)
; #define PG8_WAIT_V(n) asm volatile("s_waitcnt vmcnt(" #n ")" ::: "memory")
; #define PG8_WAIT_L(n) asm volatile("s_waitcnt lgkmcnt(" #n ")" ::: "memory")
; #define PG8_BAR __builtin_amdgcn_s_barrier()
; #define PG8_SCHED __builtin_amdgcn_sched_barrier(0)
; template <class Epi>
; __device__ __forceinline__ void gemm_phase(LAS unsigned char* lds, const Gemm g, const StaticOrder& S, const Epi& E) {
;     ...
;             PG8_LDB(B0, 0, 0); PG8_SCHED; PG8_LDA(At, 0, 0); PG8_STAGE(PG8_SA(1, 1), a1 + hstep, voffA);
;             PG8_WAIT_L(8); PG8_BAR; PG8_WAIT_L(0); PG8_MMA(0, 0, At, B0); PG8_BAR; PG8_SCHED;
;             PG8_LDB(B1, 0, 1); PG8_STAGE(PG8_SB(0, 0), b2, voffB);
;             PG8_BAR; PG8_WAIT_L(0); PG8_MMA(0, 1, At, B1); PG8_BAR;
;             PG8_LDA(At, 0, 1); PG8_STAGE(PG8_SA(0, 0), a2, voffA);
;             PG8_BAR; PG8_WAIT_L(0); PG8_MMA(1, 0, At, B0); PG8_BAR; PG8_SCHED;
;             PG8_STAGE(PG8_SB(0, 1), b2 + hstep, voffB);
;             PG8_WAIT_V(6); PG8_BAR; PG8_MMA(1, 1, At, B1); PG8_BAR;
.LBB0_203:
	ds_read_b128 v[144:147], v153
	ds_read_b128 v[160:163], v153 offset:1024
	ds_read_b128 v[164:167], v153 offset:2048
	ds_read_b128 v[168:171], v153 offset:3072
	s_add_u32 s44, s42, 0xfff80080
	s_addc_u32 s45, s43, -1
	s_cmp_eq_u32 s54, 28
	s_cselect_b32 s47, s25, s45
	s_cselect_b32 s46, s50, s44
	s_cselect_b32 s45, s23, s53
	s_cselect_b32 s44, s51, s52
	s_add_i32 m0, s11, 0xc000
	ds_read_b128 v[172:175], v154
	ds_read_b128 v[176:179], v154 offset:1024
	ds_read_b128 v[180:183], v154 offset:2048
	ds_read_b128 v[184:187], v154 offset:3072
	ds_read_b128 v[188:191], v154 offset:4096
	ds_read_b128 v[192:195], v154 offset:5120
	ds_read_b128 v[196:199], v154 offset:6144
	ds_read_b128 v[200:203], v154 offset:7168
	global_load_lds_dwordx4 v136, s[42:43]
	s_add_i32 m0, s11, 0xe000
	s_nop 0
	global_load_lds_dwordx4 v138, s[42:43]
	s_waitcnt lgkmcnt(8)
	s_barrier
	s_waitcnt lgkmcnt(0)
	s_waitcnt lgkmcnt(0)
	v_mfma_f32_16x16x32_bf16 v[124:127], v[144:147], v[172:175], v[124:127]
	v_mfma_f32_16x16x32_bf16 v[120:123], v[164:167], v[172:175], v[120:123]
	v_mfma_f32_16x16x32_bf16 v[108:111], v[144:147], v[180:183], v[108:111]
	v_mfma_f32_16x16x32_bf16 v[104:107], v[164:167], v[180:183], v[104:107]
	v_mfma_f32_16x16x32_bf16 v[92:95], v[144:147], v[188:191], v[92:95]
	v_mfma_f32_16x16x32_bf16 v[88:91], v[164:167], v[188:191], v[88:91]
	v_mfma_f32_16x16x32_bf16 v[76:79], v[144:147], v[196:199], v[76:79]
	v_mfma_f32_16x16x32_bf16 v[72:75], v[164:167], v[196:199], v[72:75]
	v_mfma_f32_16x16x32_bf16 v[124:127], v[160:163], v[176:179], v[124:127]
	v_mfma_f32_16x16x32_bf16 v[120:123], v[168:171], v[176:179], v[120:123]
	v_mfma_f32_16x16x32_bf16 v[108:111], v[160:163], v[184:187], v[108:111]
	v_mfma_f32_16x16x32_bf16 v[104:107], v[168:171], v[184:187], v[104:107]
	v_mfma_f32_16x16x32_bf16 v[92:95], v[160:163], v[192:195], v[92:95]
	v_mfma_f32_16x16x32_bf16 v[88:91], v[168:171], v[192:195], v[88:91]
	v_mfma_f32_16x16x32_bf16 v[76:79], v[160:163], v[200:203], v[76:79]
	v_mfma_f32_16x16x32_bf16 v[72:75], v[168:171], v[200:203], v[72:75]
	s_barrier
	s_add_i32 s55, s41, s10
	s_add_u32 s98, s44, s8
	s_addc_u32 s99, s45, s9
	s_mov_b32 m0, s55
	ds_read_b128 v[204:207], v155
	ds_read_b128 v[208:211], v155 offset:1024
	ds_read_b128 v[212:215], v155 offset:2048
	ds_read_b128 v[216:219], v155 offset:3072
	global_load_lds_dwordx4 v132, s[44:45]
	s_add_i32 m0, s55, 0x2000
	s_nop 0
	global_load_lds_dwordx4 v128, s[44:45]
	s_barrier
	s_waitcnt lgkmcnt(0)
	s_waitcnt lgkmcnt(0)
	v_mfma_f32_16x16x32_bf16 v[116:119], v[204:207], v[172:175], v[116:119]
	v_mfma_f32_16x16x32_bf16 v[112:115], v[212:215], v[172:175], v[112:115]
	v_mfma_f32_16x16x32_bf16 v[100:103], v[204:207], v[180:183], v[100:103]
	v_mfma_f32_16x16x32_bf16 v[96:99], v[212:215], v[180:183], v[96:99]
	v_mfma_f32_16x16x32_bf16 v[84:87], v[204:207], v[188:191], v[84:87]
	v_mfma_f32_16x16x32_bf16 v[80:83], v[212:215], v[188:191], v[80:83]
	v_mfma_f32_16x16x32_bf16 v[68:71], v[204:207], v[196:199], v[68:71]
	v_mfma_f32_16x16x32_bf16 v[64:67], v[212:215], v[196:199], v[64:67]
	v_mfma_f32_16x16x32_bf16 v[116:119], v[208:211], v[176:179], v[116:119]
	v_mfma_f32_16x16x32_bf16 v[112:115], v[216:219], v[176:179], v[112:115]
	v_mfma_f32_16x16x32_bf16 v[100:103], v[208:211], v[184:187], v[100:103]
	v_mfma_f32_16x16x32_bf16 v[96:99], v[216:219], v[184:187], v[96:99]
	v_mfma_f32_16x16x32_bf16 v[84:87], v[208:211], v[192:195], v[84:87]
	v_mfma_f32_16x16x32_bf16 v[80:83], v[216:219], v[192:195], v[80:83]
	v_mfma_f32_16x16x32_bf16 v[68:71], v[208:211], v[200:203], v[68:71]
	v_mfma_f32_16x16x32_bf16 v[64:67], v[216:219], v[200:203], v[64:67]
	s_mov_b32 m0, s11
	s_add_u32 s100, s46, s8
	s_addc_u32 s101, s47, s9
	s_barrier
	ds_read_b128 v[172:175], v154 offset:16384
	ds_read_b128 v[176:179], v154 offset:17408
	ds_read_b128 v[180:183], v154 offset:18432
	ds_read_b128 v[184:187], v154 offset:19456
	ds_read_b128 v[188:191], v154 offset:20480
	ds_read_b128 v[192:195], v154 offset:21504
	ds_read_b128 v[196:199], v154 offset:22528
	ds_read_b128 v[200:203], v154 offset:23552
	global_load_lds_dwordx4 v134, s[46:47]
	s_mov_b32 m0, s13
	s_nop 0
	global_load_lds_dwordx4 v130, s[46:47]
	s_barrier
	s_waitcnt lgkmcnt(0)
	s_waitcnt lgkmcnt(0)
	v_mfma_f32_16x16x32_bf16 v[60:63], v[144:147], v[172:175], v[60:63]
	v_mfma_f32_16x16x32_bf16 v[56:59], v[164:167], v[172:175], v[56:59]
	v_mfma_f32_16x16x32_bf16 v[44:47], v[144:147], v[180:183], v[44:47]
	v_mfma_f32_16x16x32_bf16 v[40:43], v[164:167], v[180:183], v[40:43]
	v_mfma_f32_16x16x32_bf16 v[28:31], v[144:147], v[188:191], v[28:31]
	v_mfma_f32_16x16x32_bf16 v[24:27], v[164:167], v[188:191], v[24:27]
	v_mfma_f32_16x16x32_bf16 v[12:15], v[144:147], v[196:199], v[12:15]
	v_mfma_f32_16x16x32_bf16 v[8:11], v[164:167], v[196:199], v[8:11]
	v_mfma_f32_16x16x32_bf16 v[60:63], v[160:163], v[176:179], v[60:63]
	v_mfma_f32_16x16x32_bf16 v[56:59], v[168:171], v[176:179], v[56:59]
	v_mfma_f32_16x16x32_bf16 v[44:47], v[160:163], v[184:187], v[44:47]
	v_mfma_f32_16x16x32_bf16 v[40:43], v[168:171], v[184:187], v[40:43]
	v_mfma_f32_16x16x32_bf16 v[28:31], v[160:163], v[192:195], v[28:31]
	v_mfma_f32_16x16x32_bf16 v[24:27], v[168:171], v[192:195], v[24:27]
	v_mfma_f32_16x16x32_bf16 v[12:15], v[160:163], v[200:203], v[12:15]
	v_mfma_f32_16x16x32_bf16 v[8:11], v[168:171], v[200:203], v[8:11]
	s_barrier
	s_add_u32 s56, s44, 0x80000
	s_addc_u32 s57, s45, 0
	s_add_i32 s55, s48, s10
	s_mov_b32 m0, s55
	s_nop 0
	global_load_lds_dwordx4 v132, s[56:57]
	s_add_i32 m0, s55, 0x2000
	s_nop 0
	global_load_lds_dwordx4 v128, s[56:57]
	s_waitcnt vmcnt(6)
	s_barrier
; #define PG8_STAGE(bufoff, gbase, voff) do { _Pragma("unroll") for (int _i = 0; _i < 2; ++_i) \
;         __builtin_amdgcn_global_load_lds((const unsigned*)((const char*)(gbase) + (voff)[_i]), (LAS unsigned*)(lds + (bufoff) + ldsw + _i * 8192), 16, 0, 0); } while (0)
; #define PG8_LDA(dst, b, h) do { _Pragma("unroll") for (int m = 0; m < 4; ++m) _Pragma("unroll") for (int k = 0; k < 2; ++k) dst[m][k] = *(const LAS bf16x8*)(lds + PG8_SA(b, h) + aoff + m * 2048 + k * 1024); } while (0)
; #define PG8_LDB(dst, b, h) do { _Pragma("unroll") for (int n = 0; n < 2; ++n) _Pragma("unroll") for (int k = 0; k < 2; ++k) dst[n][k] = *(const LAS bf16x8*)(lds + PG8_SB(b, h) + boff + n * 2048 + k * 1024); } while (0)
; #define PG8_MMA(ai, bj, At, Bt) do { __builtin_amdgcn_s_setprio(1); _Pragma("unroll") for (int m = 0; m < 4; ++m) _Pragma("unroll") for (int n = 0; n < 2; ++n) _Pragma("unroll") for (int k = 0; k < 2; ++k) \
;         acc[ai][bj][m][n] = __builtin_amdgcn_mfma_f32_16x16x32_bf16(Bt[n][k], At[m][k], acc[ai][bj][m][n], 0, 0, 0); __builtin_amdgcn_s_setprio(0); } while (0)
; #define PG8_WAIT_V(n) asm volatile("s_waitcnt vmcnt(" #n ")" ::: "memory")
; #define PG8_WAIT_L(n) asm volatile("s_waitcnt lgkmcnt(" #n ")" ::: "memory")
; #define PG8_BAR __builtin_amdgcn_s_barrier()
; #define PG8_SCHED __builtin_amdgcn_sched_barrier(0)
; template <class Epi>
; __device__ __forceinline__ void gemm_phase(LAS unsigned char* lds, const Gemm g, const StaticOrder& S, const Epi& E) {
;     ...
;             PG8_WAIT_V(6); PG8_BAR; PG8_MMA(1, 1, At, B1); PG8_BAR;
;             PG8_LDB(B0, 1, 0); PG8_SCHED; PG8_LDA(At, 1, 0); PG8_STAGE(PG8_SA(0, 1), a2 + hstep, voffA);
;             PG8_WAIT_L(8); PG8_BAR; PG8_WAIT_L(0); PG8_MMA(0, 0, At, B0); PG8_BAR; PG8_SCHED;
;             PG8_LDB(B1, 1, 1); PG8_STAGE(PG8_SB(1, 0), b3, voffB);
;             PG8_BAR; PG8_WAIT_L(0); PG8_MMA(0, 1, At, B1); PG8_BAR;
;             PG8_LDA(At, 1, 1); PG8_STAGE(PG8_SA(1, 0), a3, voffA);
	v_mfma_f32_16x16x32_bf16 v[52:55], v[204:207], v[172:175], v[52:55]
	v_mfma_f32_16x16x32_bf16 v[48:51], v[212:215], v[172:175], v[48:51]
	v_mfma_f32_16x16x32_bf16 v[36:39], v[204:207], v[180:183], v[36:39]
	v_mfma_f32_16x16x32_bf16 v[32:35], v[212:215], v[180:183], v[32:35]
	v_mfma_f32_16x16x32_bf16 v[20:23], v[204:207], v[188:191], v[20:23]
	v_mfma_f32_16x16x32_bf16 v[16:19], v[212:215], v[188:191], v[16:19]
	v_mfma_f32_16x16x32_bf16 v[4:7], v[204:207], v[196:199], v[4:7]
	v_mfma_f32_16x16x32_bf16 v[0:3], v[212:215], v[196:199], v[0:3]
	v_mfma_f32_16x16x32_bf16 v[52:55], v[208:211], v[176:179], v[52:55]
	v_mfma_f32_16x16x32_bf16 v[48:51], v[216:219], v[176:179], v[48:51]
	v_mfma_f32_16x16x32_bf16 v[36:39], v[208:211], v[184:187], v[36:39]
	v_mfma_f32_16x16x32_bf16 v[32:35], v[216:219], v[184:187], v[32:35]
	v_mfma_f32_16x16x32_bf16 v[20:23], v[208:211], v[192:195], v[20:23]
	v_mfma_f32_16x16x32_bf16 v[16:19], v[216:219], v[192:195], v[16:19]
	v_mfma_f32_16x16x32_bf16 v[4:7], v[208:211], v[200:203], v[4:7]
	v_mfma_f32_16x16x32_bf16 v[0:3], v[216:219], v[200:203], v[0:3]
	s_add_i32 s55, 0, 0x18000
	v_add_u32_e32 v168, s55, v151
	s_barrier
	ds_read_b128 v[144:147], v168
	ds_read_b128 v[160:163], v168 offset:1024
	ds_read_b128 v[164:167], v168 offset:2048
	ds_read_b128 v[168:171], v168 offset:3072
	s_add_u32 s46, s46, 0x80000
	s_addc_u32 s47, s47, 0
	s_mov_b32 m0, s30
	ds_read_b128 v[172:175], v154 offset:32768
	ds_read_b128 v[176:179], v154 offset:33792
	ds_read_b128 v[180:183], v154 offset:34816
	ds_read_b128 v[184:187], v154 offset:35840
	ds_read_b128 v[188:191], v154 offset:36864
	ds_read_b128 v[192:195], v154 offset:37888
	ds_read_b128 v[196:199], v154 offset:38912
	ds_read_b128 v[200:203], v154 offset:39936
	global_load_lds_dwordx4 v134, s[46:47]
	s_mov_b32 m0, s31
	s_nop 0
	global_load_lds_dwordx4 v130, s[46:47]
	s_waitcnt lgkmcnt(8)
	s_barrier
	s_waitcnt lgkmcnt(0)
	s_waitcnt lgkmcnt(0)
	v_mfma_f32_16x16x32_bf16 v[124:127], v[144:147], v[172:175], v[124:127]
	v_mfma_f32_16x16x32_bf16 v[120:123], v[164:167], v[172:175], v[120:123]
	v_mfma_f32_16x16x32_bf16 v[108:111], v[144:147], v[180:183], v[108:111]
	v_mfma_f32_16x16x32_bf16 v[104:107], v[164:167], v[180:183], v[104:107]
	v_mfma_f32_16x16x32_bf16 v[92:95], v[144:147], v[188:191], v[92:95]
	v_mfma_f32_16x16x32_bf16 v[88:91], v[164:167], v[188:191], v[88:91]
	v_mfma_f32_16x16x32_bf16 v[76:79], v[144:147], v[196:199], v[76:79]
	v_mfma_f32_16x16x32_bf16 v[72:75], v[164:167], v[196:199], v[72:75]
	v_mfma_f32_16x16x32_bf16 v[124:127], v[160:163], v[176:179], v[124:127]
	v_mfma_f32_16x16x32_bf16 v[120:123], v[168:171], v[176:179], v[120:123]
	v_mfma_f32_16x16x32_bf16 v[108:111], v[160:163], v[184:187], v[108:111]
	v_mfma_f32_16x16x32_bf16 v[104:107], v[168:171], v[184:187], v[104:107]
	v_mfma_f32_16x16x32_bf16 v[92:95], v[160:163], v[192:195], v[92:95]
	v_mfma_f32_16x16x32_bf16 v[88:91], v[168:171], v[192:195], v[88:91]
	v_mfma_f32_16x16x32_bf16 v[76:79], v[160:163], v[200:203], v[76:79]
	v_mfma_f32_16x16x32_bf16 v[72:75], v[168:171], v[200:203], v[72:75]
	s_barrier
	s_add_i32 s46, 0, 0x1c000
	s_add_i32 s47, s55, s10
	v_add_u32_e32 v216, s46, v151
	s_mov_b32 m0, s47
	ds_read_b128 v[204:207], v216
	ds_read_b128 v[208:211], v216 offset:1024
	ds_read_b128 v[212:215], v216 offset:2048
	ds_read_b128 v[216:219], v216 offset:3072
	global_load_lds_dwordx4 v132, s[98:99]
	s_add_i32 m0, s47, 0x2000
	s_nop 0
	global_load_lds_dwordx4 v128, s[98:99]
	s_barrier
	s_waitcnt lgkmcnt(0)
	s_waitcnt lgkmcnt(0)
	v_mfma_f32_16x16x32_bf16 v[116:119], v[204:207], v[172:175], v[116:119]
	v_mfma_f32_16x16x32_bf16 v[112:115], v[212:215], v[172:175], v[112:115]
	v_mfma_f32_16x16x32_bf16 v[100:103], v[204:207], v[180:183], v[100:103]
	v_mfma_f32_16x16x32_bf16 v[96:99], v[212:215], v[180:183], v[96:99]
	v_mfma_f32_16x16x32_bf16 v[84:87], v[204:207], v[188:191], v[84:87]
	v_mfma_f32_16x16x32_bf16 v[80:83], v[212:215], v[188:191], v[80:83]
	v_mfma_f32_16x16x32_bf16 v[68:71], v[204:207], v[196:199], v[68:71]
	v_mfma_f32_16x16x32_bf16 v[64:67], v[212:215], v[196:199], v[64:67]
	v_mfma_f32_16x16x32_bf16 v[116:119], v[208:211], v[176:179], v[116:119]
	v_mfma_f32_16x16x32_bf16 v[112:115], v[216:219], v[176:179], v[112:115]
	v_mfma_f32_16x16x32_bf16 v[100:103], v[208:211], v[184:187], v[100:103]
	v_mfma_f32_16x16x32_bf16 v[96:99], v[216:219], v[184:187], v[96:99]
	v_mfma_f32_16x16x32_bf16 v[84:87], v[208:211], v[192:195], v[84:87]
	v_mfma_f32_16x16x32_bf16 v[80:83], v[216:219], v[192:195], v[80:83]
	v_mfma_f32_16x16x32_bf16 v[68:71], v[208:211], v[200:203], v[68:71]
	v_mfma_f32_16x16x32_bf16 v[64:67], v[216:219], v[200:203], v[64:67]
	s_mov_b32 m0, s36
	s_barrier
	ds_read_b128 v[172:175], v154 offset:49152
	ds_read_b128 v[176:179], v154 offset:50176
	ds_read_b128 v[180:183], v154 offset:51200
	ds_read_b128 v[184:187], v154 offset:52224
	ds_read_b128 v[188:191], v154 offset:53248
	ds_read_b128 v[192:195], v154 offset:54272
	ds_read_b128 v[196:199], v154 offset:55296
	ds_read_b128 v[200:203], v154 offset:56320
	global_load_lds_dwordx4 v134, s[100:101]
	s_mov_b32 m0, s37
	s_nop 0
	global_load_lds_dwordx4 v130, s[100:101]
	s_barrier
; __device__ __forceinline__ float fast_rcp(float x) { return __builtin_amdgcn_rcpf(x); }
; __device__ __forceinline__ float fast_exp2(float x) { return __builtin_amdgcn_exp2f(x); }
; #define PG8_STAGE(bufoff, gbase, voff) do { _Pragma("unroll") for (int _i = 0; _i < 2; ++_i) \
;         __builtin_amdgcn_global_load_lds((const unsigned*)((const char*)(gbase) + (voff)[_i]), (LAS unsigned*)(lds + (bufoff) + ldsw + _i * 8192), 16, 0, 0); } while (0)
; #define PG8_MMA(ai, bj, At, Bt) do { __builtin_amdgcn_s_setprio(1); _Pragma("unroll") for (int m = 0; m < 4; ++m) _Pragma("unroll") for (int n = 0; n < 2; ++n) _Pragma("unroll") for (int k = 0; k < 2; ++k) \
;         acc[ai][bj][m][n] = __builtin_amdgcn_mfma_f32_16x16x32_bf16(Bt[n][k], At[m][k], acc[ai][bj][m][n], 0, 0, 0); __builtin_amdgcn_s_setprio(0); } while (0)
; #define PG8_WAIT_V(n) asm volatile("s_waitcnt vmcnt(" #n ")" ::: "memory")
; #define PG8_WAIT_L(n) asm volatile("s_waitcnt lgkmcnt(" #n ")" ::: "memory")
; #define PG8_BAR __builtin_amdgcn_s_barrier()
; #define PG8_SCHED __builtin_amdgcn_sched_barrier(0)
; template <class Epi>
; __device__ __forceinline__ void gemm_phase(LAS unsigned char* lds, const Gemm g, const StaticOrder& S, const Epi& E) {
;     ...
;             PG8_BAR; PG8_WAIT_L(0); PG8_MMA(1, 0, At, B0); PG8_BAR; PG8_SCHED;
;             PG8_STAGE(PG8_SB(1, 1), b3 + hstep, voffB);
;             PG8_WAIT_V(6); PG8_BAR; PG8_MMA(1, 1, At, B1); PG8_BAR;
;     __device__ __forceinline__ void operator()(const f32x4 (&acc)[2][2][4][2], const Unit& u, int wr, int wc, int fr, int fq) const {
;         const int row0 = u.pm * BM + wr * 64 + fr, col0 = u.pn * HALF + wc * 32 + 8 * fq;
; #pragma unroll
;         for (int ai = 0; ai < 2; ++ai)
; #pragma unroll
;             for (int m = 0; m < 4; ++m) { bf16_t* rowp = O + (size_t)(row0 + ai * HALF + m * 16) * DFF + col0;
;                 const float r = rs[row0 + ai * HALF + m * 16], r2 = r * r;
;                 f32x4 h0, h1;
; #pragma unroll
;                 for (int j = 0; j < 4; ++j) {
;                     const float g0 = acc[ai][0][m][0][j], g1 = acc[ai][0][m][1][j];
;                     h0[j] = g0 * r2 * fast_rcp(1.0f + fast_exp2(g0 * (-LOG2E * r))) * acc[ai][1][m][0][j];
;                     h1[j] = g1 * r2 * fast_rcp(1.0f + fast_exp2(g1 * (-LOG2E * r))) * acc[ai][1][m][1][j]; }
;                 *(u32x4*)rowp = pack8(h0, h1); }
	s_waitcnt lgkmcnt(0)
	s_waitcnt lgkmcnt(0)
	v_mfma_f32_16x16x32_bf16 v[60:63], v[144:147], v[172:175], v[60:63]
	v_mfma_f32_16x16x32_bf16 v[56:59], v[164:167], v[172:175], v[56:59]
	v_mfma_f32_16x16x32_bf16 v[44:47], v[144:147], v[180:183], v[44:47]
	v_mfma_f32_16x16x32_bf16 v[40:43], v[164:167], v[180:183], v[40:43]
	v_mfma_f32_16x16x32_bf16 v[28:31], v[144:147], v[188:191], v[28:31]
	v_mfma_f32_16x16x32_bf16 v[24:27], v[164:167], v[188:191], v[24:27]
	v_mfma_f32_16x16x32_bf16 v[12:15], v[144:147], v[196:199], v[12:15]
	v_mfma_f32_16x16x32_bf16 v[8:11], v[164:167], v[196:199], v[8:11]
	v_mfma_f32_16x16x32_bf16 v[60:63], v[160:163], v[176:179], v[60:63]
	v_mfma_f32_16x16x32_bf16 v[56:59], v[168:171], v[176:179], v[56:59]
	v_mfma_f32_16x16x32_bf16 v[44:47], v[160:163], v[184:187], v[44:47]
	v_mfma_f32_16x16x32_bf16 v[40:43], v[168:171], v[184:187], v[40:43]
	v_mfma_f32_16x16x32_bf16 v[28:31], v[160:163], v[192:195], v[28:31]
	v_mfma_f32_16x16x32_bf16 v[24:27], v[168:171], v[192:195], v[24:27]
	v_mfma_f32_16x16x32_bf16 v[12:15], v[160:163], v[200:203], v[12:15]
	v_mfma_f32_16x16x32_bf16 v[8:11], v[168:171], v[200:203], v[8:11]
	s_barrier
	s_add_u32 s44, s44, 0x80080
	s_addc_u32 s45, s45, 0
	s_add_i32 s46, s46, s10
	s_mov_b32 m0, s46
	s_nop 0
	global_load_lds_dwordx4 v132, s[44:45]
	s_add_i32 m0, s46, 0x2000
	s_nop 0
	global_load_lds_dwordx4 v128, s[44:45]
	s_waitcnt vmcnt(6)
	s_barrier
	v_mfma_f32_16x16x32_bf16 v[52:55], v[204:207], v[172:175], v[52:55]
	v_mfma_f32_16x16x32_bf16 v[48:51], v[212:215], v[172:175], v[48:51]
	v_mfma_f32_16x16x32_bf16 v[36:39], v[204:207], v[180:183], v[36:39]
	v_mfma_f32_16x16x32_bf16 v[32:35], v[212:215], v[180:183], v[32:35]
	v_mfma_f32_16x16x32_bf16 v[20:23], v[204:207], v[188:191], v[20:23]
	v_mfma_f32_16x16x32_bf16 v[16:19], v[212:215], v[188:191], v[16:19]
	v_mfma_f32_16x16x32_bf16 v[4:7], v[204:207], v[196:199], v[4:7]
	v_mfma_f32_16x16x32_bf16 v[0:3], v[212:215], v[196:199], v[0:3]
	v_mfma_f32_16x16x32_bf16 v[52:55], v[208:211], v[176:179], v[52:55]
	v_mfma_f32_16x16x32_bf16 v[48:51], v[216:219], v[176:179], v[48:51]
	v_mfma_f32_16x16x32_bf16 v[36:39], v[208:211], v[184:187], v[36:39]
	v_mfma_f32_16x16x32_bf16 v[32:35], v[216:219], v[184:187], v[32:35]
	v_mfma_f32_16x16x32_bf16 v[20:23], v[208:211], v[192:195], v[20:23]
	v_mfma_f32_16x16x32_bf16 v[16:19], v[216:219], v[192:195], v[16:19]
	v_mfma_f32_16x16x32_bf16 v[4:7], v[208:211], v[200:203], v[4:7]
	v_mfma_f32_16x16x32_bf16 v[0:3], v[216:219], v[200:203], v[0:3]
	s_add_i32 s54, s54, 2
	s_add_u32 s42, s42, 0x100
	s_addc_u32 s43, s43, 0
	s_add_u32 s52, s52, 0x100
	s_addc_u32 s53, s53, 0
	s_cmp_gt_u32 s54, 29
	s_barrier
	s_cbranch_scc0 .LBB0_203
	v_lshl_add_u32 v144, s40, 8, v150
	v_ashrrev_i32_e32 v145, 31, v144
	v_lshl_add_u64 v[148:149], v[144:145], 2, s[14:15]
	v_mov_b32_e32 v145, v224
	v_mov_b32_e32 v204, v225
	v_mov_b32_e32 v205, v226
	v_mov_b32_e32 v206, v227
	v_mov_b32_e32 v207, v228
	v_mov_b32_e32 v208, v229
	v_mov_b32_e32 v209, v230
	v_mov_b32_e32 v210, v231
	v_lshl_or_b32 v156, s34, 7, v152
	v_ashrrev_i32_e32 v157, 31, v156
	v_mov_b64_e32 v[146:147], s[20:21]
	v_mad_i64_i32 v[160:161], s[42:43], v144, s49, v[146:147]
	s_and_b64 vcc, exec, s[4:5]
	s_mov_b32 s34, s22
	s_mov_b32 s40, s24
	s_mov_b64 s[44:45], s[28:29]
	v_mul_f32_e32 v162, v145, v145
	v_mul_f32_e32 v145, 0xbfb8aa3b, v145
	v_mul_f32_e32 v163, v124, v162
	v_mul_f32_e32 v124, v124, v145
	v_exp_f32_e32 v124, v124
	s_nop 0
	v_add_f32_e32 v124, 1.0, v124
	v_rcp_f32_e32 v124, v124
	s_nop 0
	v_mul_f32_e32 v124, v163, v124
	v_mul_f32_e32 v116, v116, v124
	v_mul_f32_e32 v124, v120, v162
	v_mul_f32_e32 v120, v120, v145
	v_exp_f32_e32 v120, v120
	s_nop 0
	v_add_f32_e32 v120, 1.0, v120
	v_rcp_f32_e32 v120, v120
	s_nop 0
	v_mul_f32_e32 v120, v124, v120
	v_mul_f32_e32 v124, v125, v145
	v_exp_f32_e32 v124, v124
	v_mul_f32_e32 v120, v112, v120
	v_mul_f32_e32 v112, v125, v162
	v_add_f32_e32 v124, 1.0, v124
	v_rcp_f32_e32 v124, v124
	s_nop 0
	v_mul_f32_e32 v112, v112, v124
	v_mul_f32_e32 v117, v117, v112
	v_mul_f32_e32 v112, v121, v162
	v_mul_f32_e32 v121, v121, v145
	v_exp_f32_e32 v121, v121
	s_nop 0
	v_add_f32_e32 v121, 1.0, v121
	v_rcp_f32_e32 v121, v121
	s_nop 0
	v_mul_f32_e32 v112, v112, v121
	v_mul_f32_e32 v121, v113, v112
	v_mul_f32_e32 v113, v126, v145
	v_exp_f32_e32 v113, v113
	v_mul_f32_e32 v112, v126, v162
	v_add_f32_e32 v113, 1.0, v113
	v_rcp_f32_e32 v113, v113
	s_nop 0
	v_mul_f32_e32 v112, v112, v113
	v_mul_f32_e32 v113, v122, v145
	v_exp_f32_e32 v113, v113
	v_mul_f32_e32 v124, v118, v112
	v_mul_f32_e32 v112, v122, v162
	v_add_f32_e32 v113, 1.0, v113
	v_rcp_f32_e32 v113, v113
	s_nop 0
	v_mul_f32_e32 v112, v112, v113
	v_mul_f32_e32 v113, v127, v145
	v_exp_f32_e32 v113, v113
	v_mul_f32_e32 v122, v114, v112
	v_mul_f32_e32 v112, v127, v162
	v_cvt_pk_bf16_f32 v114, v116, v117
	v_add_f32_e32 v113, 1.0, v113
	v_rcp_f32_e32 v113, v113
	s_nop 0
	v_mul_f32_e32 v112, v112, v113
	v_mul_f32_e32 v113, v123, v145
	v_exp_f32_e32 v113, v113
	v_mul_f32_e32 v125, v119, v112
	v_mul_f32_e32 v112, v123, v162
	v_add_f32_e32 v113, 1.0, v113
	v_rcp_f32_e32 v113, v113
	s_nop 0
	v_mul_f32_e32 v112, v112, v113
	v_mul_f32_e32 v123, v115, v112
	v_lshlrev_b64 v[112:113], 1, v[156:157]
	v_lshl_add_u64 v[118:119], v[160:161], 0, v[112:113]
	v_cvt_pk_bf16_f32 v115, v124, v125
	v_cvt_pk_bf16_f32 v116, v120, v121
	v_cvt_pk_bf16_f32 v117, v122, v123
	global_store_dwordx4 v[118:119], v[114:117], off
	s_nop 1
	v_mov_b32_e32 v116, v204
	s_nop 0
	v_or_b32_e32 v114, 16, v144
	v_mad_i64_i32 v[114:115], s[42:43], v114, s49, v[146:147]
	v_mul_f32_e32 v117, v116, v116
	v_mul_f32_e32 v116, 0xbfb8aa3b, v116
	v_mul_f32_e32 v118, v108, v117
; __device__ __forceinline__ float fast_rcp(float x) { return __builtin_amdgcn_rcpf(x); }
; __device__ __forceinline__ float fast_exp2(float x) { return __builtin_amdgcn_exp2f(x); }
; __device__ __forceinline__ u32x4 pack8(f32x4 v0, f32x4 v1) { u32x4 w; w.x = cvt_pk_bf16(v0[0], v0[1]); w.y = cvt_pk_bf16(v0[2], v0[3]); w.z = cvt_pk_bf16(v1[0], v1[1]); w.w = cvt_pk_bf16(v1[2], v1[3]); return w; }
;     __device__ __forceinline__ void operator()(const f32x4 (&acc)[2][2][4][2], const Unit& u, int wr, int wc, int fr, int fq) const {
;     ...
;         for (int ai = 0; ai < 2; ++ai)
; #pragma unroll
;             for (int m = 0; m < 4; ++m) { bf16_t* rowp = O + (size_t)(row0 + ai * HALF + m * 16) * DFF + col0;
;                 const float r = rs[row0 + ai * HALF + m * 16], r2 = r * r;
;                 f32x4 h0, h1;
; #pragma unroll
;                 for (int j = 0; j < 4; ++j) {
;                     const float g0 = acc[ai][0][m][0][j], g1 = acc[ai][0][m][1][j];
;                     h0[j] = g0 * r2 * fast_rcp(1.0f + fast_exp2(g0 * (-LOG2E * r))) * acc[ai][1][m][0][j];
;                     h1[j] = g1 * r2 * fast_rcp(1.0f + fast_exp2(g1 * (-LOG2E * r))) * acc[ai][1][m][1][j]; }
;                 *(u32x4*)rowp = pack8(h0, h1); }
	v_mul_f32_e32 v108, v108, v116
	v_exp_f32_e32 v108, v108
	s_nop 0
	v_add_f32_e32 v108, 1.0, v108
	v_rcp_f32_e32 v108, v108
	s_nop 0
	v_mul_f32_e32 v108, v118, v108
	v_mul_f32_e32 v108, v100, v108
	v_mul_f32_e32 v100, v104, v117
	v_mul_f32_e32 v104, v104, v116
	v_exp_f32_e32 v104, v104
	s_nop 0
	v_add_f32_e32 v104, 1.0, v104
	v_rcp_f32_e32 v104, v104
	s_nop 0
	v_mul_f32_e32 v100, v100, v104
	v_mul_f32_e32 v104, v96, v100
	v_mul_f32_e32 v100, v109, v116
	v_exp_f32_e32 v100, v100
	v_mul_f32_e32 v96, v109, v117
	v_add_f32_e32 v100, 1.0, v100
	v_rcp_f32_e32 v100, v100
	s_nop 0
	v_mul_f32_e32 v96, v96, v100
	v_mul_f32_e32 v96, v101, v96
	v_mul_f32_e32 v101, v105, v116
	v_exp_f32_e32 v101, v101
	v_mul_f32_e32 v100, v105, v117
	v_cvt_pk_bf16_f32 v96, v108, v96
	v_add_f32_e32 v101, 1.0, v101
	v_rcp_f32_e32 v101, v101
	s_nop 0
	v_mul_f32_e32 v100, v100, v101
	v_mul_f32_e32 v105, v97, v100
	v_mul_f32_e32 v100, v110, v116
	v_exp_f32_e32 v100, v100
	v_mul_f32_e32 v101, v106, v116
	v_exp_f32_e32 v101, v101
	v_mul_f32_e32 v97, v110, v117
	v_add_f32_e32 v100, 1.0, v100
	v_rcp_f32_e32 v100, v100
	v_add_f32_e32 v101, 1.0, v101
	v_rcp_f32_e32 v101, v101
	v_mul_f32_e32 v97, v97, v100
	v_mul_f32_e32 v100, v106, v117
	v_mul_f32_e32 v100, v100, v101
	v_mul_f32_e32 v97, v102, v97
	v_mul_f32_e32 v102, v98, v100
	v_mul_f32_e32 v100, v111, v116
	v_exp_f32_e32 v100, v100
	v_mul_f32_e32 v101, v107, v116
	v_exp_f32_e32 v101, v101
	v_mul_f32_e32 v98, v111, v117
	v_add_f32_e32 v100, 1.0, v100
	v_rcp_f32_e32 v100, v100
	v_add_f32_e32 v101, 1.0, v101
	v_rcp_f32_e32 v101, v101
	v_mul_f32_e32 v98, v98, v100
	v_mul_f32_e32 v100, v107, v117
	v_mul_f32_e32 v100, v100, v101
	v_mul_f32_e32 v98, v103, v98
	v_mul_f32_e32 v99, v99, v100
	v_lshl_add_u64 v[100:101], v[114:115], 0, v[112:113]
	v_cvt_pk_bf16_f32 v97, v97, v98
	v_cvt_pk_bf16_f32 v98, v104, v105
	v_cvt_pk_bf16_f32 v99, v102, v99
	global_store_dwordx4 v[100:101], v[96:99], off
	s_nop 1
	v_mov_b32_e32 v98, v205
	s_nop 0
	v_or_b32_e32 v96, 32, v144
	v_mad_i64_i32 v[96:97], s[42:43], v96, s49, v[146:147]
	v_mul_f32_e32 v99, v98, v98
	v_mul_f32_e32 v98, 0xbfb8aa3b, v98
	v_mul_f32_e32 v100, v92, v99
	v_mul_f32_e32 v92, v92, v98
	v_exp_f32_e32 v92, v92
	s_nop 0
	v_add_f32_e32 v92, 1.0, v92
	v_rcp_f32_e32 v92, v92
	s_nop 0
	v_mul_f32_e32 v92, v100, v92
	v_mul_f32_e32 v92, v84, v92
	v_mul_f32_e32 v84, v88, v99
	v_mul_f32_e32 v88, v88, v98
	v_exp_f32_e32 v88, v88
	s_nop 0
	v_add_f32_e32 v88, 1.0, v88
	v_rcp_f32_e32 v88, v88
	s_nop 0
	v_mul_f32_e32 v84, v84, v88
	v_mul_f32_e32 v88, v80, v84
	v_mul_f32_e32 v84, v93, v98
	v_exp_f32_e32 v84, v84
	v_mul_f32_e32 v80, v93, v99
	v_add_f32_e32 v84, 1.0, v84
	v_rcp_f32_e32 v84, v84
	s_nop 0
	v_mul_f32_e32 v80, v80, v84
	v_mul_f32_e32 v80, v85, v80
	v_mul_f32_e32 v85, v89, v98
	v_exp_f32_e32 v85, v85
	v_mul_f32_e32 v84, v89, v99
	v_cvt_pk_bf16_f32 v80, v92, v80
	v_add_f32_e32 v85, 1.0, v85
	v_rcp_f32_e32 v85, v85
	s_nop 0
	v_mul_f32_e32 v84, v84, v85
	v_mul_f32_e32 v89, v81, v84
	v_mul_f32_e32 v84, v94, v98
	v_exp_f32_e32 v84, v84
	v_mul_f32_e32 v85, v90, v98
	v_exp_f32_e32 v85, v85
	v_mul_f32_e32 v81, v94, v99
	v_add_f32_e32 v84, 1.0, v84
	v_rcp_f32_e32 v84, v84
	v_add_f32_e32 v85, 1.0, v85
	v_rcp_f32_e32 v85, v85
	v_mul_f32_e32 v81, v81, v84
	v_mul_f32_e32 v84, v90, v99
	v_mul_f32_e32 v84, v84, v85
	v_mul_f32_e32 v81, v86, v81
	v_mul_f32_e32 v86, v82, v84
	v_mul_f32_e32 v84, v95, v98
	v_exp_f32_e32 v84, v84
	v_mul_f32_e32 v85, v91, v98
	v_exp_f32_e32 v85, v85
	v_mul_f32_e32 v82, v95, v99
	v_add_f32_e32 v84, 1.0, v84
	v_rcp_f32_e32 v84, v84
	v_add_f32_e32 v85, 1.0, v85
	v_rcp_f32_e32 v85, v85
	v_mul_f32_e32 v82, v82, v84
	v_mul_f32_e32 v84, v91, v99
	v_mul_f32_e32 v84, v84, v85
	v_mul_f32_e32 v82, v87, v82
	v_mul_f32_e32 v83, v83, v84
	v_lshl_add_u64 v[84:85], v[96:97], 0, v[112:113]
	v_cvt_pk_bf16_f32 v81, v81, v82
	v_cvt_pk_bf16_f32 v82, v88, v89
	v_cvt_pk_bf16_f32 v83, v86, v83
	global_store_dwordx4 v[84:85], v[80:83], off
	s_nop 1
	v_mov_b32_e32 v82, v206
	s_nop 0
	v_or_b32_e32 v80, 48, v144
	v_mad_i64_i32 v[80:81], s[42:43], v80, s49, v[146:147]
	v_mul_f32_e32 v83, v82, v82
	v_mul_f32_e32 v82, 0xbfb8aa3b, v82
	v_mul_f32_e32 v84, v76, v83
	v_mul_f32_e32 v76, v76, v82
	v_exp_f32_e32 v76, v76
	s_nop 0
	v_add_f32_e32 v76, 1.0, v76
	v_rcp_f32_e32 v76, v76
	s_nop 0
	v_mul_f32_e32 v76, v84, v76
	v_mul_f32_e32 v76, v68, v76
	v_mul_f32_e32 v68, v72, v83
	v_mul_f32_e32 v72, v72, v82
	v_exp_f32_e32 v72, v72
	s_nop 0
	v_add_f32_e32 v72, 1.0, v72
	v_rcp_f32_e32 v72, v72
	s_nop 0
	v_mul_f32_e32 v68, v68, v72
	v_mul_f32_e32 v72, v64, v68
	v_mul_f32_e32 v68, v77, v82
	v_exp_f32_e32 v68, v68
	v_mul_f32_e32 v64, v77, v83
	v_add_f32_e32 v68, 1.0, v68
	v_rcp_f32_e32 v68, v68
	s_nop 0
	v_mul_f32_e32 v64, v64, v68
	v_mul_f32_e32 v64, v69, v64
	v_mul_f32_e32 v69, v73, v82
	v_exp_f32_e32 v69, v69
	v_mul_f32_e32 v68, v73, v83
	v_cvt_pk_bf16_f32 v64, v76, v64
	v_add_f32_e32 v69, 1.0, v69
	v_rcp_f32_e32 v69, v69
	s_nop 0
	v_mul_f32_e32 v68, v68, v69
	v_mul_f32_e32 v73, v65, v68
	v_mul_f32_e32 v68, v78, v82
	v_exp_f32_e32 v68, v68
	v_mul_f32_e32 v69, v74, v82
	v_exp_f32_e32 v69, v69
	v_mul_f32_e32 v65, v78, v83
	v_add_f32_e32 v68, 1.0, v68
	v_rcp_f32_e32 v68, v68
	v_add_f32_e32 v69, 1.0, v69
	v_rcp_f32_e32 v69, v69
	v_mul_f32_e32 v65, v65, v68
	v_mul_f32_e32 v68, v74, v83
	v_mul_f32_e32 v68, v68, v69
	v_mul_f32_e32 v65, v70, v65
	v_mul_f32_e32 v70, v66, v68
	v_mul_f32_e32 v68, v79, v82
	v_exp_f32_e32 v68, v68
	v_mul_f32_e32 v69, v75, v82
	v_exp_f32_e32 v69, v69
	v_mul_f32_e32 v66, v79, v83
	v_add_f32_e32 v68, 1.0, v68
	v_rcp_f32_e32 v68, v68
	v_add_f32_e32 v69, 1.0, v69
	v_rcp_f32_e32 v69, v69
; __device__ __forceinline__ float fast_rcp(float x) { return __builtin_amdgcn_rcpf(x); }
; __device__ __forceinline__ float fast_exp2(float x) { return __builtin_amdgcn_exp2f(x); }
; __device__ __forceinline__ u32x4 pack8(f32x4 v0, f32x4 v1) { u32x4 w; w.x = cvt_pk_bf16(v0[0], v0[1]); w.y = cvt_pk_bf16(v0[2], v0[3]); w.z = cvt_pk_bf16(v1[0], v1[1]); w.w = cvt_pk_bf16(v1[2], v1[3]); return w; }
;     __device__ __forceinline__ void operator()(const f32x4 (&acc)[2][2][4][2], const Unit& u, int wr, int wc, int fr, int fq) const {
;     ...
;         for (int ai = 0; ai < 2; ++ai)
; #pragma unroll
;             for (int m = 0; m < 4; ++m) { bf16_t* rowp = O + (size_t)(row0 + ai * HALF + m * 16) * DFF + col0;
;                 const float r = rs[row0 + ai * HALF + m * 16], r2 = r * r;
;                 f32x4 h0, h1;
; #pragma unroll
;                 for (int j = 0; j < 4; ++j) {
;                     const float g0 = acc[ai][0][m][0][j], g1 = acc[ai][0][m][1][j];
;                     h0[j] = g0 * r2 * fast_rcp(1.0f + fast_exp2(g0 * (-LOG2E * r))) * acc[ai][1][m][0][j];
;                     h1[j] = g1 * r2 * fast_rcp(1.0f + fast_exp2(g1 * (-LOG2E * r))) * acc[ai][1][m][1][j]; }
;                 *(u32x4*)rowp = pack8(h0, h1); }
	v_mul_f32_e32 v66, v66, v68
	v_mul_f32_e32 v68, v75, v83
	v_mul_f32_e32 v68, v68, v69
	v_mul_f32_e32 v66, v71, v66
	v_mul_f32_e32 v67, v67, v68
	v_lshl_add_u64 v[68:69], v[80:81], 0, v[112:113]
	v_cvt_pk_bf16_f32 v65, v65, v66
	v_cvt_pk_bf16_f32 v66, v72, v73
	v_cvt_pk_bf16_f32 v67, v70, v67
	global_store_dwordx4 v[68:69], v[64:67], off
	s_nop 1
	v_mov_b32_e32 v66, v207
	s_nop 0
	v_add_u32_e32 v64, 0x80, v144
	v_mad_i64_i32 v[64:65], s[42:43], v64, s49, v[146:147]
	v_mul_f32_e32 v67, v66, v66
	v_mul_f32_e32 v66, 0xbfb8aa3b, v66
	v_mul_f32_e32 v68, v60, v67
	v_mul_f32_e32 v60, v60, v66
	v_exp_f32_e32 v60, v60
	s_nop 0
	v_add_f32_e32 v60, 1.0, v60
	v_rcp_f32_e32 v60, v60
	s_nop 0
	v_mul_f32_e32 v60, v68, v60
	v_mul_f32_e32 v60, v52, v60
	v_mul_f32_e32 v52, v56, v67
	v_mul_f32_e32 v56, v56, v66
	v_exp_f32_e32 v56, v56
	s_nop 0
	v_add_f32_e32 v56, 1.0, v56
	v_rcp_f32_e32 v56, v56
	s_nop 0
	v_mul_f32_e32 v52, v52, v56
	v_mul_f32_e32 v56, v48, v52
	v_mul_f32_e32 v52, v61, v66
	v_exp_f32_e32 v52, v52
	v_mul_f32_e32 v48, v61, v67
	v_add_f32_e32 v52, 1.0, v52
	v_rcp_f32_e32 v52, v52
	s_nop 0
	v_mul_f32_e32 v48, v48, v52
	v_mul_f32_e32 v48, v53, v48
	v_mul_f32_e32 v53, v57, v66
	v_exp_f32_e32 v53, v53
	v_mul_f32_e32 v52, v57, v67
	v_cvt_pk_bf16_f32 v48, v60, v48
	v_add_f32_e32 v53, 1.0, v53
	v_rcp_f32_e32 v53, v53
	s_nop 0
	v_mul_f32_e32 v52, v52, v53
	v_mul_f32_e32 v57, v49, v52
	v_mul_f32_e32 v52, v62, v66
	v_exp_f32_e32 v52, v52
	v_mul_f32_e32 v53, v58, v66
	v_exp_f32_e32 v53, v53
	v_mul_f32_e32 v49, v62, v67
	v_add_f32_e32 v52, 1.0, v52
	v_rcp_f32_e32 v52, v52
	v_add_f32_e32 v53, 1.0, v53
	v_rcp_f32_e32 v53, v53
	v_mul_f32_e32 v49, v49, v52
	v_mul_f32_e32 v52, v58, v67
	v_mul_f32_e32 v52, v52, v53
	v_mul_f32_e32 v49, v54, v49
	v_mul_f32_e32 v54, v50, v52
	v_mul_f32_e32 v52, v63, v66
	v_exp_f32_e32 v52, v52
	v_mul_f32_e32 v53, v59, v66
	v_exp_f32_e32 v53, v53
	v_mul_f32_e32 v50, v63, v67
	v_add_f32_e32 v52, 1.0, v52
	v_rcp_f32_e32 v52, v52
	v_add_f32_e32 v53, 1.0, v53
	v_rcp_f32_e32 v53, v53
	v_mul_f32_e32 v50, v50, v52
	v_mul_f32_e32 v52, v59, v67
	v_mul_f32_e32 v52, v52, v53
	v_mul_f32_e32 v50, v55, v50
	v_mul_f32_e32 v51, v51, v52
	v_lshl_add_u64 v[52:53], v[64:65], 0, v[112:113]
	v_cvt_pk_bf16_f32 v49, v49, v50
	v_cvt_pk_bf16_f32 v50, v56, v57
	v_cvt_pk_bf16_f32 v51, v54, v51
	global_store_dwordx4 v[52:53], v[48:51], off
	s_nop 1
	v_mov_b32_e32 v50, v208
	s_nop 0
	v_add_u32_e32 v48, 0x90, v144
	v_mad_i64_i32 v[48:49], s[42:43], v48, s49, v[146:147]
	v_mul_f32_e32 v51, v50, v50
	v_mul_f32_e32 v50, 0xbfb8aa3b, v50
	v_mul_f32_e32 v52, v44, v51
	v_mul_f32_e32 v44, v44, v50
	v_exp_f32_e32 v44, v44
	s_nop 0
	v_add_f32_e32 v44, 1.0, v44
	v_rcp_f32_e32 v44, v44
	s_nop 0
	v_mul_f32_e32 v44, v52, v44
	v_mul_f32_e32 v44, v36, v44
	v_mul_f32_e32 v36, v40, v51
	v_mul_f32_e32 v40, v40, v50
	v_exp_f32_e32 v40, v40
	s_nop 0
	v_add_f32_e32 v40, 1.0, v40
	v_rcp_f32_e32 v40, v40
	s_nop 0
	v_mul_f32_e32 v36, v36, v40
	v_mul_f32_e32 v40, v32, v36
	v_mul_f32_e32 v36, v45, v50
	v_exp_f32_e32 v36, v36
	v_mul_f32_e32 v32, v45, v51
	v_add_f32_e32 v36, 1.0, v36
	v_rcp_f32_e32 v36, v36
	s_nop 0
	v_mul_f32_e32 v32, v32, v36
	v_mul_f32_e32 v32, v37, v32
	v_mul_f32_e32 v37, v41, v50
	v_exp_f32_e32 v37, v37
	v_mul_f32_e32 v36, v41, v51
	v_cvt_pk_bf16_f32 v32, v44, v32
	v_add_f32_e32 v37, 1.0, v37
	v_rcp_f32_e32 v37, v37
	s_nop 0
	v_mul_f32_e32 v36, v36, v37
	v_mul_f32_e32 v41, v33, v36
	v_mul_f32_e32 v36, v46, v50
	v_exp_f32_e32 v36, v36
	v_mul_f32_e32 v37, v42, v50
	v_exp_f32_e32 v37, v37
	v_mul_f32_e32 v33, v46, v51
	v_add_f32_e32 v36, 1.0, v36
	v_rcp_f32_e32 v36, v36
	v_add_f32_e32 v37, 1.0, v37
	v_rcp_f32_e32 v37, v37
	v_mul_f32_e32 v33, v33, v36
	v_mul_f32_e32 v36, v42, v51
	v_mul_f32_e32 v36, v36, v37
	v_mul_f32_e32 v33, v38, v33
	v_mul_f32_e32 v38, v34, v36
	v_mul_f32_e32 v36, v47, v50
	v_exp_f32_e32 v36, v36
	v_mul_f32_e32 v37, v43, v50
	v_exp_f32_e32 v37, v37
	v_mul_f32_e32 v34, v47, v51
	v_add_f32_e32 v36, 1.0, v36
	v_rcp_f32_e32 v36, v36
	v_add_f32_e32 v37, 1.0, v37
	v_rcp_f32_e32 v37, v37
	v_mul_f32_e32 v34, v34, v36
	v_mul_f32_e32 v36, v43, v51
	v_mul_f32_e32 v36, v36, v37
	v_mul_f32_e32 v34, v39, v34
	v_mul_f32_e32 v35, v35, v36
	v_lshl_add_u64 v[36:37], v[48:49], 0, v[112:113]
; __device__ __forceinline__ float fast_rcp(float x) { return __builtin_amdgcn_rcpf(x); }
; __device__ __forceinline__ float fast_exp2(float x) { return __builtin_amdgcn_exp2f(x); }
; #define PG8_WAIT_V(n) asm volatile("s_waitcnt vmcnt(" #n ")" ::: "memory")
; #define PG8_BAR __builtin_amdgcn_s_barrier()
; __device__ __forceinline__ u32x4 pack8(f32x4 v0, f32x4 v1) { u32x4 w; w.x = cvt_pk_bf16(v0[0], v0[1]); w.y = cvt_pk_bf16(v0[2], v0[3]); w.z = cvt_pk_bf16(v1[0], v1[1]); w.w = cvt_pk_bf16(v1[2], v1[3]); return w; }
; template <class Epi>
; __device__ __forceinline__ void gemm_phase(LAS unsigned char* lds, const Gemm g, const StaticOrder& S, const Epi& E) {
;     ...
;     PG8_WAIT_V(0);
;     if (wr == 0) PG8_BAR;
;     PG8_BAR;
;     __device__ __forceinline__ void operator()(const f32x4 (&acc)[2][2][4][2], const Unit& u, int wr, int wc, int fr, int fq) const {
;     ...
;             for (int m = 0; m < 4; ++m) { bf16_t* rowp = O + (size_t)(row0 + ai * HALF + m * 16) * DFF + col0;
;                 const float r = rs[row0 + ai * HALF + m * 16], r2 = r * r;
;                 f32x4 h0, h1;
; #pragma unroll
;                 for (int j = 0; j < 4; ++j) {
;                     const float g0 = acc[ai][0][m][0][j], g1 = acc[ai][0][m][1][j];
;                     h0[j] = g0 * r2 * fast_rcp(1.0f + fast_exp2(g0 * (-LOG2E * r))) * acc[ai][1][m][0][j];
;                     h1[j] = g1 * r2 * fast_rcp(1.0f + fast_exp2(g1 * (-LOG2E * r))) * acc[ai][1][m][1][j]; }
;                 *(u32x4*)rowp = pack8(h0, h1); }
	v_cvt_pk_bf16_f32 v33, v33, v34
	v_cvt_pk_bf16_f32 v34, v40, v41
	v_cvt_pk_bf16_f32 v35, v38, v35
	global_store_dwordx4 v[36:37], v[32:35], off
	s_nop 1
	v_mov_b32_e32 v34, v209
	s_nop 0
	v_add_u32_e32 v32, 0xa0, v144
	v_mad_i64_i32 v[32:33], s[42:43], v32, s49, v[146:147]
	v_mul_f32_e32 v35, v34, v34
	v_mul_f32_e32 v34, 0xbfb8aa3b, v34
	v_mul_f32_e32 v36, v28, v35
	v_mul_f32_e32 v28, v28, v34
	v_exp_f32_e32 v28, v28
	s_nop 0
	v_add_f32_e32 v28, 1.0, v28
	v_rcp_f32_e32 v28, v28
	s_nop 0
	v_mul_f32_e32 v28, v36, v28
	v_mul_f32_e32 v28, v20, v28
	v_mul_f32_e32 v20, v24, v35
	v_mul_f32_e32 v24, v24, v34
	v_exp_f32_e32 v24, v24
	s_nop 0
	v_add_f32_e32 v24, 1.0, v24
	v_rcp_f32_e32 v24, v24
	s_nop 0
	v_mul_f32_e32 v20, v20, v24
	v_mul_f32_e32 v24, v16, v20
	v_mul_f32_e32 v20, v29, v34
	v_exp_f32_e32 v20, v20
	v_mul_f32_e32 v16, v29, v35
	v_add_f32_e32 v20, 1.0, v20
	v_rcp_f32_e32 v20, v20
	s_nop 0
	v_mul_f32_e32 v16, v16, v20
	v_mul_f32_e32 v16, v21, v16
	v_mul_f32_e32 v21, v25, v34
	v_exp_f32_e32 v21, v21
	v_mul_f32_e32 v20, v25, v35
	v_cvt_pk_bf16_f32 v16, v28, v16
	v_add_f32_e32 v21, 1.0, v21
	v_rcp_f32_e32 v21, v21
	s_nop 0
	v_mul_f32_e32 v20, v20, v21
	v_mul_f32_e32 v25, v17, v20
	v_mul_f32_e32 v20, v30, v34
	v_exp_f32_e32 v20, v20
	v_mul_f32_e32 v21, v26, v34
	v_exp_f32_e32 v21, v21
	v_mul_f32_e32 v17, v30, v35
	v_add_f32_e32 v20, 1.0, v20
	v_rcp_f32_e32 v20, v20
	v_add_f32_e32 v21, 1.0, v21
	v_rcp_f32_e32 v21, v21
	v_mul_f32_e32 v17, v17, v20
	v_mul_f32_e32 v20, v26, v35
	v_mul_f32_e32 v20, v20, v21
	v_mul_f32_e32 v17, v22, v17
	v_mul_f32_e32 v22, v18, v20
	v_mul_f32_e32 v20, v31, v34
	v_exp_f32_e32 v20, v20
	v_mul_f32_e32 v21, v27, v34
	v_exp_f32_e32 v21, v21
	v_mul_f32_e32 v18, v31, v35
	v_add_f32_e32 v20, 1.0, v20
	v_rcp_f32_e32 v20, v20
	v_add_f32_e32 v21, 1.0, v21
	v_rcp_f32_e32 v21, v21
	v_mul_f32_e32 v18, v18, v20
	v_mul_f32_e32 v20, v27, v35
	v_mul_f32_e32 v20, v20, v21
	v_mul_f32_e32 v18, v23, v18
	v_mul_f32_e32 v19, v19, v20
	v_lshl_add_u64 v[20:21], v[32:33], 0, v[112:113]
	v_cvt_pk_bf16_f32 v17, v17, v18
	v_cvt_pk_bf16_f32 v18, v24, v25
	v_cvt_pk_bf16_f32 v19, v22, v19
	global_store_dwordx4 v[20:21], v[16:19], off
	s_nop 1
	v_mov_b32_e32 v18, v210
	s_nop 0
	v_add_u32_e32 v16, 0xb0, v144
	v_mad_i64_i32 v[16:17], s[42:43], v16, s49, v[146:147]
	s_mov_b64 s[42:43], s[26:27]
	v_mul_f32_e32 v19, v18, v18
	v_mul_f32_e32 v18, 0xbfb8aa3b, v18
	v_mul_f32_e32 v20, v12, v19
	v_mul_f32_e32 v12, v12, v18
	v_exp_f32_e32 v12, v12
	s_nop 0
	v_add_f32_e32 v12, 1.0, v12
	v_rcp_f32_e32 v12, v12
	s_nop 0
	v_mul_f32_e32 v12, v20, v12
	v_mul_f32_e32 v12, v4, v12
	v_mul_f32_e32 v4, v8, v19
	v_mul_f32_e32 v8, v8, v18
	v_exp_f32_e32 v8, v8
	s_nop 0
	v_add_f32_e32 v8, 1.0, v8
	v_rcp_f32_e32 v8, v8
	s_nop 0
	v_mul_f32_e32 v4, v4, v8
	v_mul_f32_e32 v8, v0, v4
	v_mul_f32_e32 v4, v13, v18
	v_exp_f32_e32 v4, v4
	v_mul_f32_e32 v0, v13, v19
	v_add_f32_e32 v4, 1.0, v4
	v_rcp_f32_e32 v4, v4
	s_nop 0
	v_mul_f32_e32 v0, v0, v4
	v_mul_f32_e32 v0, v5, v0
	v_mul_f32_e32 v5, v9, v18
	v_exp_f32_e32 v5, v5
	v_mul_f32_e32 v4, v9, v19
	v_cvt_pk_bf16_f32 v0, v12, v0
	v_add_f32_e32 v5, 1.0, v5
	v_rcp_f32_e32 v5, v5
	s_nop 0
	v_mul_f32_e32 v4, v4, v5
	v_mul_f32_e32 v9, v1, v4
	v_mul_f32_e32 v4, v14, v18
	v_exp_f32_e32 v4, v4
	v_mul_f32_e32 v5, v10, v18
	v_exp_f32_e32 v5, v5
	v_mul_f32_e32 v1, v14, v19
	v_add_f32_e32 v4, 1.0, v4
	v_rcp_f32_e32 v4, v4
	v_add_f32_e32 v5, 1.0, v5
	v_rcp_f32_e32 v5, v5
	v_mul_f32_e32 v1, v1, v4
	v_mul_f32_e32 v4, v10, v19
	v_mul_f32_e32 v4, v4, v5
	v_mul_f32_e32 v1, v6, v1
	v_mul_f32_e32 v6, v2, v4
	v_mul_f32_e32 v4, v15, v18
	v_exp_f32_e32 v4, v4
	v_mul_f32_e32 v5, v11, v18
	v_exp_f32_e32 v5, v5
	v_mul_f32_e32 v2, v15, v19
	v_add_f32_e32 v4, 1.0, v4
	v_rcp_f32_e32 v4, v4
	v_add_f32_e32 v5, 1.0, v5
	v_rcp_f32_e32 v5, v5
	v_mul_f32_e32 v2, v2, v4
	v_mul_f32_e32 v4, v11, v19
	v_mul_f32_e32 v4, v4, v5
	v_mul_f32_e32 v2, v7, v2
	v_mul_f32_e32 v3, v3, v4
	v_lshl_add_u64 v[4:5], v[16:17], 0, v[112:113]
	v_cvt_pk_bf16_f32 v1, v1, v2
	v_cvt_pk_bf16_f32 v2, v8, v9
	v_cvt_pk_bf16_f32 v3, v6, v3
	global_store_dwordx4 v[4:5], v[0:3], off
	s_cbranch_vccz .LBB0_200
	s_waitcnt vmcnt(0)
	s_cmpk_gt_u32 s3, 0xff
	s_cbranch_scc1 .LBB0_207
	s_barrier

; #define PG8_STAGE(bufoff, gbase, voff) do { _Pragma("unroll") for (int _i = 0; _i < 2; ++_i) \
;         __builtin_amdgcn_global_load_lds((const unsigned*)((const char*)(gbase) + (voff)[_i]), (LAS unsigned*)(lds + (bufoff) + ldsw + _i * 8192), 16, 0, 0); } while (0)
; #define PG8_LDA(dst, b, h) do { _Pragma("unroll") for (int m = 0; m < 4; ++m) _Pragma("unroll") for (int k = 0; k < 2; ++k) dst[m][k] = *(const LAS bf16x8*)(lds + PG8_SA(b, h) + aoff + m * 2048 + k * 1024); } while (0)
; #define PG8_LDB(dst, b, h) do { _Pragma("unroll") for (int n = 0; n < 2; ++n) _Pragma("unroll") for (int k = 0; k < 2; ++k) dst[n][k] = *(const LAS bf16x8*)(lds + PG8_SB(b, h) + boff + n * 2048 + k * 1024); } while (0)
; #define PG8_MMA(ai, bj, At, Bt) do { __builtin_amdgcn_s_setprio(1); _Pragma("unroll") for (int m = 0; m < 4; ++m) _Pragma("unroll") for (int n = 0; n < 2; ++n) _Pragma("unroll") for (int k = 0; k < 2; ++k) \
;         acc[ai][bj][m][n] = __builtin_amdgcn_mfma_f32_16x16x32_bf16(Bt[n][k], At[m][k], acc[ai][bj][m][n], 0, 0, 0); __builtin_amdgcn_s_setprio(0); } while (0)
; #define PG8_WAIT_V(n) asm volatile("s_waitcnt vmcnt(" #n ")" ::: "memory")
; #define PG8_WAIT_L(n) asm volatile("s_waitcnt lgkmcnt(" #n ")" ::: "memory")
; template <class Epi>
; __device__ __forceinline__ void gemm_phase(LAS unsigned char* lds, const Gemm g, const StaticOrder& S, const Epi& E) {
;     ...
;         for (int t = 0; t < nt; t += 2) {
;             const bool last = (t == nt - 2);
;             const char* a1 = cA + (size_t)(t + 1) * kstep;
;             const char* a2 = last ? nA : cA + (size_t)(t + 2) * kstep; const char* b2 = last ? nB : cB + (size_t)(t + 2) * kstep;
;             const char* a3 = a2 + kstep; const char* b3 = b2 + kstep;
;             PG8_LDB(B0, 0, 0); PG8_SCHED; PG8_LDA(At, 0, 0); PG8_STAGE(PG8_SA(1, 1), a1 + hstep, voffA);
;             PG8_WAIT_L(8); PG8_BAR; PG8_WAIT_L(0); PG8_MMA(0, 0, At, B0); PG8_BAR; PG8_SCHED;
;             PG8_LDB(B1, 0, 1); PG8_STAGE(PG8_SB(0, 0), b2, voffB);
;             PG8_BAR; PG8_WAIT_L(0); PG8_MMA(0, 1, At, B1); PG8_BAR;
;             PG8_LDA(At, 0, 1); PG8_STAGE(PG8_SA(0, 0), a2, voffA);
;             PG8_BAR; PG8_WAIT_L(0); PG8_MMA(1, 0, At, B0); PG8_BAR; PG8_SCHED;
;             PG8_STAGE(PG8_SB(0, 1), b2 + hstep, voffB);
;             PG8_WAIT_V(6); PG8_BAR; PG8_MMA(1, 1, At, B1); PG8_BAR;
.LBB0_283:
	ds_read_b128 v[148:151], v145
	ds_read_b128 v[152:155], v145 offset:1024
	ds_read_b128 v[160:163], v145 offset:2048
	ds_read_b128 v[164:167], v145 offset:3072
	s_add_u32 s50, s48, 0x100
	s_addc_u32 s51, s49, 0
	s_cmpk_eq_i32 s65, 0x54
	s_cselect_b32 s55, s47, s51
	s_cselect_b32 s54, s46, s50
	s_cselect_b32 s53, s5, s64
	s_cselect_b32 s52, s4, s63
	s_add_i32 m0, s23, 0xc000
	ds_read_b128 v[168:171], v146
	ds_read_b128 v[172:175], v146 offset:1024
	ds_read_b128 v[176:179], v146 offset:2048
	ds_read_b128 v[180:183], v146 offset:3072
	ds_read_b128 v[184:187], v146 offset:4096
	ds_read_b128 v[188:191], v146 offset:5120
	ds_read_b128 v[192:195], v146 offset:6144
	ds_read_b128 v[196:199], v146 offset:7168
	global_load_lds_dwordx4 v136, s[48:49]
	s_add_i32 m0, s23, 0xe000
	s_nop 0
	global_load_lds_dwordx4 v138, s[48:49]
	s_waitcnt lgkmcnt(8)
	s_barrier
	s_waitcnt lgkmcnt(0)
	s_waitcnt lgkmcnt(0)
	v_mfma_f32_16x16x32_bf16 v[124:127], v[148:151], v[168:171], v[124:127]
	v_mfma_f32_16x16x32_bf16 v[120:123], v[160:163], v[168:171], v[120:123]
	v_mfma_f32_16x16x32_bf16 v[112:115], v[148:151], v[176:179], v[112:115]
	v_mfma_f32_16x16x32_bf16 v[104:107], v[160:163], v[176:179], v[104:107]
	v_mfma_f32_16x16x32_bf16 v[96:99], v[148:151], v[184:187], v[96:99]
	v_mfma_f32_16x16x32_bf16 v[88:91], v[160:163], v[184:187], v[88:91]
	v_mfma_f32_16x16x32_bf16 v[80:83], v[148:151], v[192:195], v[80:83]
	v_mfma_f32_16x16x32_bf16 v[72:75], v[160:163], v[192:195], v[72:75]
	v_mfma_f32_16x16x32_bf16 v[124:127], v[152:155], v[172:175], v[124:127]
	v_mfma_f32_16x16x32_bf16 v[120:123], v[164:167], v[172:175], v[120:123]
	v_mfma_f32_16x16x32_bf16 v[112:115], v[152:155], v[180:183], v[112:115]
	v_mfma_f32_16x16x32_bf16 v[104:107], v[164:167], v[180:183], v[104:107]
	v_mfma_f32_16x16x32_bf16 v[96:99], v[152:155], v[188:191], v[96:99]
	v_mfma_f32_16x16x32_bf16 v[88:91], v[164:167], v[188:191], v[88:91]
	v_mfma_f32_16x16x32_bf16 v[80:83], v[152:155], v[196:199], v[80:83]
	v_mfma_f32_16x16x32_bf16 v[72:75], v[164:167], v[196:199], v[72:75]
	s_barrier
	s_add_i32 s48, s39, s13
	s_add_u32 s98, s52, s6
	s_addc_u32 s99, s53, s7
	s_mov_b32 m0, s48
	ds_read_b128 v[200:203], v147
	ds_read_b128 v[204:207], v147 offset:1024
	ds_read_b128 v[208:211], v147 offset:2048
	ds_read_b128 v[212:215], v147 offset:3072
	global_load_lds_dwordx4 v132, s[52:53]
	s_add_i32 m0, s48, 0x2000
	s_nop 0
	global_load_lds_dwordx4 v128, s[52:53]
	s_barrier
	s_waitcnt lgkmcnt(0)
	s_waitcnt lgkmcnt(0)
	v_mfma_f32_16x16x32_bf16 v[116:119], v[200:203], v[168:171], v[116:119]
	v_mfma_f32_16x16x32_bf16 v[108:111], v[208:211], v[168:171], v[108:111]
	v_mfma_f32_16x16x32_bf16 v[100:103], v[200:203], v[176:179], v[100:103]
	v_mfma_f32_16x16x32_bf16 v[92:95], v[208:211], v[176:179], v[92:95]
	v_mfma_f32_16x16x32_bf16 v[84:87], v[200:203], v[184:187], v[84:87]
	v_mfma_f32_16x16x32_bf16 v[76:79], v[208:211], v[184:187], v[76:79]
	v_mfma_f32_16x16x32_bf16 v[68:71], v[200:203], v[192:195], v[68:71]
	v_mfma_f32_16x16x32_bf16 v[64:67], v[208:211], v[192:195], v[64:67]
	v_mfma_f32_16x16x32_bf16 v[116:119], v[204:207], v[172:175], v[116:119]
	v_mfma_f32_16x16x32_bf16 v[108:111], v[212:215], v[172:175], v[108:111]
	v_mfma_f32_16x16x32_bf16 v[100:103], v[204:207], v[180:183], v[100:103]
	v_mfma_f32_16x16x32_bf16 v[92:95], v[212:215], v[180:183], v[92:95]
	v_mfma_f32_16x16x32_bf16 v[84:87], v[204:207], v[188:191], v[84:87]
	v_mfma_f32_16x16x32_bf16 v[76:79], v[212:215], v[188:191], v[76:79]
	v_mfma_f32_16x16x32_bf16 v[68:71], v[204:207], v[196:199], v[68:71]
	v_mfma_f32_16x16x32_bf16 v[64:67], v[212:215], v[196:199], v[64:67]
	s_mov_b32 m0, s23
	s_add_u32 s100, s54, s6
	s_addc_u32 s101, s55, s7
	s_barrier
	ds_read_b128 v[168:171], v146 offset:16384
	ds_read_b128 v[172:175], v146 offset:17408
	ds_read_b128 v[176:179], v146 offset:18432
	ds_read_b128 v[180:183], v146 offset:19456
	ds_read_b128 v[184:187], v146 offset:20480
	ds_read_b128 v[188:191], v146 offset:21504
	ds_read_b128 v[192:195], v146 offset:22528
	ds_read_b128 v[196:199], v146 offset:23552
	global_load_lds_dwordx4 v134, s[54:55]
	s_mov_b32 m0, s30
	s_nop 0
	global_load_lds_dwordx4 v130, s[54:55]
	s_barrier
	s_waitcnt lgkmcnt(0)
	s_waitcnt lgkmcnt(0)
	v_mfma_f32_16x16x32_bf16 v[60:63], v[148:151], v[168:171], v[60:63]
	v_mfma_f32_16x16x32_bf16 v[56:59], v[160:163], v[168:171], v[56:59]
	v_mfma_f32_16x16x32_bf16 v[52:55], v[148:151], v[176:179], v[52:55]
	v_mfma_f32_16x16x32_bf16 v[44:47], v[160:163], v[176:179], v[44:47]
	v_mfma_f32_16x16x32_bf16 v[36:39], v[148:151], v[184:187], v[36:39]
	v_mfma_f32_16x16x32_bf16 v[28:31], v[160:163], v[184:187], v[28:31]
	v_mfma_f32_16x16x32_bf16 v[20:23], v[148:151], v[192:195], v[20:23]
	v_mfma_f32_16x16x32_bf16 v[12:15], v[160:163], v[192:195], v[12:15]
	v_mfma_f32_16x16x32_bf16 v[60:63], v[152:155], v[172:175], v[60:63]
	v_mfma_f32_16x16x32_bf16 v[56:59], v[164:167], v[172:175], v[56:59]
	v_mfma_f32_16x16x32_bf16 v[52:55], v[152:155], v[180:183], v[52:55]
	v_mfma_f32_16x16x32_bf16 v[44:47], v[164:167], v[180:183], v[44:47]
	v_mfma_f32_16x16x32_bf16 v[36:39], v[152:155], v[188:191], v[36:39]
	v_mfma_f32_16x16x32_bf16 v[28:31], v[164:167], v[188:191], v[28:31]
	v_mfma_f32_16x16x32_bf16 v[20:23], v[152:155], v[196:199], v[20:23]
	v_mfma_f32_16x16x32_bf16 v[12:15], v[164:167], v[196:199], v[12:15]
	s_barrier
	s_add_u32 s48, s52, 0x160000
	s_addc_u32 s49, s53, 0
	s_add_i32 s66, s40, s13
	s_mov_b32 m0, s66
	s_nop 0
	global_load_lds_dwordx4 v132, s[48:49]
	s_add_i32 m0, s66, 0x2000
	s_nop 0
	global_load_lds_dwordx4 v128, s[48:49]
	s_waitcnt vmcnt(6)
	s_barrier
; #define PG8_STAGE(bufoff, gbase, voff) do { _Pragma("unroll") for (int _i = 0; _i < 2; ++_i) \
;         __builtin_amdgcn_global_load_lds((const unsigned*)((const char*)(gbase) + (voff)[_i]), (LAS unsigned*)(lds + (bufoff) + ldsw + _i * 8192), 16, 0, 0); } while (0)
; #define PG8_LDA(dst, b, h) do { _Pragma("unroll") for (int m = 0; m < 4; ++m) _Pragma("unroll") for (int k = 0; k < 2; ++k) dst[m][k] = *(const LAS bf16x8*)(lds + PG8_SA(b, h) + aoff + m * 2048 + k * 1024); } while (0)
; #define PG8_LDB(dst, b, h) do { _Pragma("unroll") for (int n = 0; n < 2; ++n) _Pragma("unroll") for (int k = 0; k < 2; ++k) dst[n][k] = *(const LAS bf16x8*)(lds + PG8_SB(b, h) + boff + n * 2048 + k * 1024); } while (0)
; #define PG8_MMA(ai, bj, At, Bt) do { __builtin_amdgcn_s_setprio(1); _Pragma("unroll") for (int m = 0; m < 4; ++m) _Pragma("unroll") for (int n = 0; n < 2; ++n) _Pragma("unroll") for (int k = 0; k < 2; ++k) \
;         acc[ai][bj][m][n] = __builtin_amdgcn_mfma_f32_16x16x32_bf16(Bt[n][k], At[m][k], acc[ai][bj][m][n], 0, 0, 0); __builtin_amdgcn_s_setprio(0); } while (0)
; #define PG8_WAIT_V(n) asm volatile("s_waitcnt vmcnt(" #n ")" ::: "memory")
; #define PG8_WAIT_L(n) asm volatile("s_waitcnt lgkmcnt(" #n ")" ::: "memory")
; #define PG8_BAR __builtin_amdgcn_s_barrier()
; #define PG8_SCHED __builtin_amdgcn_sched_barrier(0)
; template <class Epi>
; __device__ __forceinline__ void gemm_phase(LAS unsigned char* lds, const Gemm g, const StaticOrder& S, const Epi& E) {
;     ...
;             PG8_WAIT_V(6); PG8_BAR; PG8_MMA(1, 1, At, B1); PG8_BAR;
;             PG8_LDB(B0, 1, 0); PG8_SCHED; PG8_LDA(At, 1, 0); PG8_STAGE(PG8_SA(0, 1), a2 + hstep, voffA);
;             PG8_WAIT_L(8); PG8_BAR; PG8_WAIT_L(0); PG8_MMA(0, 0, At, B0); PG8_BAR; PG8_SCHED;
;             PG8_LDB(B1, 1, 1); PG8_STAGE(PG8_SB(1, 0), b3, voffB);
;             PG8_BAR; PG8_WAIT_L(0); PG8_MMA(0, 1, At, B1); PG8_BAR;
;             PG8_LDA(At, 1, 1); PG8_STAGE(PG8_SA(1, 0), a3, voffA);
	v_mfma_f32_16x16x32_bf16 v[48:51], v[200:203], v[168:171], v[48:51]
	v_mfma_f32_16x16x32_bf16 v[40:43], v[208:211], v[168:171], v[40:43]
	v_mfma_f32_16x16x32_bf16 v[32:35], v[200:203], v[176:179], v[32:35]
	v_mfma_f32_16x16x32_bf16 v[24:27], v[208:211], v[176:179], v[24:27]
	v_mfma_f32_16x16x32_bf16 v[16:19], v[200:203], v[184:187], v[16:19]
	v_mfma_f32_16x16x32_bf16 v[8:11], v[208:211], v[184:187], v[8:11]
	v_mfma_f32_16x16x32_bf16 v[4:7], v[200:203], v[192:195], v[4:7]
	v_mfma_f32_16x16x32_bf16 v[0:3], v[208:211], v[192:195], v[0:3]
	v_mfma_f32_16x16x32_bf16 v[48:51], v[204:207], v[172:175], v[48:51]
	v_mfma_f32_16x16x32_bf16 v[40:43], v[212:215], v[172:175], v[40:43]
	v_mfma_f32_16x16x32_bf16 v[32:35], v[204:207], v[180:183], v[32:35]
	v_mfma_f32_16x16x32_bf16 v[24:27], v[212:215], v[180:183], v[24:27]
	v_mfma_f32_16x16x32_bf16 v[16:19], v[204:207], v[188:191], v[16:19]
	v_mfma_f32_16x16x32_bf16 v[8:11], v[212:215], v[188:191], v[8:11]
	v_mfma_f32_16x16x32_bf16 v[4:7], v[204:207], v[196:199], v[4:7]
	v_mfma_f32_16x16x32_bf16 v[0:3], v[212:215], v[196:199], v[0:3]
	s_add_i32 s66, 0, 0x18000
	v_add_u32_e32 v164, s66, v143
	s_barrier
	ds_read_b128 v[148:151], v164
	ds_read_b128 v[152:155], v164 offset:1024
	ds_read_b128 v[160:163], v164 offset:2048
	ds_read_b128 v[164:167], v164 offset:3072
	s_add_u32 s48, s54, 0x160000
	s_addc_u32 s49, s55, 0
	s_mov_b32 m0, s31
	ds_read_b128 v[168:171], v146 offset:32768
	ds_read_b128 v[172:175], v146 offset:33792
	ds_read_b128 v[176:179], v146 offset:34816
	ds_read_b128 v[180:183], v146 offset:35840
	ds_read_b128 v[184:187], v146 offset:36864
	ds_read_b128 v[188:191], v146 offset:37888
	ds_read_b128 v[192:195], v146 offset:38912
	ds_read_b128 v[196:199], v146 offset:39936
	global_load_lds_dwordx4 v134, s[48:49]
	s_mov_b32 m0, s33
	s_nop 0
	global_load_lds_dwordx4 v130, s[48:49]
	s_waitcnt lgkmcnt(8)
	s_barrier
	s_waitcnt lgkmcnt(0)
	s_waitcnt lgkmcnt(0)
	v_mfma_f32_16x16x32_bf16 v[124:127], v[148:151], v[168:171], v[124:127]
	v_mfma_f32_16x16x32_bf16 v[120:123], v[160:163], v[168:171], v[120:123]
	v_mfma_f32_16x16x32_bf16 v[112:115], v[148:151], v[176:179], v[112:115]
	v_mfma_f32_16x16x32_bf16 v[104:107], v[160:163], v[176:179], v[104:107]
	v_mfma_f32_16x16x32_bf16 v[96:99], v[148:151], v[184:187], v[96:99]
	v_mfma_f32_16x16x32_bf16 v[88:91], v[160:163], v[184:187], v[88:91]
	v_mfma_f32_16x16x32_bf16 v[80:83], v[148:151], v[192:195], v[80:83]
	v_mfma_f32_16x16x32_bf16 v[72:75], v[160:163], v[192:195], v[72:75]
	v_mfma_f32_16x16x32_bf16 v[124:127], v[152:155], v[172:175], v[124:127]
	v_mfma_f32_16x16x32_bf16 v[120:123], v[164:167], v[172:175], v[120:123]
	v_mfma_f32_16x16x32_bf16 v[112:115], v[152:155], v[180:183], v[112:115]
	v_mfma_f32_16x16x32_bf16 v[104:107], v[164:167], v[180:183], v[104:107]
	v_mfma_f32_16x16x32_bf16 v[96:99], v[152:155], v[188:191], v[96:99]
	v_mfma_f32_16x16x32_bf16 v[88:91], v[164:167], v[188:191], v[88:91]
	v_mfma_f32_16x16x32_bf16 v[80:83], v[152:155], v[196:199], v[80:83]
	v_mfma_f32_16x16x32_bf16 v[72:75], v[164:167], v[196:199], v[72:75]
	s_barrier
	s_add_i32 s54, 0, 0x1c000
	s_add_i32 s48, s66, s13
	v_add_u32_e32 v212, s54, v143
	s_mov_b32 m0, s48
	ds_read_b128 v[200:203], v212
	ds_read_b128 v[204:207], v212 offset:1024
	ds_read_b128 v[208:211], v212 offset:2048
	ds_read_b128 v[212:215], v212 offset:3072
	global_load_lds_dwordx4 v132, s[98:99]
	s_add_i32 m0, s48, 0x2000
	s_nop 0
	global_load_lds_dwordx4 v128, s[98:99]
	s_barrier
	s_waitcnt lgkmcnt(0)
	s_waitcnt lgkmcnt(0)
	v_mfma_f32_16x16x32_bf16 v[116:119], v[200:203], v[168:171], v[116:119]
	v_mfma_f32_16x16x32_bf16 v[108:111], v[208:211], v[168:171], v[108:111]
	v_mfma_f32_16x16x32_bf16 v[100:103], v[200:203], v[176:179], v[100:103]
	v_mfma_f32_16x16x32_bf16 v[92:95], v[208:211], v[176:179], v[92:95]
	v_mfma_f32_16x16x32_bf16 v[84:87], v[200:203], v[184:187], v[84:87]
	v_mfma_f32_16x16x32_bf16 v[76:79], v[208:211], v[184:187], v[76:79]
	v_mfma_f32_16x16x32_bf16 v[68:71], v[200:203], v[192:195], v[68:71]
	v_mfma_f32_16x16x32_bf16 v[64:67], v[208:211], v[192:195], v[64:67]
	v_mfma_f32_16x16x32_bf16 v[116:119], v[204:207], v[172:175], v[116:119]
	v_mfma_f32_16x16x32_bf16 v[108:111], v[212:215], v[172:175], v[108:111]
	v_mfma_f32_16x16x32_bf16 v[100:103], v[204:207], v[180:183], v[100:103]
	v_mfma_f32_16x16x32_bf16 v[92:95], v[212:215], v[180:183], v[92:95]
	v_mfma_f32_16x16x32_bf16 v[84:87], v[204:207], v[188:191], v[84:87]
	v_mfma_f32_16x16x32_bf16 v[76:79], v[212:215], v[188:191], v[76:79]
	v_mfma_f32_16x16x32_bf16 v[68:71], v[204:207], v[196:199], v[68:71]
	v_mfma_f32_16x16x32_bf16 v[64:67], v[212:215], v[196:199], v[64:67]
	s_mov_b32 m0, s34
	s_barrier
	ds_read_b128 v[168:171], v146 offset:49152
	ds_read_b128 v[172:175], v146 offset:50176
	ds_read_b128 v[176:179], v146 offset:51200
	ds_read_b128 v[180:183], v146 offset:52224
	ds_read_b128 v[184:187], v146 offset:53248
	ds_read_b128 v[188:191], v146 offset:54272
	ds_read_b128 v[192:195], v146 offset:55296
	ds_read_b128 v[196:199], v146 offset:56320
	global_load_lds_dwordx4 v134, s[100:101]
	s_mov_b32 m0, s36
	s_nop 0
	global_load_lds_dwordx4 v130, s[100:101]
	s_barrier
; #define PG8_STAGE(bufoff, gbase, voff) do { _Pragma("unroll") for (int _i = 0; _i < 2; ++_i) \
;         __builtin_amdgcn_global_load_lds((const unsigned*)((const char*)(gbase) + (voff)[_i]), (LAS unsigned*)(lds + (bufoff) + ldsw + _i * 8192), 16, 0, 0); } while (0)
; #define PG8_MMA(ai, bj, At, Bt) do { __builtin_amdgcn_s_setprio(1); _Pragma("unroll") for (int m = 0; m < 4; ++m) _Pragma("unroll") for (int n = 0; n < 2; ++n) _Pragma("unroll") for (int k = 0; k < 2; ++k) \
;         acc[ai][bj][m][n] = __builtin_amdgcn_mfma_f32_16x16x32_bf16(Bt[n][k], At[m][k], acc[ai][bj][m][n], 0, 0, 0); __builtin_amdgcn_s_setprio(0); } while (0)
; #define PG8_WAIT_V(n) asm volatile("s_waitcnt vmcnt(" #n ")" ::: "memory")
; #define PG8_WAIT_L(n) asm volatile("s_waitcnt lgkmcnt(" #n ")" ::: "memory")
; #define PG8_BAR __builtin_amdgcn_s_barrier()
; #define PG8_SCHED __builtin_amdgcn_sched_barrier(0)
; template <class Epi>
; __device__ __forceinline__ void gemm_phase(LAS unsigned char* lds, const Gemm g, const StaticOrder& S, const Epi& E) {
;     ...
;             PG8_BAR; PG8_WAIT_L(0); PG8_MMA(1, 0, At, B0); PG8_BAR; PG8_SCHED;
;             PG8_STAGE(PG8_SB(1, 1), b3 + hstep, voffB);
;             PG8_WAIT_V(6); PG8_BAR; PG8_MMA(1, 1, At, B1); PG8_BAR;
;         }
	s_waitcnt lgkmcnt(0)
	s_waitcnt lgkmcnt(0)
	v_mfma_f32_16x16x32_bf16 v[60:63], v[148:151], v[168:171], v[60:63]
	v_mfma_f32_16x16x32_bf16 v[56:59], v[160:163], v[168:171], v[56:59]
	v_mfma_f32_16x16x32_bf16 v[52:55], v[148:151], v[176:179], v[52:55]
	v_mfma_f32_16x16x32_bf16 v[44:47], v[160:163], v[176:179], v[44:47]
	v_mfma_f32_16x16x32_bf16 v[36:39], v[148:151], v[184:187], v[36:39]
	v_mfma_f32_16x16x32_bf16 v[28:31], v[160:163], v[184:187], v[28:31]
	v_mfma_f32_16x16x32_bf16 v[20:23], v[148:151], v[192:195], v[20:23]
	v_mfma_f32_16x16x32_bf16 v[12:15], v[160:163], v[192:195], v[12:15]
	v_mfma_f32_16x16x32_bf16 v[60:63], v[152:155], v[172:175], v[60:63]
	v_mfma_f32_16x16x32_bf16 v[56:59], v[164:167], v[172:175], v[56:59]
	v_mfma_f32_16x16x32_bf16 v[52:55], v[152:155], v[180:183], v[52:55]
	v_mfma_f32_16x16x32_bf16 v[44:47], v[164:167], v[180:183], v[44:47]
	v_mfma_f32_16x16x32_bf16 v[36:39], v[152:155], v[188:191], v[36:39]
	v_mfma_f32_16x16x32_bf16 v[28:31], v[164:167], v[188:191], v[28:31]
	v_mfma_f32_16x16x32_bf16 v[20:23], v[152:155], v[196:199], v[20:23]
	v_mfma_f32_16x16x32_bf16 v[12:15], v[164:167], v[196:199], v[12:15]
	s_barrier
	s_add_u32 s48, s52, 0x160080
	s_addc_u32 s49, s53, 0
	s_add_i32 s52, s54, s13
	s_mov_b32 m0, s52
	s_nop 0
	global_load_lds_dwordx4 v132, s[48:49]
	s_add_i32 m0, s52, 0x2000
	s_nop 0
	global_load_lds_dwordx4 v128, s[48:49]
	s_waitcnt vmcnt(6)
	s_barrier
	v_mfma_f32_16x16x32_bf16 v[48:51], v[200:203], v[168:171], v[48:51]
	v_mfma_f32_16x16x32_bf16 v[40:43], v[208:211], v[168:171], v[40:43]
	v_mfma_f32_16x16x32_bf16 v[32:35], v[200:203], v[176:179], v[32:35]
	v_mfma_f32_16x16x32_bf16 v[24:27], v[208:211], v[176:179], v[24:27]
	v_mfma_f32_16x16x32_bf16 v[16:19], v[200:203], v[184:187], v[16:19]
	v_mfma_f32_16x16x32_bf16 v[8:11], v[208:211], v[184:187], v[8:11]
	v_mfma_f32_16x16x32_bf16 v[4:7], v[200:203], v[192:195], v[4:7]
	v_mfma_f32_16x16x32_bf16 v[0:3], v[208:211], v[192:195], v[0:3]
	v_mfma_f32_16x16x32_bf16 v[48:51], v[204:207], v[172:175], v[48:51]
	v_mfma_f32_16x16x32_bf16 v[40:43], v[212:215], v[172:175], v[40:43]
	v_mfma_f32_16x16x32_bf16 v[32:35], v[204:207], v[180:183], v[32:35]
	v_mfma_f32_16x16x32_bf16 v[24:27], v[212:215], v[180:183], v[24:27]
	v_mfma_f32_16x16x32_bf16 v[16:19], v[204:207], v[188:191], v[16:19]
	v_mfma_f32_16x16x32_bf16 v[8:11], v[212:215], v[188:191], v[8:11]
	v_mfma_f32_16x16x32_bf16 v[4:7], v[204:207], v[196:199], v[4:7]
	v_mfma_f32_16x16x32_bf16 v[0:3], v[212:215], v[196:199], v[0:3]
	s_add_i32 s65, s65, 2
	s_add_u32 s63, s63, 0x100
	s_addc_u32 s64, s64, 0
	s_cmpk_gt_u32 s65, 0x55
	s_mov_b64 s[48:49], s[50:51]
	s_barrier
	s_cbranch_scc0 .LBB0_283
; #define PG8_WAIT_V(n) asm volatile("s_waitcnt vmcnt(" #n ")" ::: "memory")
; #define PG8_BAR __builtin_amdgcn_s_barrier()
; __device__ __forceinline__ u32x4 pack8(f32x4 v0, f32x4 v1) { u32x4 w; w.x = cvt_pk_bf16(v0[0], v0[1]); w.y = cvt_pk_bf16(v0[2], v0[3]); w.z = cvt_pk_bf16(v1[0], v1[1]); w.w = cvt_pk_bf16(v1[2], v1[3]); return w; }
; template <class Epi>
; __device__ __forceinline__ void gemm_phase(LAS unsigned char* lds, const Gemm g, const StaticOrder& S, const Epi& E) {
;     ...
;         cur = nxt; cA = nA; cB = nB; ++ui;
;     }
;     PG8_WAIT_V(0);
;     if (wr == 0) PG8_BAR;
;     PG8_BAR;
;     __device__ __forceinline__ void operator()(const f32x4 (&acc)[2][2][4][2], const Unit& u, int wr, int wc, int fr, int fq) const {
;         const int row0 = u.pm * BM + wr * 64 + fr, col0 = u.pn * BM + wc * 32 + 8 * fq;
; #pragma unroll
;         for (int ai = 0; ai < 2; ++ai)
; #pragma unroll
;             for (int m = 0; m < 4; ++m) { bf16_t* rowp = O + (size_t)(row0 + ai * HALF + m * 16) * ldc + col0;
; #pragma unroll
;                 for (int bj = 0; bj < 2; ++bj) *(u32x4*)(rowp + bj * HALF) = pack8(acc[ai][bj][m][0], acc[ai][bj][m][1]); }
;     }
	v_lshl_add_u32 v148, s61, 8, v142
	v_lshl_or_b32 v140, s62, 8, v144
	v_ashrrev_i32_e32 v149, 31, v148
	v_ashrrev_i32_e32 v141, 31, v140
	v_lshlrev_b64 v[150:151], 12, v[148:149]
	v_lshl_add_u64 v[150:151], s[24:25], 0, v[150:151]
	v_lshlrev_b64 v[152:153], 1, v[140:141]
	v_lshl_add_u64 v[140:141], v[150:151], 0, v[152:153]
	v_cvt_pk_bf16_f32 v124, v124, v125
	v_cvt_pk_bf16_f32 v125, v126, v127
	v_cvt_pk_bf16_f32 v126, v120, v121
	v_cvt_pk_bf16_f32 v127, v122, v123
	global_store_dwordx4 v[140:141], v[124:127], off
	v_cvt_pk_bf16_f32 v116, v116, v117
	v_cvt_pk_bf16_f32 v117, v118, v119
	v_cvt_pk_bf16_f32 v118, v108, v109
	v_or_b32_e32 v108, 16, v148
	v_ashrrev_i32_e32 v109, 31, v108
	v_lshlrev_b64 v[108:109], 12, v[108:109]
	v_lshl_add_u64 v[108:109], s[24:25], 0, v[108:109]
	v_cvt_pk_bf16_f32 v119, v110, v111
	global_store_dwordx4 v[140:141], v[116:119], off offset:256
	s_mov_b32 s62, s59
	s_mov_b32 s61, s60
	v_lshl_add_u64 v[116:117], v[108:109], 0, v[152:153]
	v_cvt_pk_bf16_f32 v108, v112, v113
	v_cvt_pk_bf16_f32 v109, v114, v115
	v_cvt_pk_bf16_f32 v110, v104, v105
	v_cvt_pk_bf16_f32 v111, v106, v107
	global_store_dwordx4 v[116:117], v[108:111], off
	v_cvt_pk_bf16_f32 v100, v100, v101
	v_cvt_pk_bf16_f32 v101, v102, v103
	v_cvt_pk_bf16_f32 v102, v92, v93
	v_or_b32_e32 v92, 32, v148
	v_ashrrev_i32_e32 v93, 31, v92
	v_lshlrev_b64 v[92:93], 12, v[92:93]
	v_lshl_add_u64 v[92:93], s[24:25], 0, v[92:93]
	v_cvt_pk_bf16_f32 v103, v94, v95
	global_store_dwordx4 v[116:117], v[100:103], off offset:256
	s_mov_b64 s[50:51], s[4:5]
	s_mov_b64 s[48:49], s[46:47]
	v_lshl_add_u64 v[100:101], v[92:93], 0, v[152:153]
	v_cvt_pk_bf16_f32 v92, v96, v97
	v_cvt_pk_bf16_f32 v93, v98, v99
	v_cvt_pk_bf16_f32 v94, v88, v89
	v_cvt_pk_bf16_f32 v95, v90, v91
	global_store_dwordx4 v[100:101], v[92:95], off
	v_cvt_pk_bf16_f32 v84, v84, v85
	v_cvt_pk_bf16_f32 v85, v86, v87
	v_cvt_pk_bf16_f32 v86, v76, v77
	v_or_b32_e32 v76, 48, v148
	v_ashrrev_i32_e32 v77, 31, v76
	v_lshlrev_b64 v[76:77], 12, v[76:77]
	v_lshl_add_u64 v[76:77], s[24:25], 0, v[76:77]
	v_cvt_pk_bf16_f32 v87, v78, v79
	global_store_dwordx4 v[100:101], v[84:87], off offset:256
	s_nop 1
	v_lshl_add_u64 v[84:85], v[76:77], 0, v[152:153]
	v_cvt_pk_bf16_f32 v76, v80, v81
	v_cvt_pk_bf16_f32 v77, v82, v83
	v_cvt_pk_bf16_f32 v78, v72, v73
	v_cvt_pk_bf16_f32 v79, v74, v75
	global_store_dwordx4 v[84:85], v[76:79], off
	v_cvt_pk_bf16_f32 v68, v68, v69
	v_cvt_pk_bf16_f32 v69, v70, v71
	v_cvt_pk_bf16_f32 v70, v64, v65
	v_cvt_pk_bf16_f32 v71, v66, v67
	global_store_dwordx4 v[84:85], v[68:71], off offset:256
	v_cvt_pk_bf16_f32 v60, v60, v61
	v_cvt_pk_bf16_f32 v61, v62, v63
	v_cvt_pk_bf16_f32 v62, v56, v57
	v_add_co_u32_e32 v56, vcc, s41, v140
	v_lshl_add_u64 v[64:65], v[140:141], 0, s[8:9]
	s_nop 0
	v_addc_co_u32_e32 v57, vcc, 0, v141, vcc
	v_cvt_pk_bf16_f32 v63, v58, v59
	global_store_dwordx4 v[56:57], v[60:63], off
	v_cvt_pk_bf16_f32 v48, v48, v49
	v_cvt_pk_bf16_f32 v49, v50, v51
	v_cvt_pk_bf16_f32 v50, v40, v41
	v_cvt_pk_bf16_f32 v51, v42, v43
	global_store_dwordx4 v[64:65], v[48:51], off offset:256
	v_cvt_pk_bf16_f32 v40, v52, v53
	v_cvt_pk_bf16_f32 v41, v54, v55
	v_cvt_pk_bf16_f32 v42, v44, v45
	v_add_co_u32_e32 v44, vcc, s56, v140
	s_nop 0
	v_lshl_add_u64 v[48:49], v[140:141], 0, s[26:27]
	v_addc_co_u32_e32 v45, vcc, 0, v141, vcc
	v_cvt_pk_bf16_f32 v43, v46, v47
	global_store_dwordx4 v[44:45], v[40:43], off
	v_cvt_pk_bf16_f32 v32, v32, v33
	v_cvt_pk_bf16_f32 v33, v34, v35
	v_cvt_pk_bf16_f32 v34, v24, v25
	v_cvt_pk_bf16_f32 v35, v26, v27
	global_store_dwordx4 v[48:49], v[32:35], off offset:256
	v_cvt_pk_bf16_f32 v24, v36, v37
	v_cvt_pk_bf16_f32 v25, v38, v39
	v_cvt_pk_bf16_f32 v26, v28, v29
	v_add_co_u32_e32 v28, vcc, s57, v140
	s_nop 0
	v_lshl_add_u64 v[32:33], v[140:141], 0, s[28:29]
	v_addc_co_u32_e32 v29, vcc, 0, v141, vcc
	v_cvt_pk_bf16_f32 v27, v30, v31
	global_store_dwordx4 v[28:29], v[24:27], off
	v_cvt_pk_bf16_f32 v16, v16, v17
	v_cvt_pk_bf16_f32 v17, v18, v19
	v_cvt_pk_bf16_f32 v18, v8, v9
	v_cvt_pk_bf16_f32 v19, v10, v11
	global_store_dwordx4 v[32:33], v[16:19], off offset:256
	v_cvt_pk_bf16_f32 v8, v20, v21
	v_cvt_pk_bf16_f32 v9, v22, v23
	v_cvt_pk_bf16_f32 v10, v12, v13
	v_add_co_u32_e32 v12, vcc, s58, v140
	s_nop 0
	v_lshl_add_u64 v[16:17], v[140:141], 0, s[42:43]
	v_addc_co_u32_e32 v13, vcc, 0, v141, vcc
	s_and_b64 vcc, exec, s[44:45]
	v_cvt_pk_bf16_f32 v11, v14, v15
	global_store_dwordx4 v[12:13], v[8:11], off
	v_cvt_pk_bf16_f32 v4, v4, v5
	v_cvt_pk_bf16_f32 v5, v6, v7
	v_cvt_pk_bf16_f32 v6, v0, v1
	v_cvt_pk_bf16_f32 v7, v2, v3
	global_store_dwordx4 v[16:17], v[4:7], off offset:256
	s_cbranch_vccz .LBB0_276
	s_waitcnt vmcnt(0)
	s_cmpk_gt_u32 s3, 0xff
	v_readlane_b32 s62, v232, 20
	s_cbranch_scc1 .LBB0_287
	s_barrier

; #define PG8_STAGE(bufoff, gbase, voff) do { _Pragma("unroll") for (int _i = 0; _i < 2; ++_i) \
;         __builtin_amdgcn_global_load_lds((const unsigned*)((const char*)(gbase) + (voff)[_i]), (LAS unsigned*)(lds + (bufoff) + ldsw + _i * 8192), 16, 0, 0); } while (0)
; #define PG8_LDA(dst, b, h) do { _Pragma("unroll") for (int m = 0; m < 4; ++m) _Pragma("unroll") for (int k = 0; k < 2; ++k) dst[m][k] = *(const LAS bf16x8*)(lds + PG8_SA(b, h) + aoff + m * 2048 + k * 1024); } while (0)
; #define PG8_LDB(dst, b, h) do { _Pragma("unroll") for (int n = 0; n < 2; ++n) _Pragma("unroll") for (int k = 0; k < 2; ++k) dst[n][k] = *(const LAS bf16x8*)(lds + PG8_SB(b, h) + boff + n * 2048 + k * 1024); } while (0)
; #define PG8_MMA(ai, bj, At, Bt) do { __builtin_amdgcn_s_setprio(1); _Pragma("unroll") for (int m = 0; m < 4; ++m) _Pragma("unroll") for (int n = 0; n < 2; ++n) _Pragma("unroll") for (int k = 0; k < 2; ++k) \
;         acc[ai][bj][m][n] = __builtin_amdgcn_mfma_f32_16x16x32_bf16(Bt[n][k], At[m][k], acc[ai][bj][m][n], 0, 0, 0); __builtin_amdgcn_s_setprio(0); } while (0)
; #define PG8_WAIT_V(n) asm volatile("s_waitcnt vmcnt(" #n ")" ::: "memory")
; #define PG8_WAIT_L(n) asm volatile("s_waitcnt lgkmcnt(" #n ")" ::: "memory")
; template <class Epi>
; __device__ __forceinline__ void gemm_phase(LAS unsigned char* lds, const Gemm g, const StaticOrder& S, const Epi& E) {
;     ...
;         for (int t = 0; t < nt; t += 2) {
;             const bool last = (t == nt - 2);
;             const char* a1 = cA + (size_t)(t + 1) * kstep;
;             const char* a2 = last ? nA : cA + (size_t)(t + 2) * kstep; const char* b2 = last ? nB : cB + (size_t)(t + 2) * kstep;
;             const char* a3 = a2 + kstep; const char* b3 = b2 + kstep;
;             PG8_LDB(B0, 0, 0); PG8_SCHED; PG8_LDA(At, 0, 0); PG8_STAGE(PG8_SA(1, 1), a1 + hstep, voffA);
;             PG8_WAIT_L(8); PG8_BAR; PG8_WAIT_L(0); PG8_MMA(0, 0, At, B0); PG8_BAR; PG8_SCHED;
;             PG8_LDB(B1, 0, 1); PG8_STAGE(PG8_SB(0, 0), b2, voffB);
;             PG8_BAR; PG8_WAIT_L(0); PG8_MMA(0, 1, At, B1); PG8_BAR;
;             PG8_LDA(At, 0, 1); PG8_STAGE(PG8_SA(0, 0), a2, voffA);
;             PG8_BAR; PG8_WAIT_L(0); PG8_MMA(1, 0, At, B0); PG8_BAR; PG8_SCHED;
;             PG8_STAGE(PG8_SB(0, 1), b2 + hstep, voffB);
;             PG8_WAIT_V(6); PG8_BAR; PG8_MMA(1, 1, At, B1); PG8_BAR;
.LBB0_407:
	ds_read_b128 v[150:153], v164
	ds_read_b128 v[154:157], v164 offset:1024
	ds_read_b128 v[168:171], v164 offset:2048
	ds_read_b128 v[172:175], v164 offset:3072
	s_add_u32 s48, s46, 0xfff80080
	s_addc_u32 s49, s47, -1
	s_cmp_eq_u32 s57, 28
	s_cselect_b32 s51, s9, s49
	s_cselect_b32 s50, s45, s48
	s_cselect_b32 s49, s7, s56
	s_cselect_b32 s48, s54, s55
	s_add_i32 m0, s27, 0xc000
	ds_read_b128 v[176:179], v165
	ds_read_b128 v[180:183], v165 offset:1024
	ds_read_b128 v[184:187], v165 offset:2048
	ds_read_b128 v[188:191], v165 offset:3072
	ds_read_b128 v[192:195], v165 offset:4096
	ds_read_b128 v[196:199], v165 offset:5120
	ds_read_b128 v[200:203], v165 offset:6144
	ds_read_b128 v[204:207], v165 offset:7168
	global_load_lds_dwordx4 v142, s[46:47]
	s_add_i32 m0, s27, 0xe000
	s_nop 0
	global_load_lds_dwordx4 v144, s[46:47]
	s_waitcnt lgkmcnt(8)
	s_barrier
	s_waitcnt lgkmcnt(0)
	s_waitcnt lgkmcnt(0)
	v_mfma_f32_16x16x32_bf16 v[124:127], v[150:153], v[176:179], v[124:127]
	v_mfma_f32_16x16x32_bf16 v[120:123], v[168:171], v[176:179], v[120:123]
	v_mfma_f32_16x16x32_bf16 v[108:111], v[150:153], v[184:187], v[108:111]
	v_mfma_f32_16x16x32_bf16 v[104:107], v[168:171], v[184:187], v[104:107]
	v_mfma_f32_16x16x32_bf16 v[92:95], v[150:153], v[192:195], v[92:95]
	v_mfma_f32_16x16x32_bf16 v[88:91], v[168:171], v[192:195], v[88:91]
	v_mfma_f32_16x16x32_bf16 v[76:79], v[150:153], v[200:203], v[76:79]
	v_mfma_f32_16x16x32_bf16 v[72:75], v[168:171], v[200:203], v[72:75]
	v_mfma_f32_16x16x32_bf16 v[124:127], v[154:157], v[180:183], v[124:127]
	v_mfma_f32_16x16x32_bf16 v[120:123], v[172:175], v[180:183], v[120:123]
	v_mfma_f32_16x16x32_bf16 v[108:111], v[154:157], v[188:191], v[108:111]
	v_mfma_f32_16x16x32_bf16 v[104:107], v[172:175], v[188:191], v[104:107]
	v_mfma_f32_16x16x32_bf16 v[92:95], v[154:157], v[196:199], v[92:95]
	v_mfma_f32_16x16x32_bf16 v[88:91], v[172:175], v[196:199], v[88:91]
	v_mfma_f32_16x16x32_bf16 v[76:79], v[154:157], v[204:207], v[76:79]
	v_mfma_f32_16x16x32_bf16 v[72:75], v[172:175], v[204:207], v[72:75]
	s_barrier
	s_add_i32 s58, s41, s23
	s_add_u32 s98, s48, s2
	s_addc_u32 s99, s49, s3
	s_mov_b32 m0, s58
	ds_read_b128 v[208:211], v166
	ds_read_b128 v[212:215], v166 offset:1024
	ds_read_b128 v[216:219], v166 offset:2048
	ds_read_b128 v[220:223], v166 offset:3072
	global_load_lds_dwordx4 v132, s[48:49]
	s_add_i32 m0, s58, 0x2000
	s_nop 0
	global_load_lds_dwordx4 v128, s[48:49]
	s_barrier
	s_waitcnt lgkmcnt(0)
	s_waitcnt lgkmcnt(0)
	v_mfma_f32_16x16x32_bf16 v[116:119], v[208:211], v[176:179], v[116:119]
	v_mfma_f32_16x16x32_bf16 v[112:115], v[216:219], v[176:179], v[112:115]
	v_mfma_f32_16x16x32_bf16 v[100:103], v[208:211], v[184:187], v[100:103]
	v_mfma_f32_16x16x32_bf16 v[96:99], v[216:219], v[184:187], v[96:99]
	v_mfma_f32_16x16x32_bf16 v[84:87], v[208:211], v[192:195], v[84:87]
	v_mfma_f32_16x16x32_bf16 v[80:83], v[216:219], v[192:195], v[80:83]
	v_mfma_f32_16x16x32_bf16 v[68:71], v[208:211], v[200:203], v[68:71]
	v_mfma_f32_16x16x32_bf16 v[64:67], v[216:219], v[200:203], v[64:67]
	v_mfma_f32_16x16x32_bf16 v[116:119], v[212:215], v[180:183], v[116:119]
	v_mfma_f32_16x16x32_bf16 v[112:115], v[220:223], v[180:183], v[112:115]
	v_mfma_f32_16x16x32_bf16 v[100:103], v[212:215], v[188:191], v[100:103]
	v_mfma_f32_16x16x32_bf16 v[96:99], v[220:223], v[188:191], v[96:99]
	v_mfma_f32_16x16x32_bf16 v[84:87], v[212:215], v[196:199], v[84:87]
	v_mfma_f32_16x16x32_bf16 v[80:83], v[220:223], v[196:199], v[80:83]
	v_mfma_f32_16x16x32_bf16 v[68:71], v[212:215], v[204:207], v[68:71]
	v_mfma_f32_16x16x32_bf16 v[64:67], v[220:223], v[204:207], v[64:67]
	s_mov_b32 m0, s27
	s_add_u32 s100, s50, s2
	s_addc_u32 s101, s51, s3
	s_barrier
	ds_read_b128 v[176:179], v165 offset:16384
	ds_read_b128 v[180:183], v165 offset:17408
	ds_read_b128 v[184:187], v165 offset:18432
	ds_read_b128 v[188:191], v165 offset:19456
	ds_read_b128 v[192:195], v165 offset:20480
	ds_read_b128 v[196:199], v165 offset:21504
	ds_read_b128 v[200:203], v165 offset:22528
	ds_read_b128 v[204:207], v165 offset:23552
	global_load_lds_dwordx4 v134, s[50:51]
	s_mov_b32 m0, s30
	s_nop 0
	global_load_lds_dwordx4 v130, s[50:51]
	s_barrier
	s_waitcnt lgkmcnt(0)
	s_waitcnt lgkmcnt(0)
	v_mfma_f32_16x16x32_bf16 v[60:63], v[150:153], v[176:179], v[60:63]
	v_mfma_f32_16x16x32_bf16 v[56:59], v[168:171], v[176:179], v[56:59]
	v_mfma_f32_16x16x32_bf16 v[44:47], v[150:153], v[184:187], v[44:47]
	v_mfma_f32_16x16x32_bf16 v[40:43], v[168:171], v[184:187], v[40:43]
	v_mfma_f32_16x16x32_bf16 v[28:31], v[150:153], v[192:195], v[28:31]
	v_mfma_f32_16x16x32_bf16 v[24:27], v[168:171], v[192:195], v[24:27]
	v_mfma_f32_16x16x32_bf16 v[12:15], v[150:153], v[200:203], v[12:15]
	v_mfma_f32_16x16x32_bf16 v[8:11], v[168:171], v[200:203], v[8:11]
	v_mfma_f32_16x16x32_bf16 v[60:63], v[154:157], v[180:183], v[60:63]
	v_mfma_f32_16x16x32_bf16 v[56:59], v[172:175], v[180:183], v[56:59]
	v_mfma_f32_16x16x32_bf16 v[44:47], v[154:157], v[188:191], v[44:47]
	v_mfma_f32_16x16x32_bf16 v[40:43], v[172:175], v[188:191], v[40:43]
	v_mfma_f32_16x16x32_bf16 v[28:31], v[154:157], v[196:199], v[28:31]
	v_mfma_f32_16x16x32_bf16 v[24:27], v[172:175], v[196:199], v[24:27]
	v_mfma_f32_16x16x32_bf16 v[12:15], v[154:157], v[204:207], v[12:15]
	v_mfma_f32_16x16x32_bf16 v[8:11], v[172:175], v[204:207], v[8:11]
	s_barrier
	s_add_u32 s58, s48, 0x80000
	s_addc_u32 s59, s49, 0
	s_add_i32 s60, s52, s23
	s_mov_b32 m0, s60
	s_nop 0
	global_load_lds_dwordx4 v132, s[58:59]
	s_add_i32 m0, s60, 0x2000
	s_nop 0
	global_load_lds_dwordx4 v128, s[58:59]
	s_waitcnt vmcnt(6)
	s_barrier
; #define PG8_STAGE(bufoff, gbase, voff) do { _Pragma("unroll") for (int _i = 0; _i < 2; ++_i) \
;         __builtin_amdgcn_global_load_lds((const unsigned*)((const char*)(gbase) + (voff)[_i]), (LAS unsigned*)(lds + (bufoff) + ldsw + _i * 8192), 16, 0, 0); } while (0)
; #define PG8_LDA(dst, b, h) do { _Pragma("unroll") for (int m = 0; m < 4; ++m) _Pragma("unroll") for (int k = 0; k < 2; ++k) dst[m][k] = *(const LAS bf16x8*)(lds + PG8_SA(b, h) + aoff + m * 2048 + k * 1024); } while (0)
; #define PG8_LDB(dst, b, h) do { _Pragma("unroll") for (int n = 0; n < 2; ++n) _Pragma("unroll") for (int k = 0; k < 2; ++k) dst[n][k] = *(const LAS bf16x8*)(lds + PG8_SB(b, h) + boff + n * 2048 + k * 1024); } while (0)
; #define PG8_MMA(ai, bj, At, Bt) do { __builtin_amdgcn_s_setprio(1); _Pragma("unroll") for (int m = 0; m < 4; ++m) _Pragma("unroll") for (int n = 0; n < 2; ++n) _Pragma("unroll") for (int k = 0; k < 2; ++k) \
;         acc[ai][bj][m][n] = __builtin_amdgcn_mfma_f32_16x16x32_bf16(Bt[n][k], At[m][k], acc[ai][bj][m][n], 0, 0, 0); __builtin_amdgcn_s_setprio(0); } while (0)
; #define PG8_WAIT_V(n) asm volatile("s_waitcnt vmcnt(" #n ")" ::: "memory")
; #define PG8_WAIT_L(n) asm volatile("s_waitcnt lgkmcnt(" #n ")" ::: "memory")
; #define PG8_BAR __builtin_amdgcn_s_barrier()
; #define PG8_SCHED __builtin_amdgcn_sched_barrier(0)
; template <class Epi>
; __device__ __forceinline__ void gemm_phase(LAS unsigned char* lds, const Gemm g, const StaticOrder& S, const Epi& E) {
;     ...
;             PG8_WAIT_V(6); PG8_BAR; PG8_MMA(1, 1, At, B1); PG8_BAR;
;             PG8_LDB(B0, 1, 0); PG8_SCHED; PG8_LDA(At, 1, 0); PG8_STAGE(PG8_SA(0, 1), a2 + hstep, voffA);
;             PG8_WAIT_L(8); PG8_BAR; PG8_WAIT_L(0); PG8_MMA(0, 0, At, B0); PG8_BAR; PG8_SCHED;
;             PG8_LDB(B1, 1, 1); PG8_STAGE(PG8_SB(1, 0), b3, voffB);
;             PG8_BAR; PG8_WAIT_L(0); PG8_MMA(0, 1, At, B1); PG8_BAR;
;             PG8_LDA(At, 1, 1); PG8_STAGE(PG8_SA(1, 0), a3, voffA);
	v_mfma_f32_16x16x32_bf16 v[52:55], v[208:211], v[176:179], v[52:55]
	v_mfma_f32_16x16x32_bf16 v[48:51], v[216:219], v[176:179], v[48:51]
	v_mfma_f32_16x16x32_bf16 v[36:39], v[208:211], v[184:187], v[36:39]
	v_mfma_f32_16x16x32_bf16 v[32:35], v[216:219], v[184:187], v[32:35]
	v_mfma_f32_16x16x32_bf16 v[20:23], v[208:211], v[192:195], v[20:23]
	v_mfma_f32_16x16x32_bf16 v[16:19], v[216:219], v[192:195], v[16:19]
	v_mfma_f32_16x16x32_bf16 v[4:7], v[208:211], v[200:203], v[4:7]
	v_mfma_f32_16x16x32_bf16 v[0:3], v[216:219], v[200:203], v[0:3]
	v_mfma_f32_16x16x32_bf16 v[52:55], v[212:215], v[180:183], v[52:55]
	v_mfma_f32_16x16x32_bf16 v[48:51], v[220:223], v[180:183], v[48:51]
	v_mfma_f32_16x16x32_bf16 v[36:39], v[212:215], v[188:191], v[36:39]
	v_mfma_f32_16x16x32_bf16 v[32:35], v[220:223], v[188:191], v[32:35]
	v_mfma_f32_16x16x32_bf16 v[20:23], v[212:215], v[196:199], v[20:23]
	v_mfma_f32_16x16x32_bf16 v[16:19], v[220:223], v[196:199], v[16:19]
	v_mfma_f32_16x16x32_bf16 v[4:7], v[212:215], v[204:207], v[4:7]
	v_mfma_f32_16x16x32_bf16 v[0:3], v[220:223], v[204:207], v[0:3]
	s_add_i32 s58, 0, 0x18000
	v_add_u32_e32 v136, s58, v161
	s_barrier
	ds_read_b128 v[150:153], v136
	ds_read_b128 v[154:157], v136 offset:1024
	ds_read_b128 v[168:171], v136 offset:2048
	ds_read_b128 v[172:175], v136 offset:3072
	s_add_u32 s50, s50, 0x80000
	s_addc_u32 s51, s51, 0
	s_mov_b32 m0, s31
	ds_read_b128 v[176:179], v165 offset:32768
	ds_read_b128 v[180:183], v165 offset:33792
	ds_read_b128 v[184:187], v165 offset:34816
	ds_read_b128 v[188:191], v165 offset:35840
	ds_read_b128 v[192:195], v165 offset:36864
	ds_read_b128 v[196:199], v165 offset:37888
	ds_read_b128 v[200:203], v165 offset:38912
	ds_read_b128 v[204:207], v165 offset:39936
	global_load_lds_dwordx4 v134, s[50:51]
	s_mov_b32 m0, s33
	s_nop 0
	global_load_lds_dwordx4 v130, s[50:51]
	s_waitcnt lgkmcnt(8)
	s_barrier
	s_waitcnt lgkmcnt(0)
	s_waitcnt lgkmcnt(0)
	v_mfma_f32_16x16x32_bf16 v[124:127], v[150:153], v[176:179], v[124:127]
	v_mfma_f32_16x16x32_bf16 v[120:123], v[168:171], v[176:179], v[120:123]
	v_mfma_f32_16x16x32_bf16 v[108:111], v[150:153], v[184:187], v[108:111]
	v_mfma_f32_16x16x32_bf16 v[104:107], v[168:171], v[184:187], v[104:107]
	v_mfma_f32_16x16x32_bf16 v[92:95], v[150:153], v[192:195], v[92:95]
	v_mfma_f32_16x16x32_bf16 v[88:91], v[168:171], v[192:195], v[88:91]
	v_mfma_f32_16x16x32_bf16 v[76:79], v[150:153], v[200:203], v[76:79]
	v_mfma_f32_16x16x32_bf16 v[72:75], v[168:171], v[200:203], v[72:75]
	v_mfma_f32_16x16x32_bf16 v[124:127], v[154:157], v[180:183], v[124:127]
	v_mfma_f32_16x16x32_bf16 v[120:123], v[172:175], v[180:183], v[120:123]
	v_mfma_f32_16x16x32_bf16 v[108:111], v[154:157], v[188:191], v[108:111]
	v_mfma_f32_16x16x32_bf16 v[104:107], v[172:175], v[188:191], v[104:107]
	v_mfma_f32_16x16x32_bf16 v[92:95], v[154:157], v[196:199], v[92:95]
	v_mfma_f32_16x16x32_bf16 v[88:91], v[172:175], v[196:199], v[88:91]
	v_mfma_f32_16x16x32_bf16 v[76:79], v[154:157], v[204:207], v[76:79]
	v_mfma_f32_16x16x32_bf16 v[72:75], v[172:175], v[204:207], v[72:75]
	s_barrier
	s_add_i32 s50, 0, 0x1c000
	s_add_i32 s51, s58, s23
	v_add_u32_e32 v136, s50, v161
	s_mov_b32 m0, s51
	ds_read_b128 v[208:211], v136
	ds_read_b128 v[212:215], v136 offset:1024
	ds_read_b128 v[216:219], v136 offset:2048
	ds_read_b128 v[220:223], v136 offset:3072
	global_load_lds_dwordx4 v132, s[98:99]
	s_add_i32 m0, s51, 0x2000
	s_nop 0
	global_load_lds_dwordx4 v128, s[98:99]
	s_barrier
	s_waitcnt lgkmcnt(0)
	s_waitcnt lgkmcnt(0)
	v_mfma_f32_16x16x32_bf16 v[116:119], v[208:211], v[176:179], v[116:119]
	v_mfma_f32_16x16x32_bf16 v[112:115], v[216:219], v[176:179], v[112:115]
	v_mfma_f32_16x16x32_bf16 v[100:103], v[208:211], v[184:187], v[100:103]
	v_mfma_f32_16x16x32_bf16 v[96:99], v[216:219], v[184:187], v[96:99]
	v_mfma_f32_16x16x32_bf16 v[84:87], v[208:211], v[192:195], v[84:87]
	v_mfma_f32_16x16x32_bf16 v[80:83], v[216:219], v[192:195], v[80:83]
	v_mfma_f32_16x16x32_bf16 v[68:71], v[208:211], v[200:203], v[68:71]
	v_mfma_f32_16x16x32_bf16 v[64:67], v[216:219], v[200:203], v[64:67]
	v_mfma_f32_16x16x32_bf16 v[116:119], v[212:215], v[180:183], v[116:119]
	v_mfma_f32_16x16x32_bf16 v[112:115], v[220:223], v[180:183], v[112:115]
	v_mfma_f32_16x16x32_bf16 v[100:103], v[212:215], v[188:191], v[100:103]
	v_mfma_f32_16x16x32_bf16 v[96:99], v[220:223], v[188:191], v[96:99]
	v_mfma_f32_16x16x32_bf16 v[84:87], v[212:215], v[196:199], v[84:87]
	v_mfma_f32_16x16x32_bf16 v[80:83], v[220:223], v[196:199], v[80:83]
	v_mfma_f32_16x16x32_bf16 v[68:71], v[212:215], v[204:207], v[68:71]
	v_mfma_f32_16x16x32_bf16 v[64:67], v[220:223], v[204:207], v[64:67]
	s_mov_b32 m0, s37
	s_barrier
	ds_read_b128 v[176:179], v165 offset:49152
	ds_read_b128 v[180:183], v165 offset:50176
	ds_read_b128 v[184:187], v165 offset:51200
	ds_read_b128 v[188:191], v165 offset:52224
	ds_read_b128 v[192:195], v165 offset:53248
	ds_read_b128 v[196:199], v165 offset:54272
	ds_read_b128 v[200:203], v165 offset:55296
	ds_read_b128 v[204:207], v165 offset:56320
	global_load_lds_dwordx4 v134, s[100:101]
	s_mov_b32 m0, s38
	s_nop 0
	global_load_lds_dwordx4 v130, s[100:101]
	s_barrier
; #define PG8_STAGE(bufoff, gbase, voff) do { _Pragma("unroll") for (int _i = 0; _i < 2; ++_i) \
;         __builtin_amdgcn_global_load_lds((const unsigned*)((const char*)(gbase) + (voff)[_i]), (LAS unsigned*)(lds + (bufoff) + ldsw + _i * 8192), 16, 0, 0); } while (0)
; #define PG8_MMA(ai, bj, At, Bt) do { __builtin_amdgcn_s_setprio(1); _Pragma("unroll") for (int m = 0; m < 4; ++m) _Pragma("unroll") for (int n = 0; n < 2; ++n) _Pragma("unroll") for (int k = 0; k < 2; ++k) \
;         acc[ai][bj][m][n] = __builtin_amdgcn_mfma_f32_16x16x32_bf16(Bt[n][k], At[m][k], acc[ai][bj][m][n], 0, 0, 0); __builtin_amdgcn_s_setprio(0); } while (0)
; #define PG8_WAIT_V(n) asm volatile("s_waitcnt vmcnt(" #n ")" ::: "memory")
; #define PG8_WAIT_L(n) asm volatile("s_waitcnt lgkmcnt(" #n ")" ::: "memory")
; #define PG8_BAR __builtin_amdgcn_s_barrier()
; #define PG8_SCHED __builtin_amdgcn_sched_barrier(0)
; __device__ __forceinline__ u32x4 pack8(f32x4 v0, f32x4 v1) { u32x4 w; w.x = cvt_pk_bf16(v0[0], v0[1]); w.y = cvt_pk_bf16(v0[2], v0[3]); w.z = cvt_pk_bf16(v1[0], v1[1]); w.w = cvt_pk_bf16(v1[2], v1[3]); return w; }
; template <class Epi>
; __device__ __forceinline__ void gemm_phase(LAS unsigned char* lds, const Gemm g, const StaticOrder& S, const Epi& E) {
;     ...
;             PG8_BAR; PG8_WAIT_L(0); PG8_MMA(1, 0, At, B0); PG8_BAR; PG8_SCHED;
;             PG8_STAGE(PG8_SB(1, 1), b3 + hstep, voffB);
;             PG8_WAIT_V(6); PG8_BAR; PG8_MMA(1, 1, At, B1); PG8_BAR;
;     __device__ __forceinline__ void operator()(const f32x4 (&acc)[2][2][4][2], const Unit& u, int wr, int wc, int fr, int fq) const {
;     ...
;         } else {
;             const int col0 = u.pn * BM + wc * 32 + 8 * fq; const float sc = (u.pn < 2) ? QSCALE : 1.0f;
; #pragma unroll
;             for (int ai = 0; ai < 2; ++ai)
; #pragma unroll
;                 for (int m = 0; m < 4; ++m) { bf16_t* rowp = O + (size_t)(row0 + ai * HALF + m * 16) * NQKV + col0; const float scr_ = sc * rowsc[row0 + ai * HALF + m * 16];
; #pragma unroll
;                     for (int bj = 0; bj < 2; ++bj) *(u32x4*)(rowp + bj * HALF) = pack8(acc[ai][bj][m][0] * scr_, acc[ai][bj][m][1] * scr_); }
	s_waitcnt lgkmcnt(0)
	s_waitcnt lgkmcnt(0)
	v_mfma_f32_16x16x32_bf16 v[60:63], v[150:153], v[176:179], v[60:63]
	v_mfma_f32_16x16x32_bf16 v[56:59], v[168:171], v[176:179], v[56:59]
	v_mfma_f32_16x16x32_bf16 v[44:47], v[150:153], v[184:187], v[44:47]
	v_mfma_f32_16x16x32_bf16 v[40:43], v[168:171], v[184:187], v[40:43]
	v_mfma_f32_16x16x32_bf16 v[28:31], v[150:153], v[192:195], v[28:31]
	v_mfma_f32_16x16x32_bf16 v[24:27], v[168:171], v[192:195], v[24:27]
	v_mfma_f32_16x16x32_bf16 v[12:15], v[150:153], v[200:203], v[12:15]
	v_mfma_f32_16x16x32_bf16 v[8:11], v[168:171], v[200:203], v[8:11]
	v_mfma_f32_16x16x32_bf16 v[60:63], v[154:157], v[180:183], v[60:63]
	v_mfma_f32_16x16x32_bf16 v[56:59], v[172:175], v[180:183], v[56:59]
	v_mfma_f32_16x16x32_bf16 v[44:47], v[154:157], v[188:191], v[44:47]
	v_mfma_f32_16x16x32_bf16 v[40:43], v[172:175], v[188:191], v[40:43]
	v_mfma_f32_16x16x32_bf16 v[28:31], v[154:157], v[196:199], v[28:31]
	v_mfma_f32_16x16x32_bf16 v[24:27], v[172:175], v[196:199], v[24:27]
	v_mfma_f32_16x16x32_bf16 v[12:15], v[154:157], v[204:207], v[12:15]
	v_mfma_f32_16x16x32_bf16 v[8:11], v[172:175], v[204:207], v[8:11]
	s_barrier
	s_add_u32 s48, s48, 0x80080
	s_addc_u32 s49, s49, 0
	s_add_i32 s50, s50, s23
	s_mov_b32 m0, s50
	s_nop 0
	global_load_lds_dwordx4 v132, s[48:49]
	s_add_i32 m0, s50, 0x2000
	s_nop 0
	global_load_lds_dwordx4 v128, s[48:49]
	s_waitcnt vmcnt(6)
	s_barrier
	v_mfma_f32_16x16x32_bf16 v[52:55], v[208:211], v[176:179], v[52:55]
	v_mfma_f32_16x16x32_bf16 v[48:51], v[216:219], v[176:179], v[48:51]
	v_mfma_f32_16x16x32_bf16 v[36:39], v[208:211], v[184:187], v[36:39]
	v_mfma_f32_16x16x32_bf16 v[32:35], v[216:219], v[184:187], v[32:35]
	v_mfma_f32_16x16x32_bf16 v[20:23], v[208:211], v[192:195], v[20:23]
	v_mfma_f32_16x16x32_bf16 v[16:19], v[216:219], v[192:195], v[16:19]
	v_mfma_f32_16x16x32_bf16 v[4:7], v[208:211], v[200:203], v[4:7]
	v_mfma_f32_16x16x32_bf16 v[0:3], v[216:219], v[200:203], v[0:3]
	v_mfma_f32_16x16x32_bf16 v[52:55], v[212:215], v[180:183], v[52:55]
	v_mfma_f32_16x16x32_bf16 v[48:51], v[220:223], v[180:183], v[48:51]
	v_mfma_f32_16x16x32_bf16 v[36:39], v[212:215], v[188:191], v[36:39]
	v_mfma_f32_16x16x32_bf16 v[32:35], v[220:223], v[188:191], v[32:35]
	v_mfma_f32_16x16x32_bf16 v[20:23], v[212:215], v[196:199], v[20:23]
	v_mfma_f32_16x16x32_bf16 v[16:19], v[220:223], v[196:199], v[16:19]
	v_mfma_f32_16x16x32_bf16 v[4:7], v[212:215], v[204:207], v[4:7]
	v_mfma_f32_16x16x32_bf16 v[0:3], v[220:223], v[204:207], v[0:3]
	s_add_i32 s57, s57, 2
	s_add_u32 s46, s46, 0x100
	s_addc_u32 s47, s47, 0
	s_add_u32 s55, s55, 0x100
	s_addc_u32 s56, s56, 0
	s_cmp_gt_u32 s57, 29
	s_barrier
	s_cbranch_scc0 .LBB0_407
	v_lshl_add_u32 v154, s44, 8, v160
	s_add_i32 s9, s34, -6
	s_lshl_b32 s7, s34, 8
	s_cmp_gt_u32 s9, 11
	s_mov_b64 s[44:45], -1
	v_ashrrev_i32_e32 v155, 31, v154
	v_or_b32_e32 v174, 16, v154
	v_or_b32_e32 v173, 32, v154
	v_or_b32_e32 v172, 48, v154
	v_add_u32_e32 v171, 0x80, v154
	v_add_u32_e32 v170, 0x90, v154
	v_add_u32_e32 v169, 0xa0, v154
	v_add_u32_e32 v168, 0xb0, v154
	s_cbranch_scc0 .LBB0_410
	v_lshl_add_u64 v[150:151], v[154:155], 2, s[14:15]
	global_load_dword v136, v[150:151], off
	global_load_dword v204, v[150:151], off offset:64
	global_load_dword v205, v[150:151], off offset:128
	global_load_dword v206, v[150:151], off offset:192
	global_load_dword v207, v[150:151], off offset:512
	global_load_dword v208, v[150:151], off offset:576
	global_load_dword v209, v[150:151], off offset:640
	global_load_dword v210, v[150:151], off offset:704
	s_cmp_lt_i32 s34, 2
	v_or_b32_e32 v156, s7, v162
	s_cselect_b64 vcc, -1, 0
	v_mov_b64_e32 v[152:153], s[20:21]
	v_cndmask_b32_e32 v175, 1.0, v167, vcc
	v_ashrrev_i32_e32 v157, 31, v156
	v_mad_i64_i32 v[176:177], s[44:45], v154, s53, v[152:153]
	v_lshlrev_b64 v[156:157], 1, v[156:157]
	v_lshl_add_u64 v[180:181], v[176:177], 0, v[156:157]
	s_waitcnt vmcnt(0)
	v_mul_f32_e32 v136, v175, v136
	v_pk_mul_f32 v[178:179], v[126:127], v[136:137] op_sel_hi:[1,0]
	v_pk_mul_f32 v[176:177], v[124:125], v[136:137] op_sel_hi:[1,0]
	v_pk_mul_f32 v[182:183], v[122:123], v[136:137] op_sel_hi:[1,0]
	v_pk_mul_f32 v[184:185], v[120:121], v[136:137] op_sel_hi:[1,0]
	v_cvt_pk_bf16_f32 v176, v176, v177
	v_cvt_pk_bf16_f32 v177, v178, v179
	v_pk_mul_f32 v[186:187], v[118:119], v[136:137] op_sel_hi:[1,0]
	v_cvt_pk_bf16_f32 v178, v184, v185
	v_cvt_pk_bf16_f32 v179, v182, v183
	v_pk_mul_f32 v[188:189], v[116:117], v[136:137] op_sel_hi:[1,0]
	v_pk_mul_f32 v[190:191], v[114:115], v[136:137] op_sel_hi:[1,0]
	v_pk_mul_f32 v[192:193], v[112:113], v[136:137] op_sel_hi:[1,0]
	global_store_dwordx4 v[180:181], v[176:179], off
	s_nop 1
	v_cvt_pk_bf16_f32 v176, v188, v189
	v_cvt_pk_bf16_f32 v177, v186, v187
	v_cvt_pk_bf16_f32 v178, v192, v193
	v_cvt_pk_bf16_f32 v179, v190, v191
	global_store_dwordx4 v[180:181], v[176:179], off offset:256
	s_nop 1
	v_mov_b32_e32 v136, v204
	v_mul_f32_e32 v136, v175, v136
	v_mad_i64_i32 v[176:177], s[44:45], v174, s53, v[152:153]
	v_lshl_add_u64 v[180:181], v[176:177], 0, v[156:157]
	v_pk_mul_f32 v[178:179], v[110:111], v[136:137] op_sel_hi:[1,0]
	v_pk_mul_f32 v[176:177], v[108:109], v[136:137] op_sel_hi:[1,0]
	v_pk_mul_f32 v[182:183], v[106:107], v[136:137] op_sel_hi:[1,0]
	v_pk_mul_f32 v[184:185], v[104:105], v[136:137] op_sel_hi:[1,0]
	v_cvt_pk_bf16_f32 v176, v176, v177
	v_cvt_pk_bf16_f32 v177, v178, v179
	v_pk_mul_f32 v[186:187], v[102:103], v[136:137] op_sel_hi:[1,0]
	v_cvt_pk_bf16_f32 v178, v184, v185
	v_cvt_pk_bf16_f32 v179, v182, v183
	v_pk_mul_f32 v[188:189], v[100:101], v[136:137] op_sel_hi:[1,0]
	v_pk_mul_f32 v[190:191], v[98:99], v[136:137] op_sel_hi:[1,0]
; __device__ __forceinline__ u32x4 pack8(f32x4 v0, f32x4 v1) { u32x4 w; w.x = cvt_pk_bf16(v0[0], v0[1]); w.y = cvt_pk_bf16(v0[2], v0[3]); w.z = cvt_pk_bf16(v1[0], v1[1]); w.w = cvt_pk_bf16(v1[2], v1[3]); return w; }
;     __device__ __forceinline__ void operator()(const f32x4 (&acc)[2][2][4][2], const Unit& u, int wr, int wc, int fr, int fq) const {
;     ...
;         } else {
;             const int col0 = u.pn * BM + wc * 32 + 8 * fq; const float sc = (u.pn < 2) ? QSCALE : 1.0f;
; #pragma unroll
;             for (int ai = 0; ai < 2; ++ai)
; #pragma unroll
;                 for (int m = 0; m < 4; ++m) { bf16_t* rowp = O + (size_t)(row0 + ai * HALF + m * 16) * NQKV + col0; const float scr_ = sc * rowsc[row0 + ai * HALF + m * 16];
; #pragma unroll
;                     for (int bj = 0; bj < 2; ++bj) *(u32x4*)(rowp + bj * HALF) = pack8(acc[ai][bj][m][0] * scr_, acc[ai][bj][m][1] * scr_); }
	v_pk_mul_f32 v[192:193], v[96:97], v[136:137] op_sel_hi:[1,0]
	global_store_dwordx4 v[180:181], v[176:179], off
	s_nop 1
	v_cvt_pk_bf16_f32 v176, v188, v189
	v_cvt_pk_bf16_f32 v177, v186, v187
	v_cvt_pk_bf16_f32 v178, v192, v193
	v_cvt_pk_bf16_f32 v179, v190, v191
	global_store_dwordx4 v[180:181], v[176:179], off offset:256
	s_nop 1
	v_mov_b32_e32 v136, v205
	v_mul_f32_e32 v136, v175, v136
	v_mad_i64_i32 v[176:177], s[44:45], v173, s53, v[152:153]
	v_lshl_add_u64 v[180:181], v[176:177], 0, v[156:157]
	v_pk_mul_f32 v[178:179], v[94:95], v[136:137] op_sel_hi:[1,0]
	v_pk_mul_f32 v[176:177], v[92:93], v[136:137] op_sel_hi:[1,0]
	v_pk_mul_f32 v[182:183], v[90:91], v[136:137] op_sel_hi:[1,0]
	v_pk_mul_f32 v[184:185], v[88:89], v[136:137] op_sel_hi:[1,0]
	v_cvt_pk_bf16_f32 v176, v176, v177
	v_cvt_pk_bf16_f32 v177, v178, v179
	v_pk_mul_f32 v[186:187], v[86:87], v[136:137] op_sel_hi:[1,0]
	v_cvt_pk_bf16_f32 v178, v184, v185
	v_cvt_pk_bf16_f32 v179, v182, v183
	v_pk_mul_f32 v[188:189], v[84:85], v[136:137] op_sel_hi:[1,0]
	v_pk_mul_f32 v[190:191], v[82:83], v[136:137] op_sel_hi:[1,0]
	v_pk_mul_f32 v[192:193], v[80:81], v[136:137] op_sel_hi:[1,0]
	global_store_dwordx4 v[180:181], v[176:179], off
	s_nop 1
	v_cvt_pk_bf16_f32 v176, v188, v189
	v_cvt_pk_bf16_f32 v177, v186, v187
	v_cvt_pk_bf16_f32 v178, v192, v193
	v_cvt_pk_bf16_f32 v179, v190, v191
	global_store_dwordx4 v[180:181], v[176:179], off offset:256
	s_nop 1
	v_mov_b32_e32 v136, v206
	v_mul_f32_e32 v136, v175, v136
	v_mad_i64_i32 v[176:177], s[44:45], v172, s53, v[152:153]
	v_lshl_add_u64 v[180:181], v[176:177], 0, v[156:157]
	v_pk_mul_f32 v[178:179], v[78:79], v[136:137] op_sel_hi:[1,0]
	v_pk_mul_f32 v[176:177], v[76:77], v[136:137] op_sel_hi:[1,0]
	v_pk_mul_f32 v[182:183], v[74:75], v[136:137] op_sel_hi:[1,0]
	v_pk_mul_f32 v[184:185], v[72:73], v[136:137] op_sel_hi:[1,0]
	v_cvt_pk_bf16_f32 v176, v176, v177
	v_cvt_pk_bf16_f32 v177, v178, v179
	v_pk_mul_f32 v[186:187], v[70:71], v[136:137] op_sel_hi:[1,0]
	v_cvt_pk_bf16_f32 v178, v184, v185
	v_cvt_pk_bf16_f32 v179, v182, v183
	v_pk_mul_f32 v[188:189], v[68:69], v[136:137] op_sel_hi:[1,0]
	v_pk_mul_f32 v[190:191], v[66:67], v[136:137] op_sel_hi:[1,0]
	v_pk_mul_f32 v[192:193], v[64:65], v[136:137] op_sel_hi:[1,0]
	global_store_dwordx4 v[180:181], v[176:179], off
	s_nop 1
	v_cvt_pk_bf16_f32 v176, v188, v189
	v_cvt_pk_bf16_f32 v177, v186, v187
	v_cvt_pk_bf16_f32 v178, v192, v193
	v_cvt_pk_bf16_f32 v179, v190, v191
	global_store_dwordx4 v[180:181], v[176:179], off offset:256
	s_nop 1
	v_mov_b32_e32 v136, v207
	v_mul_f32_e32 v136, v175, v136
	v_mad_i64_i32 v[176:177], s[44:45], v171, s53, v[152:153]
	v_lshl_add_u64 v[180:181], v[176:177], 0, v[156:157]
	v_pk_mul_f32 v[178:179], v[62:63], v[136:137] op_sel_hi:[1,0]
	v_pk_mul_f32 v[176:177], v[60:61], v[136:137] op_sel_hi:[1,0]
	v_pk_mul_f32 v[182:183], v[58:59], v[136:137] op_sel_hi:[1,0]
	v_pk_mul_f32 v[184:185], v[56:57], v[136:137] op_sel_hi:[1,0]
	v_cvt_pk_bf16_f32 v176, v176, v177
	v_cvt_pk_bf16_f32 v177, v178, v179
	v_pk_mul_f32 v[186:187], v[54:55], v[136:137] op_sel_hi:[1,0]
	v_cvt_pk_bf16_f32 v178, v184, v185
	v_cvt_pk_bf16_f32 v179, v182, v183
	v_pk_mul_f32 v[188:189], v[52:53], v[136:137] op_sel_hi:[1,0]
	v_pk_mul_f32 v[190:191], v[50:51], v[136:137] op_sel_hi:[1,0]
	v_pk_mul_f32 v[192:193], v[48:49], v[136:137] op_sel_hi:[1,0]
	global_store_dwordx4 v[180:181], v[176:179], off
	s_nop 1
	v_cvt_pk_bf16_f32 v176, v188, v189
	v_cvt_pk_bf16_f32 v177, v186, v187
	v_cvt_pk_bf16_f32 v178, v192, v193
	v_cvt_pk_bf16_f32 v179, v190, v191
	global_store_dwordx4 v[180:181], v[176:179], off offset:256
	s_nop 1
	v_mov_b32_e32 v136, v208
	v_mul_f32_e32 v136, v175, v136
	v_mad_i64_i32 v[176:177], s[44:45], v170, s53, v[152:153]
	v_lshl_add_u64 v[180:181], v[176:177], 0, v[156:157]
	v_pk_mul_f32 v[178:179], v[46:47], v[136:137] op_sel_hi:[1,0]
	v_pk_mul_f32 v[176:177], v[44:45], v[136:137] op_sel_hi:[1,0]
	v_pk_mul_f32 v[182:183], v[42:43], v[136:137] op_sel_hi:[1,0]
	v_pk_mul_f32 v[184:185], v[40:41], v[136:137] op_sel_hi:[1,0]
	v_cvt_pk_bf16_f32 v176, v176, v177
	v_cvt_pk_bf16_f32 v177, v178, v179
	v_pk_mul_f32 v[186:187], v[38:39], v[136:137] op_sel_hi:[1,0]
	v_cvt_pk_bf16_f32 v178, v184, v185
	v_cvt_pk_bf16_f32 v179, v182, v183
	v_pk_mul_f32 v[188:189], v[36:37], v[136:137] op_sel_hi:[1,0]
	v_pk_mul_f32 v[190:191], v[34:35], v[136:137] op_sel_hi:[1,0]
	v_pk_mul_f32 v[192:193], v[32:33], v[136:137] op_sel_hi:[1,0]
	global_store_dwordx4 v[180:181], v[176:179], off
	s_nop 1
	v_cvt_pk_bf16_f32 v176, v188, v189
	v_cvt_pk_bf16_f32 v177, v186, v187
	v_cvt_pk_bf16_f32 v178, v192, v193
	v_cvt_pk_bf16_f32 v179, v190, v191
	global_store_dwordx4 v[180:181], v[176:179], off offset:256
	s_nop 1
	v_mov_b32_e32 v136, v209
	v_mul_f32_e32 v136, v175, v136
	v_mad_i64_i32 v[176:177], s[44:45], v169, s53, v[152:153]
	v_lshl_add_u64 v[180:181], v[176:177], 0, v[156:157]
	v_pk_mul_f32 v[178:179], v[30:31], v[136:137] op_sel_hi:[1,0]
	v_pk_mul_f32 v[176:177], v[28:29], v[136:137] op_sel_hi:[1,0]
	v_pk_mul_f32 v[182:183], v[26:27], v[136:137] op_sel_hi:[1,0]
	v_pk_mul_f32 v[184:185], v[24:25], v[136:137] op_sel_hi:[1,0]
	v_cvt_pk_bf16_f32 v176, v176, v177
	v_cvt_pk_bf16_f32 v177, v178, v179
	v_pk_mul_f32 v[186:187], v[22:23], v[136:137] op_sel_hi:[1,0]
	v_cvt_pk_bf16_f32 v178, v184, v185
	v_cvt_pk_bf16_f32 v179, v182, v183
	v_pk_mul_f32 v[188:189], v[20:21], v[136:137] op_sel_hi:[1,0]
	v_pk_mul_f32 v[190:191], v[18:19], v[136:137] op_sel_hi:[1,0]
	v_pk_mul_f32 v[192:193], v[16:17], v[136:137] op_sel_hi:[1,0]
	global_store_dwordx4 v[180:181], v[176:179], off
	s_nop 1
	v_cvt_pk_bf16_f32 v176, v188, v189
	v_cvt_pk_bf16_f32 v177, v186, v187
	v_cvt_pk_bf16_f32 v178, v192, v193
	v_cvt_pk_bf16_f32 v179, v190, v191
	global_store_dwordx4 v[180:181], v[176:179], off offset:256
	s_nop 1
	v_mov_b32_e32 v136, v210
	v_mad_i64_i32 v[150:151], s[44:45], v168, s53, v[152:153]
	v_lshl_add_u64 v[156:157], v[150:151], 0, v[156:157]
	s_mov_b64 s[44:45], 0
	v_mul_f32_e32 v136, v175, v136
	v_pk_mul_f32 v[152:153], v[14:15], v[136:137] op_sel_hi:[1,0]
	v_pk_mul_f32 v[150:151], v[12:13], v[136:137] op_sel_hi:[1,0]
	v_pk_mul_f32 v[176:177], v[10:11], v[136:137] op_sel_hi:[1,0]
	v_pk_mul_f32 v[178:179], v[8:9], v[136:137] op_sel_hi:[1,0]
	v_cvt_pk_bf16_f32 v150, v150, v151
	v_cvt_pk_bf16_f32 v151, v152, v153
	v_pk_mul_f32 v[180:181], v[6:7], v[136:137] op_sel_hi:[1,0]
	v_cvt_pk_bf16_f32 v152, v178, v179
	v_cvt_pk_bf16_f32 v153, v176, v177
	v_pk_mul_f32 v[182:183], v[4:5], v[136:137] op_sel_hi:[1,0]
	v_pk_mul_f32 v[184:185], v[2:3], v[136:137] op_sel_hi:[1,0]
	v_pk_mul_f32 v[186:187], v[0:1], v[136:137] op_sel_hi:[1,0]
	global_store_dwordx4 v[156:157], v[150:153], off
	s_nop 1
	v_cvt_pk_bf16_f32 v150, v182, v183
	v_cvt_pk_bf16_f32 v151, v180, v181
	v_cvt_pk_bf16_f32 v152, v186, v187
	v_cvt_pk_bf16_f32 v153, v184, v185
	global_store_dwordx4 v[156:157], v[150:153], off offset:256

; #define PG8_STAGE(bufoff, gbase, voff) do { _Pragma("unroll") for (int _i = 0; _i < 2; ++_i) \
;         __builtin_amdgcn_global_load_lds((const unsigned*)((const char*)(gbase) + (voff)[_i]), (LAS unsigned*)(lds + (bufoff) + ldsw + _i * 8192), 16, 0, 0); } while (0)
; #define PG8_LDA(dst, b, h) do { _Pragma("unroll") for (int m = 0; m < 4; ++m) _Pragma("unroll") for (int k = 0; k < 2; ++k) dst[m][k] = *(const LAS bf16x8*)(lds + PG8_SA(b, h) + aoff + m * 2048 + k * 1024); } while (0)
; #define PG8_LDB(dst, b, h) do { _Pragma("unroll") for (int n = 0; n < 2; ++n) _Pragma("unroll") for (int k = 0; k < 2; ++k) dst[n][k] = *(const LAS bf16x8*)(lds + PG8_SB(b, h) + boff + n * 2048 + k * 1024); } while (0)
; #define PG8_MMA(ai, bj, At, Bt) do { __builtin_amdgcn_s_setprio(1); _Pragma("unroll") for (int m = 0; m < 4; ++m) _Pragma("unroll") for (int n = 0; n < 2; ++n) _Pragma("unroll") for (int k = 0; k < 2; ++k) \
;         acc[ai][bj][m][n] = __builtin_amdgcn_mfma_f32_16x16x32_bf16(Bt[n][k], At[m][k], acc[ai][bj][m][n], 0, 0, 0); __builtin_amdgcn_s_setprio(0); } while (0)
; #define PG8_WAIT_V(n) asm volatile("s_waitcnt vmcnt(" #n ")" ::: "memory")
; #define PG8_WAIT_L(n) asm volatile("s_waitcnt lgkmcnt(" #n ")" ::: "memory")
; template <class Epi>
; __device__ __forceinline__ void gemm_phase(LAS unsigned char* lds, const Gemm g, const StaticOrder& S, const Epi& E) {
;     ...
;         for (int t = 0; t < nt; t += 2) {
;             const bool last = (t == nt - 2);
;             const char* a1 = cA + (size_t)(t + 1) * kstep;
;             const char* a2 = last ? nA : cA + (size_t)(t + 2) * kstep; const char* b2 = last ? nB : cB + (size_t)(t + 2) * kstep;
;             const char* a3 = a2 + kstep; const char* b3 = b2 + kstep;
;             PG8_LDB(B0, 0, 0); PG8_SCHED; PG8_LDA(At, 0, 0); PG8_STAGE(PG8_SA(1, 1), a1 + hstep, voffA);
;             PG8_WAIT_L(8); PG8_BAR; PG8_WAIT_L(0); PG8_MMA(0, 0, At, B0); PG8_BAR; PG8_SCHED;
;             PG8_LDB(B1, 0, 1); PG8_STAGE(PG8_SB(0, 0), b2, voffB);
;             PG8_BAR; PG8_WAIT_L(0); PG8_MMA(0, 1, At, B1); PG8_BAR;
;             PG8_LDA(At, 0, 1); PG8_STAGE(PG8_SA(0, 0), a2, voffA);
;             PG8_BAR; PG8_WAIT_L(0); PG8_MMA(1, 0, At, B0); PG8_BAR; PG8_SCHED;
;             PG8_STAGE(PG8_SB(0, 1), b2 + hstep, voffB);
;             PG8_WAIT_V(6); PG8_BAR; PG8_MMA(1, 1, At, B1); PG8_BAR;
.LBB0_673:
	ds_read_b128 v[148:151], v145
	ds_read_b128 v[152:155], v145 offset:1024
	ds_read_b128 v[160:163], v145 offset:2048
	ds_read_b128 v[164:167], v145 offset:3072
	s_add_u32 s52, s50, 0xfff80080
	s_addc_u32 s53, s51, -1
	s_cmp_eq_u32 s69, 28
	s_cselect_b32 s55, s43, s53
	s_cselect_b32 s54, s65, s52
	s_cselect_b32 s53, s41, s68
	s_cselect_b32 s52, s66, s67
	s_add_i32 m0, s28, 0xc000
	ds_read_b128 v[168:171], v146
	ds_read_b128 v[172:175], v146 offset:1024
	ds_read_b128 v[176:179], v146 offset:2048
	ds_read_b128 v[180:183], v146 offset:3072
	ds_read_b128 v[184:187], v146 offset:4096
	ds_read_b128 v[188:191], v146 offset:5120
	ds_read_b128 v[192:195], v146 offset:6144
	ds_read_b128 v[196:199], v146 offset:7168
	global_load_lds_dwordx4 v136, s[50:51]
	s_add_i32 m0, s28, 0xe000
	s_nop 0
	global_load_lds_dwordx4 v138, s[50:51]
	s_waitcnt lgkmcnt(8)
	s_barrier
	s_waitcnt lgkmcnt(0)
	s_waitcnt lgkmcnt(0)
	v_mfma_f32_16x16x32_bf16 v[124:127], v[148:151], v[168:171], v[124:127]
	v_mfma_f32_16x16x32_bf16 v[120:123], v[160:163], v[168:171], v[120:123]
	v_mfma_f32_16x16x32_bf16 v[112:115], v[148:151], v[176:179], v[112:115]
	v_mfma_f32_16x16x32_bf16 v[104:107], v[160:163], v[176:179], v[104:107]
	v_mfma_f32_16x16x32_bf16 v[96:99], v[148:151], v[184:187], v[96:99]
	v_mfma_f32_16x16x32_bf16 v[88:91], v[160:163], v[184:187], v[88:91]
	v_mfma_f32_16x16x32_bf16 v[80:83], v[148:151], v[192:195], v[80:83]
	v_mfma_f32_16x16x32_bf16 v[72:75], v[160:163], v[192:195], v[72:75]
	v_mfma_f32_16x16x32_bf16 v[124:127], v[152:155], v[172:175], v[124:127]
	v_mfma_f32_16x16x32_bf16 v[120:123], v[164:167], v[172:175], v[120:123]
	v_mfma_f32_16x16x32_bf16 v[112:115], v[152:155], v[180:183], v[112:115]
	v_mfma_f32_16x16x32_bf16 v[104:107], v[164:167], v[180:183], v[104:107]
	v_mfma_f32_16x16x32_bf16 v[96:99], v[152:155], v[188:191], v[96:99]
	v_mfma_f32_16x16x32_bf16 v[88:91], v[164:167], v[188:191], v[88:91]
	v_mfma_f32_16x16x32_bf16 v[80:83], v[152:155], v[196:199], v[80:83]
	v_mfma_f32_16x16x32_bf16 v[72:75], v[164:167], v[196:199], v[72:75]
	s_barrier
	s_add_i32 s70, s58, s23
	s_add_u32 s98, s52, s6
	s_addc_u32 s99, s53, s7
	s_mov_b32 m0, s70
	ds_read_b128 v[200:203], v147
	ds_read_b128 v[204:207], v147 offset:1024
	ds_read_b128 v[208:211], v147 offset:2048
	ds_read_b128 v[212:215], v147 offset:3072
	global_load_lds_dwordx4 v132, s[52:53]
	s_add_i32 m0, s70, 0x2000
	s_nop 0
	global_load_lds_dwordx4 v128, s[52:53]
	s_barrier
	s_waitcnt lgkmcnt(0)
	s_waitcnt lgkmcnt(0)
	v_mfma_f32_16x16x32_bf16 v[116:119], v[200:203], v[168:171], v[116:119]
	v_mfma_f32_16x16x32_bf16 v[108:111], v[208:211], v[168:171], v[108:111]
	v_mfma_f32_16x16x32_bf16 v[100:103], v[200:203], v[176:179], v[100:103]
	v_mfma_f32_16x16x32_bf16 v[92:95], v[208:211], v[176:179], v[92:95]
	v_mfma_f32_16x16x32_bf16 v[84:87], v[200:203], v[184:187], v[84:87]
	v_mfma_f32_16x16x32_bf16 v[76:79], v[208:211], v[184:187], v[76:79]
	v_mfma_f32_16x16x32_bf16 v[68:71], v[200:203], v[192:195], v[68:71]
	v_mfma_f32_16x16x32_bf16 v[64:67], v[208:211], v[192:195], v[64:67]
	v_mfma_f32_16x16x32_bf16 v[116:119], v[204:207], v[172:175], v[116:119]
	v_mfma_f32_16x16x32_bf16 v[108:111], v[212:215], v[172:175], v[108:111]
	v_mfma_f32_16x16x32_bf16 v[100:103], v[204:207], v[180:183], v[100:103]
	v_mfma_f32_16x16x32_bf16 v[92:95], v[212:215], v[180:183], v[92:95]
	v_mfma_f32_16x16x32_bf16 v[84:87], v[204:207], v[188:191], v[84:87]
	v_mfma_f32_16x16x32_bf16 v[76:79], v[212:215], v[188:191], v[76:79]
	v_mfma_f32_16x16x32_bf16 v[68:71], v[204:207], v[196:199], v[68:71]
	v_mfma_f32_16x16x32_bf16 v[64:67], v[212:215], v[196:199], v[64:67]
	s_mov_b32 m0, s28
	s_add_u32 s100, s54, s6
	s_addc_u32 s101, s55, s7
	s_barrier
	ds_read_b128 v[168:171], v146 offset:16384
	ds_read_b128 v[172:175], v146 offset:17408
	ds_read_b128 v[176:179], v146 offset:18432
	ds_read_b128 v[180:183], v146 offset:19456
	ds_read_b128 v[184:187], v146 offset:20480
	ds_read_b128 v[188:191], v146 offset:21504
	ds_read_b128 v[192:195], v146 offset:22528
	ds_read_b128 v[196:199], v146 offset:23552
	global_load_lds_dwordx4 v134, s[54:55]
	s_mov_b32 m0, s29
	s_nop 0
	global_load_lds_dwordx4 v130, s[54:55]
	s_barrier
	s_waitcnt lgkmcnt(0)
	s_waitcnt lgkmcnt(0)
	v_mfma_f32_16x16x32_bf16 v[60:63], v[148:151], v[168:171], v[60:63]
	v_mfma_f32_16x16x32_bf16 v[56:59], v[160:163], v[168:171], v[56:59]
	v_mfma_f32_16x16x32_bf16 v[52:55], v[148:151], v[176:179], v[52:55]
	v_mfma_f32_16x16x32_bf16 v[44:47], v[160:163], v[176:179], v[44:47]
	v_mfma_f32_16x16x32_bf16 v[36:39], v[148:151], v[184:187], v[36:39]
	v_mfma_f32_16x16x32_bf16 v[28:31], v[160:163], v[184:187], v[28:31]
	v_mfma_f32_16x16x32_bf16 v[20:23], v[148:151], v[192:195], v[20:23]
	v_mfma_f32_16x16x32_bf16 v[12:15], v[160:163], v[192:195], v[12:15]
	v_mfma_f32_16x16x32_bf16 v[60:63], v[152:155], v[172:175], v[60:63]
	v_mfma_f32_16x16x32_bf16 v[56:59], v[164:167], v[172:175], v[56:59]
	v_mfma_f32_16x16x32_bf16 v[52:55], v[152:155], v[180:183], v[52:55]
	v_mfma_f32_16x16x32_bf16 v[44:47], v[164:167], v[180:183], v[44:47]
	v_mfma_f32_16x16x32_bf16 v[36:39], v[152:155], v[188:191], v[36:39]
	v_mfma_f32_16x16x32_bf16 v[28:31], v[164:167], v[188:191], v[28:31]
	v_mfma_f32_16x16x32_bf16 v[20:23], v[152:155], v[196:199], v[20:23]
	v_mfma_f32_16x16x32_bf16 v[12:15], v[164:167], v[196:199], v[12:15]
	s_barrier
	s_add_u32 s70, s52, 0x80000
	s_addc_u32 s71, s53, 0
	s_add_i32 s72, s59, s23
	s_mov_b32 m0, s72
	s_nop 0
	global_load_lds_dwordx4 v132, s[70:71]
	s_add_i32 m0, s72, 0x2000
	s_nop 0
	global_load_lds_dwordx4 v128, s[70:71]
	s_waitcnt vmcnt(6)
	s_barrier
; #define PG8_STAGE(bufoff, gbase, voff) do { _Pragma("unroll") for (int _i = 0; _i < 2; ++_i) \
;         __builtin_amdgcn_global_load_lds((const unsigned*)((const char*)(gbase) + (voff)[_i]), (LAS unsigned*)(lds + (bufoff) + ldsw + _i * 8192), 16, 0, 0); } while (0)
; #define PG8_LDA(dst, b, h) do { _Pragma("unroll") for (int m = 0; m < 4; ++m) _Pragma("unroll") for (int k = 0; k < 2; ++k) dst[m][k] = *(const LAS bf16x8*)(lds + PG8_SA(b, h) + aoff + m * 2048 + k * 1024); } while (0)
; #define PG8_LDB(dst, b, h) do { _Pragma("unroll") for (int n = 0; n < 2; ++n) _Pragma("unroll") for (int k = 0; k < 2; ++k) dst[n][k] = *(const LAS bf16x8*)(lds + PG8_SB(b, h) + boff + n * 2048 + k * 1024); } while (0)
; #define PG8_MMA(ai, bj, At, Bt) do { __builtin_amdgcn_s_setprio(1); _Pragma("unroll") for (int m = 0; m < 4; ++m) _Pragma("unroll") for (int n = 0; n < 2; ++n) _Pragma("unroll") for (int k = 0; k < 2; ++k) \
;         acc[ai][bj][m][n] = __builtin_amdgcn_mfma_f32_16x16x32_bf16(Bt[n][k], At[m][k], acc[ai][bj][m][n], 0, 0, 0); __builtin_amdgcn_s_setprio(0); } while (0)
; #define PG8_WAIT_V(n) asm volatile("s_waitcnt vmcnt(" #n ")" ::: "memory")
; #define PG8_WAIT_L(n) asm volatile("s_waitcnt lgkmcnt(" #n ")" ::: "memory")
; #define PG8_BAR __builtin_amdgcn_s_barrier()
; #define PG8_SCHED __builtin_amdgcn_sched_barrier(0)
; template <class Epi>
; __device__ __forceinline__ void gemm_phase(LAS unsigned char* lds, const Gemm g, const StaticOrder& S, const Epi& E) {
;     ...
;             PG8_WAIT_V(6); PG8_BAR; PG8_MMA(1, 1, At, B1); PG8_BAR;
;             PG8_LDB(B0, 1, 0); PG8_SCHED; PG8_LDA(At, 1, 0); PG8_STAGE(PG8_SA(0, 1), a2 + hstep, voffA);
;             PG8_WAIT_L(8); PG8_BAR; PG8_WAIT_L(0); PG8_MMA(0, 0, At, B0); PG8_BAR; PG8_SCHED;
;             PG8_LDB(B1, 1, 1); PG8_STAGE(PG8_SB(1, 0), b3, voffB);
;             PG8_BAR; PG8_WAIT_L(0); PG8_MMA(0, 1, At, B1); PG8_BAR;
;             PG8_LDA(At, 1, 1); PG8_STAGE(PG8_SA(1, 0), a3, voffA);
	v_mfma_f32_16x16x32_bf16 v[48:51], v[200:203], v[168:171], v[48:51]
	v_mfma_f32_16x16x32_bf16 v[40:43], v[208:211], v[168:171], v[40:43]
	v_mfma_f32_16x16x32_bf16 v[32:35], v[200:203], v[176:179], v[32:35]
	v_mfma_f32_16x16x32_bf16 v[24:27], v[208:211], v[176:179], v[24:27]
	v_mfma_f32_16x16x32_bf16 v[16:19], v[200:203], v[184:187], v[16:19]
	v_mfma_f32_16x16x32_bf16 v[8:11], v[208:211], v[184:187], v[8:11]
	v_mfma_f32_16x16x32_bf16 v[4:7], v[200:203], v[192:195], v[4:7]
	v_mfma_f32_16x16x32_bf16 v[0:3], v[208:211], v[192:195], v[0:3]
	v_mfma_f32_16x16x32_bf16 v[48:51], v[204:207], v[172:175], v[48:51]
	v_mfma_f32_16x16x32_bf16 v[40:43], v[212:215], v[172:175], v[40:43]
	v_mfma_f32_16x16x32_bf16 v[32:35], v[204:207], v[180:183], v[32:35]
	v_mfma_f32_16x16x32_bf16 v[24:27], v[212:215], v[180:183], v[24:27]
	v_mfma_f32_16x16x32_bf16 v[16:19], v[204:207], v[188:191], v[16:19]
	v_mfma_f32_16x16x32_bf16 v[8:11], v[212:215], v[188:191], v[8:11]
	v_mfma_f32_16x16x32_bf16 v[4:7], v[204:207], v[196:199], v[4:7]
	v_mfma_f32_16x16x32_bf16 v[0:3], v[212:215], v[196:199], v[0:3]
	s_add_i32 s70, 0, 0x18000
	v_add_u32_e32 v164, s70, v143
	s_barrier
	ds_read_b128 v[148:151], v164
	ds_read_b128 v[152:155], v164 offset:1024
	ds_read_b128 v[160:163], v164 offset:2048
	ds_read_b128 v[164:167], v164 offset:3072
	s_add_u32 s54, s54, 0x80000
	s_addc_u32 s55, s55, 0
	s_mov_b32 m0, s33
	ds_read_b128 v[168:171], v146 offset:32768
	ds_read_b128 v[172:175], v146 offset:33792
	ds_read_b128 v[176:179], v146 offset:34816
	ds_read_b128 v[180:183], v146 offset:35840
	ds_read_b128 v[184:187], v146 offset:36864
	ds_read_b128 v[188:191], v146 offset:37888
	ds_read_b128 v[192:195], v146 offset:38912
	ds_read_b128 v[196:199], v146 offset:39936
	global_load_lds_dwordx4 v134, s[54:55]
	s_mov_b32 m0, s36
	s_nop 0
	global_load_lds_dwordx4 v130, s[54:55]
	s_waitcnt lgkmcnt(8)
	s_barrier
	s_waitcnt lgkmcnt(0)
	s_waitcnt lgkmcnt(0)
	v_mfma_f32_16x16x32_bf16 v[124:127], v[148:151], v[168:171], v[124:127]
	v_mfma_f32_16x16x32_bf16 v[120:123], v[160:163], v[168:171], v[120:123]
	v_mfma_f32_16x16x32_bf16 v[112:115], v[148:151], v[176:179], v[112:115]
	v_mfma_f32_16x16x32_bf16 v[104:107], v[160:163], v[176:179], v[104:107]
	v_mfma_f32_16x16x32_bf16 v[96:99], v[148:151], v[184:187], v[96:99]
	v_mfma_f32_16x16x32_bf16 v[88:91], v[160:163], v[184:187], v[88:91]
	v_mfma_f32_16x16x32_bf16 v[80:83], v[148:151], v[192:195], v[80:83]
	v_mfma_f32_16x16x32_bf16 v[72:75], v[160:163], v[192:195], v[72:75]
	v_mfma_f32_16x16x32_bf16 v[124:127], v[152:155], v[172:175], v[124:127]
	v_mfma_f32_16x16x32_bf16 v[120:123], v[164:167], v[172:175], v[120:123]
	v_mfma_f32_16x16x32_bf16 v[112:115], v[152:155], v[180:183], v[112:115]
	v_mfma_f32_16x16x32_bf16 v[104:107], v[164:167], v[180:183], v[104:107]
	v_mfma_f32_16x16x32_bf16 v[96:99], v[152:155], v[188:191], v[96:99]
	v_mfma_f32_16x16x32_bf16 v[88:91], v[164:167], v[188:191], v[88:91]
	v_mfma_f32_16x16x32_bf16 v[80:83], v[152:155], v[196:199], v[80:83]
	v_mfma_f32_16x16x32_bf16 v[72:75], v[164:167], v[196:199], v[72:75]
	s_barrier
	s_add_i32 s54, 0, 0x1c000
	s_add_i32 s55, s70, s23
	v_add_u32_e32 v212, s54, v143
	s_mov_b32 m0, s55
	ds_read_b128 v[200:203], v212
	ds_read_b128 v[204:207], v212 offset:1024
	ds_read_b128 v[208:211], v212 offset:2048
	ds_read_b128 v[212:215], v212 offset:3072
	global_load_lds_dwordx4 v132, s[98:99]
	s_add_i32 m0, s55, 0x2000
	s_nop 0
	global_load_lds_dwordx4 v128, s[98:99]
	s_barrier
	s_waitcnt lgkmcnt(0)
	s_waitcnt lgkmcnt(0)
	v_mfma_f32_16x16x32_bf16 v[116:119], v[200:203], v[168:171], v[116:119]
	v_mfma_f32_16x16x32_bf16 v[108:111], v[208:211], v[168:171], v[108:111]
	v_mfma_f32_16x16x32_bf16 v[100:103], v[200:203], v[176:179], v[100:103]
	v_mfma_f32_16x16x32_bf16 v[92:95], v[208:211], v[176:179], v[92:95]
	v_mfma_f32_16x16x32_bf16 v[84:87], v[200:203], v[184:187], v[84:87]
	v_mfma_f32_16x16x32_bf16 v[76:79], v[208:211], v[184:187], v[76:79]
	v_mfma_f32_16x16x32_bf16 v[68:71], v[200:203], v[192:195], v[68:71]
	v_mfma_f32_16x16x32_bf16 v[64:67], v[208:211], v[192:195], v[64:67]
	v_mfma_f32_16x16x32_bf16 v[116:119], v[204:207], v[172:175], v[116:119]
	v_mfma_f32_16x16x32_bf16 v[108:111], v[212:215], v[172:175], v[108:111]
	v_mfma_f32_16x16x32_bf16 v[100:103], v[204:207], v[180:183], v[100:103]
	v_mfma_f32_16x16x32_bf16 v[92:95], v[212:215], v[180:183], v[92:95]
	v_mfma_f32_16x16x32_bf16 v[84:87], v[204:207], v[188:191], v[84:87]
	v_mfma_f32_16x16x32_bf16 v[76:79], v[212:215], v[188:191], v[76:79]
	v_mfma_f32_16x16x32_bf16 v[68:71], v[204:207], v[196:199], v[68:71]
	v_mfma_f32_16x16x32_bf16 v[64:67], v[212:215], v[196:199], v[64:67]
	s_mov_b32 m0, s49
	s_barrier
	ds_read_b128 v[168:171], v146 offset:49152
	ds_read_b128 v[172:175], v146 offset:50176
	ds_read_b128 v[176:179], v146 offset:51200
	ds_read_b128 v[180:183], v146 offset:52224
	ds_read_b128 v[184:187], v146 offset:53248
	ds_read_b128 v[188:191], v146 offset:54272
	ds_read_b128 v[192:195], v146 offset:55296
	ds_read_b128 v[196:199], v146 offset:56320
	global_load_lds_dwordx4 v134, s[100:101]
	s_mov_b32 m0, s56
	s_nop 0
	global_load_lds_dwordx4 v130, s[100:101]
	s_barrier
; #define PG8_STAGE(bufoff, gbase, voff) do { _Pragma("unroll") for (int _i = 0; _i < 2; ++_i) \
;         __builtin_amdgcn_global_load_lds((const unsigned*)((const char*)(gbase) + (voff)[_i]), (LAS unsigned*)(lds + (bufoff) + ldsw + _i * 8192), 16, 0, 0); } while (0)
; #define PG8_MMA(ai, bj, At, Bt) do { __builtin_amdgcn_s_setprio(1); _Pragma("unroll") for (int m = 0; m < 4; ++m) _Pragma("unroll") for (int n = 0; n < 2; ++n) _Pragma("unroll") for (int k = 0; k < 2; ++k) \
;         acc[ai][bj][m][n] = __builtin_amdgcn_mfma_f32_16x16x32_bf16(Bt[n][k], At[m][k], acc[ai][bj][m][n], 0, 0, 0); __builtin_amdgcn_s_setprio(0); } while (0)
; #define PG8_WAIT_V(n) asm volatile("s_waitcnt vmcnt(" #n ")" ::: "memory")
; #define PG8_WAIT_L(n) asm volatile("s_waitcnt lgkmcnt(" #n ")" ::: "memory")
; #define PG8_BAR __builtin_amdgcn_s_barrier()
; #define PG8_SCHED __builtin_amdgcn_sched_barrier(0)
; template <class Epi>
; __device__ __forceinline__ void gemm_phase(LAS unsigned char* lds, const Gemm g, const StaticOrder& S, const Epi& E) {
;     ...
;             PG8_BAR; PG8_WAIT_L(0); PG8_MMA(1, 0, At, B0); PG8_BAR; PG8_SCHED;
;             PG8_STAGE(PG8_SB(1, 1), b3 + hstep, voffB);
;             PG8_WAIT_V(6); PG8_BAR; PG8_MMA(1, 1, At, B1); PG8_BAR;
;         }
	s_waitcnt lgkmcnt(0)
	s_waitcnt lgkmcnt(0)
	v_mfma_f32_16x16x32_bf16 v[60:63], v[148:151], v[168:171], v[60:63]
	v_mfma_f32_16x16x32_bf16 v[56:59], v[160:163], v[168:171], v[56:59]
	v_mfma_f32_16x16x32_bf16 v[52:55], v[148:151], v[176:179], v[52:55]
	v_mfma_f32_16x16x32_bf16 v[44:47], v[160:163], v[176:179], v[44:47]
	v_mfma_f32_16x16x32_bf16 v[36:39], v[148:151], v[184:187], v[36:39]
	v_mfma_f32_16x16x32_bf16 v[28:31], v[160:163], v[184:187], v[28:31]
	v_mfma_f32_16x16x32_bf16 v[20:23], v[148:151], v[192:195], v[20:23]
	v_mfma_f32_16x16x32_bf16 v[12:15], v[160:163], v[192:195], v[12:15]
	v_mfma_f32_16x16x32_bf16 v[60:63], v[152:155], v[172:175], v[60:63]
	v_mfma_f32_16x16x32_bf16 v[56:59], v[164:167], v[172:175], v[56:59]
	v_mfma_f32_16x16x32_bf16 v[52:55], v[152:155], v[180:183], v[52:55]
	v_mfma_f32_16x16x32_bf16 v[44:47], v[164:167], v[180:183], v[44:47]
	v_mfma_f32_16x16x32_bf16 v[36:39], v[152:155], v[188:191], v[36:39]
	v_mfma_f32_16x16x32_bf16 v[28:31], v[164:167], v[188:191], v[28:31]
	v_mfma_f32_16x16x32_bf16 v[20:23], v[152:155], v[196:199], v[20:23]
	v_mfma_f32_16x16x32_bf16 v[12:15], v[164:167], v[196:199], v[12:15]
	s_barrier
	s_add_u32 s52, s52, 0x80080
	s_addc_u32 s53, s53, 0
	s_add_i32 s54, s54, s23
	s_mov_b32 m0, s54
	s_nop 0
	global_load_lds_dwordx4 v132, s[52:53]
	s_add_i32 m0, s54, 0x2000
	s_nop 0
	global_load_lds_dwordx4 v128, s[52:53]
	s_waitcnt vmcnt(6)
	s_barrier
	v_mfma_f32_16x16x32_bf16 v[48:51], v[200:203], v[168:171], v[48:51]
	v_mfma_f32_16x16x32_bf16 v[40:43], v[208:211], v[168:171], v[40:43]
	v_mfma_f32_16x16x32_bf16 v[32:35], v[200:203], v[176:179], v[32:35]
	v_mfma_f32_16x16x32_bf16 v[24:27], v[208:211], v[176:179], v[24:27]
	v_mfma_f32_16x16x32_bf16 v[16:19], v[200:203], v[184:187], v[16:19]
	v_mfma_f32_16x16x32_bf16 v[8:11], v[208:211], v[184:187], v[8:11]
	v_mfma_f32_16x16x32_bf16 v[4:7], v[200:203], v[192:195], v[4:7]
	v_mfma_f32_16x16x32_bf16 v[0:3], v[208:211], v[192:195], v[0:3]
	v_mfma_f32_16x16x32_bf16 v[48:51], v[204:207], v[172:175], v[48:51]
	v_mfma_f32_16x16x32_bf16 v[40:43], v[212:215], v[172:175], v[40:43]
	v_mfma_f32_16x16x32_bf16 v[32:35], v[204:207], v[180:183], v[32:35]
	v_mfma_f32_16x16x32_bf16 v[24:27], v[212:215], v[180:183], v[24:27]
	v_mfma_f32_16x16x32_bf16 v[16:19], v[204:207], v[188:191], v[16:19]
	v_mfma_f32_16x16x32_bf16 v[8:11], v[212:215], v[188:191], v[8:11]
	v_mfma_f32_16x16x32_bf16 v[4:7], v[204:207], v[196:199], v[4:7]
	v_mfma_f32_16x16x32_bf16 v[0:3], v[212:215], v[196:199], v[0:3]
	s_add_i32 s69, s69, 2
	s_add_u32 s50, s50, 0x100
	s_addc_u32 s51, s51, 0
	s_add_u32 s67, s67, 0x100
	s_addc_u32 s68, s68, 0
	s_cmp_gt_u32 s69, 29
	s_barrier
	s_cbranch_scc0 .LBB0_673
; #define PG8_WAIT_V(n) asm volatile("s_waitcnt vmcnt(" #n ")" ::: "memory")
; #define PG8_BAR __builtin_amdgcn_s_barrier()
; __device__ __forceinline__ u32x4 pack8(f32x4 v0, f32x4 v1) { u32x4 w; w.x = cvt_pk_bf16(v0[0], v0[1]); w.y = cvt_pk_bf16(v0[2], v0[3]); w.z = cvt_pk_bf16(v1[0], v1[1]); w.w = cvt_pk_bf16(v1[2], v1[3]); return w; }
; template <class Epi>
; __device__ __forceinline__ void gemm_phase(LAS unsigned char* lds, const Gemm g, const StaticOrder& S, const Epi& E) {
;     ...
;         cur = nxt; cA = nA; cB = nB; ++ui;
;     }
;     PG8_WAIT_V(0);
;     if (wr == 0) PG8_BAR;
;     PG8_BAR;
;     __device__ __forceinline__ void operator()(const f32x4 (&acc)[2][2][4][2], const Unit& u, int wr, int wc, int fr, int fq) const {
;         const int row0 = u.pm * BM + wr * 64 + fr, col0 = u.pn * BM + wc * 32 + 8 * fq;
; #pragma unroll
;         for (int ai = 0; ai < 2; ++ai)
; #pragma unroll
;             for (int m = 0; m < 4; ++m) { bf16_t* rowp = O + (size_t)(row0 + ai * HALF + m * 16) * ldc + col0;
; #pragma unroll
;                 for (int bj = 0; bj < 2; ++bj) *(u32x4*)(rowp + bj * HALF) = pack8(acc[ai][bj][m][0], acc[ai][bj][m][1]); }
;     }
	v_lshl_add_u32 v148, s48, 8, v142
	v_lshl_or_b32 v140, s64, 8, v144
	v_ashrrev_i32_e32 v149, 31, v148
	v_ashrrev_i32_e32 v141, 31, v140
	v_lshlrev_b64 v[150:151], 12, v[148:149]
	v_lshl_add_u64 v[150:151], s[24:25], 0, v[150:151]
	v_lshlrev_b64 v[152:153], 1, v[140:141]
	v_lshl_add_u64 v[140:141], v[150:151], 0, v[152:153]
	v_cvt_pk_bf16_f32 v124, v124, v125
	v_cvt_pk_bf16_f32 v125, v126, v127
	v_cvt_pk_bf16_f32 v126, v120, v121
	v_cvt_pk_bf16_f32 v127, v122, v123
	global_store_dwordx4 v[140:141], v[124:127], off
	v_cvt_pk_bf16_f32 v116, v116, v117
	v_cvt_pk_bf16_f32 v117, v118, v119
	v_cvt_pk_bf16_f32 v118, v108, v109
	v_or_b32_e32 v108, 16, v148
	v_ashrrev_i32_e32 v109, 31, v108
	v_lshlrev_b64 v[108:109], 12, v[108:109]
	v_lshl_add_u64 v[108:109], s[24:25], 0, v[108:109]
	v_cvt_pk_bf16_f32 v119, v110, v111
	global_store_dwordx4 v[140:141], v[116:119], off offset:256
	s_mov_b32 s64, s40
	s_mov_b32 s48, s42
	v_lshl_add_u64 v[116:117], v[108:109], 0, v[152:153]
	v_cvt_pk_bf16_f32 v108, v112, v113
	v_cvt_pk_bf16_f32 v109, v114, v115
	v_cvt_pk_bf16_f32 v110, v104, v105
	v_cvt_pk_bf16_f32 v111, v106, v107
	global_store_dwordx4 v[116:117], v[108:111], off
	v_cvt_pk_bf16_f32 v100, v100, v101
	v_cvt_pk_bf16_f32 v101, v102, v103
	v_cvt_pk_bf16_f32 v102, v92, v93
	v_or_b32_e32 v92, 32, v148
	v_ashrrev_i32_e32 v93, 31, v92
	v_lshlrev_b64 v[92:93], 12, v[92:93]
	v_lshl_add_u64 v[92:93], s[24:25], 0, v[92:93]
	v_cvt_pk_bf16_f32 v103, v94, v95
	global_store_dwordx4 v[116:117], v[100:103], off offset:256
	s_mov_b64 s[52:53], s[46:47]
	s_mov_b64 s[50:51], s[44:45]
	v_lshl_add_u64 v[100:101], v[92:93], 0, v[152:153]
	v_cvt_pk_bf16_f32 v92, v96, v97
	v_cvt_pk_bf16_f32 v93, v98, v99
	v_cvt_pk_bf16_f32 v94, v88, v89
	v_cvt_pk_bf16_f32 v95, v90, v91
	global_store_dwordx4 v[100:101], v[92:95], off
	v_cvt_pk_bf16_f32 v84, v84, v85
	v_cvt_pk_bf16_f32 v85, v86, v87
	v_cvt_pk_bf16_f32 v86, v76, v77
	v_or_b32_e32 v76, 48, v148
	v_ashrrev_i32_e32 v77, 31, v76
	v_lshlrev_b64 v[76:77], 12, v[76:77]
	v_lshl_add_u64 v[76:77], s[24:25], 0, v[76:77]
	v_cvt_pk_bf16_f32 v87, v78, v79
	global_store_dwordx4 v[100:101], v[84:87], off offset:256
	s_nop 1
	v_lshl_add_u64 v[84:85], v[76:77], 0, v[152:153]
	v_cvt_pk_bf16_f32 v76, v80, v81
	v_cvt_pk_bf16_f32 v77, v82, v83
	v_cvt_pk_bf16_f32 v78, v72, v73
	v_cvt_pk_bf16_f32 v79, v74, v75
	global_store_dwordx4 v[84:85], v[76:79], off
	v_cvt_pk_bf16_f32 v68, v68, v69
	v_cvt_pk_bf16_f32 v69, v70, v71
	v_cvt_pk_bf16_f32 v70, v64, v65
	v_cvt_pk_bf16_f32 v71, v66, v67
	global_store_dwordx4 v[84:85], v[68:71], off offset:256
	v_cvt_pk_bf16_f32 v60, v60, v61
	v_cvt_pk_bf16_f32 v61, v62, v63
	v_cvt_pk_bf16_f32 v62, v56, v57
	v_add_co_u32_e32 v56, vcc, s60, v140
	v_lshl_add_u64 v[64:65], v[140:141], 0, s[2:3]
	s_nop 0
	v_addc_co_u32_e32 v57, vcc, 0, v141, vcc
	v_cvt_pk_bf16_f32 v63, v58, v59
	global_store_dwordx4 v[56:57], v[60:63], off
	v_cvt_pk_bf16_f32 v48, v48, v49
	v_cvt_pk_bf16_f32 v49, v50, v51
	v_cvt_pk_bf16_f32 v50, v40, v41
	v_cvt_pk_bf16_f32 v51, v42, v43
	global_store_dwordx4 v[64:65], v[48:51], off offset:256
	v_cvt_pk_bf16_f32 v40, v52, v53
	v_cvt_pk_bf16_f32 v41, v54, v55
	v_cvt_pk_bf16_f32 v42, v44, v45
	v_add_co_u32_e32 v44, vcc, s61, v140
	s_nop 0
	v_lshl_add_u64 v[48:49], v[140:141], 0, s[8:9]
	v_addc_co_u32_e32 v45, vcc, 0, v141, vcc
	v_cvt_pk_bf16_f32 v43, v46, v47
	global_store_dwordx4 v[44:45], v[40:43], off
	v_cvt_pk_bf16_f32 v32, v32, v33
	v_cvt_pk_bf16_f32 v33, v34, v35
	v_cvt_pk_bf16_f32 v34, v24, v25
	v_cvt_pk_bf16_f32 v35, v26, v27
	global_store_dwordx4 v[48:49], v[32:35], off offset:256
	v_cvt_pk_bf16_f32 v24, v36, v37
	v_cvt_pk_bf16_f32 v25, v38, v39
	v_cvt_pk_bf16_f32 v26, v28, v29
	v_add_co_u32_e32 v28, vcc, s62, v140
	s_nop 0
	v_lshl_add_u64 v[32:33], v[140:141], 0, s[30:31]
	v_addc_co_u32_e32 v29, vcc, 0, v141, vcc
	v_cvt_pk_bf16_f32 v27, v30, v31
	global_store_dwordx4 v[28:29], v[24:27], off
	v_cvt_pk_bf16_f32 v16, v16, v17
	v_cvt_pk_bf16_f32 v17, v18, v19
	v_cvt_pk_bf16_f32 v18, v8, v9
	v_cvt_pk_bf16_f32 v19, v10, v11
	global_store_dwordx4 v[32:33], v[16:19], off offset:256
	v_cvt_pk_bf16_f32 v8, v20, v21
	v_cvt_pk_bf16_f32 v9, v22, v23
	v_cvt_pk_bf16_f32 v10, v12, v13
	v_add_co_u32_e32 v12, vcc, s63, v140
	s_nop 0
	v_lshl_add_u64 v[16:17], v[140:141], 0, s[34:35]
	v_addc_co_u32_e32 v13, vcc, 0, v141, vcc
	s_and_b64 vcc, exec, s[38:39]
	v_cvt_pk_bf16_f32 v11, v14, v15
	global_store_dwordx4 v[12:13], v[8:11], off
	v_cvt_pk_bf16_f32 v4, v4, v5
	v_cvt_pk_bf16_f32 v5, v6, v7
	v_cvt_pk_bf16_f32 v6, v0, v1
	v_cvt_pk_bf16_f32 v7, v2, v3
	global_store_dwordx4 v[16:17], v[4:7], off offset:256
	s_cbranch_vccz .LBB0_670
	s_waitcnt vmcnt(0)
	s_cmpk_gt_u32 s10, 0xff
	v_readlane_b32 s62, v232, 20
	v_readlane_b32 s61, v232, 21
	s_cbranch_scc1 .LBB0_677
	s_barrier

; #define PG8_STAGE(bufoff, gbase, voff) do { _Pragma("unroll") for (int _i = 0; _i < 2; ++_i) \
;         __builtin_amdgcn_global_load_lds((const unsigned*)((const char*)(gbase) + (voff)[_i]), (LAS unsigned*)(lds + (bufoff) + ldsw + _i * 8192), 16, 0, 0); } while (0)
; #define PG8_LDA(dst, b, h) do { _Pragma("unroll") for (int m = 0; m < 4; ++m) _Pragma("unroll") for (int k = 0; k < 2; ++k) dst[m][k] = *(const LAS bf16x8*)(lds + PG8_SA(b, h) + aoff + m * 2048 + k * 1024); } while (0)
; #define PG8_LDB(dst, b, h) do { _Pragma("unroll") for (int n = 0; n < 2; ++n) _Pragma("unroll") for (int k = 0; k < 2; ++k) dst[n][k] = *(const LAS bf16x8*)(lds + PG8_SB(b, h) + boff + n * 2048 + k * 1024); } while (0)
; #define PG8_MMA(ai, bj, At, Bt) do { __builtin_amdgcn_s_setprio(1); _Pragma("unroll") for (int m = 0; m < 4; ++m) _Pragma("unroll") for (int n = 0; n < 2; ++n) _Pragma("unroll") for (int k = 0; k < 2; ++k) \
;         acc[ai][bj][m][n] = __builtin_amdgcn_mfma_f32_16x16x32_bf16(Bt[n][k], At[m][k], acc[ai][bj][m][n], 0, 0, 0); __builtin_amdgcn_s_setprio(0); } while (0)
; #define PG8_WAIT_V(n) asm volatile("s_waitcnt vmcnt(" #n ")" ::: "memory")
; #define PG8_WAIT_L(n) asm volatile("s_waitcnt lgkmcnt(" #n ")" ::: "memory")
; template <class Epi>
; __device__ __forceinline__ void gemm_phase(LAS unsigned char* lds, const Gemm g, const StaticOrder& S, const Epi& E) {
;     ...
;         for (int t = 0; t < nt; t += 2) {
;             const bool last = (t == nt - 2);
;             const char* a1 = cA + (size_t)(t + 1) * kstep;
;             const char* a2 = last ? nA : cA + (size_t)(t + 2) * kstep; const char* b2 = last ? nB : cB + (size_t)(t + 2) * kstep;
;             const char* a3 = a2 + kstep; const char* b3 = b2 + kstep;
;             PG8_LDB(B0, 0, 0); PG8_SCHED; PG8_LDA(At, 0, 0); PG8_STAGE(PG8_SA(1, 1), a1 + hstep, voffA);
;             PG8_WAIT_L(8); PG8_BAR; PG8_WAIT_L(0); PG8_MMA(0, 0, At, B0); PG8_BAR; PG8_SCHED;
;             PG8_LDB(B1, 0, 1); PG8_STAGE(PG8_SB(0, 0), b2, voffB);
;             PG8_BAR; PG8_WAIT_L(0); PG8_MMA(0, 1, At, B1); PG8_BAR;
;             PG8_LDA(At, 0, 1); PG8_STAGE(PG8_SA(0, 0), a2, voffA);
;             PG8_BAR; PG8_WAIT_L(0); PG8_MMA(1, 0, At, B0); PG8_BAR; PG8_SCHED;
;             PG8_STAGE(PG8_SB(0, 1), b2 + hstep, voffB);
;             PG8_WAIT_V(6); PG8_BAR; PG8_MMA(1, 1, At, B1); PG8_BAR;
.LBB0_796:
	ds_read_b128 v[144:147], v155
	ds_read_b128 v[148:151], v155 offset:1024
	ds_read_b128 v[160:163], v155 offset:2048
	ds_read_b128 v[164:167], v155 offset:3072
	s_add_u32 s42, s40, 0xfff80080
	s_addc_u32 s43, s41, -1
	s_cmp_eq_u32 s58, 28
	s_cselect_b32 s45, s31, s43
	s_cselect_b32 s44, s54, s42
	s_cselect_b32 s43, s9, s57
	s_cselect_b32 s42, s55, s56
	s_add_i32 m0, s27, 0xc000
	ds_read_b128 v[168:171], v156
	ds_read_b128 v[172:175], v156 offset:1024
	ds_read_b128 v[176:179], v156 offset:2048
	ds_read_b128 v[180:183], v156 offset:3072
	ds_read_b128 v[184:187], v156 offset:4096
	ds_read_b128 v[188:191], v156 offset:5120
	ds_read_b128 v[192:195], v156 offset:6144
	ds_read_b128 v[196:199], v156 offset:7168
	global_load_lds_dwordx4 v136, s[40:41]
	s_add_i32 m0, s27, 0xe000
	s_nop 0
	global_load_lds_dwordx4 v138, s[40:41]
	s_waitcnt lgkmcnt(8)
	s_barrier
	s_waitcnt lgkmcnt(0)
	s_waitcnt lgkmcnt(0)
	v_mfma_f32_16x16x32_bf16 v[124:127], v[144:147], v[168:171], v[124:127]
	v_mfma_f32_16x16x32_bf16 v[120:123], v[160:163], v[168:171], v[120:123]
	v_mfma_f32_16x16x32_bf16 v[108:111], v[144:147], v[176:179], v[108:111]
	v_mfma_f32_16x16x32_bf16 v[104:107], v[160:163], v[176:179], v[104:107]
	v_mfma_f32_16x16x32_bf16 v[92:95], v[144:147], v[184:187], v[92:95]
	v_mfma_f32_16x16x32_bf16 v[88:91], v[160:163], v[184:187], v[88:91]
	v_mfma_f32_16x16x32_bf16 v[76:79], v[144:147], v[192:195], v[76:79]
	v_mfma_f32_16x16x32_bf16 v[72:75], v[160:163], v[192:195], v[72:75]
	v_mfma_f32_16x16x32_bf16 v[124:127], v[148:151], v[172:175], v[124:127]
	v_mfma_f32_16x16x32_bf16 v[120:123], v[164:167], v[172:175], v[120:123]
	v_mfma_f32_16x16x32_bf16 v[108:111], v[148:151], v[180:183], v[108:111]
	v_mfma_f32_16x16x32_bf16 v[104:107], v[164:167], v[180:183], v[104:107]
	v_mfma_f32_16x16x32_bf16 v[92:95], v[148:151], v[188:191], v[92:95]
	v_mfma_f32_16x16x32_bf16 v[88:91], v[164:167], v[188:191], v[88:91]
	v_mfma_f32_16x16x32_bf16 v[76:79], v[148:151], v[196:199], v[76:79]
	v_mfma_f32_16x16x32_bf16 v[72:75], v[164:167], v[196:199], v[72:75]
	s_barrier
	s_add_i32 s59, s50, s23
	s_add_u32 s98, s42, s2
	s_addc_u32 s99, s43, s3
	s_mov_b32 m0, s59
	ds_read_b128 v[200:203], v157
	ds_read_b128 v[204:207], v157 offset:1024
	ds_read_b128 v[208:211], v157 offset:2048
	ds_read_b128 v[212:215], v157 offset:3072
	global_load_lds_dwordx4 v132, s[42:43]
	s_add_i32 m0, s59, 0x2000
	s_nop 0
	global_load_lds_dwordx4 v128, s[42:43]
	s_barrier
	s_waitcnt lgkmcnt(0)
	s_waitcnt lgkmcnt(0)
	v_mfma_f32_16x16x32_bf16 v[116:119], v[200:203], v[168:171], v[116:119]
	v_mfma_f32_16x16x32_bf16 v[112:115], v[208:211], v[168:171], v[112:115]
	v_mfma_f32_16x16x32_bf16 v[100:103], v[200:203], v[176:179], v[100:103]
	v_mfma_f32_16x16x32_bf16 v[96:99], v[208:211], v[176:179], v[96:99]
	v_mfma_f32_16x16x32_bf16 v[84:87], v[200:203], v[184:187], v[84:87]
	v_mfma_f32_16x16x32_bf16 v[80:83], v[208:211], v[184:187], v[80:83]
	v_mfma_f32_16x16x32_bf16 v[68:71], v[200:203], v[192:195], v[68:71]
	v_mfma_f32_16x16x32_bf16 v[64:67], v[208:211], v[192:195], v[64:67]
	v_mfma_f32_16x16x32_bf16 v[116:119], v[204:207], v[172:175], v[116:119]
	v_mfma_f32_16x16x32_bf16 v[112:115], v[212:215], v[172:175], v[112:115]
	v_mfma_f32_16x16x32_bf16 v[100:103], v[204:207], v[180:183], v[100:103]
	v_mfma_f32_16x16x32_bf16 v[96:99], v[212:215], v[180:183], v[96:99]
	v_mfma_f32_16x16x32_bf16 v[84:87], v[204:207], v[188:191], v[84:87]
	v_mfma_f32_16x16x32_bf16 v[80:83], v[212:215], v[188:191], v[80:83]
	v_mfma_f32_16x16x32_bf16 v[68:71], v[204:207], v[196:199], v[68:71]
	v_mfma_f32_16x16x32_bf16 v[64:67], v[212:215], v[196:199], v[64:67]
	s_mov_b32 m0, s27
	s_add_u32 s100, s44, s2
	s_addc_u32 s101, s45, s3
	s_barrier
	ds_read_b128 v[168:171], v156 offset:16384
	ds_read_b128 v[172:175], v156 offset:17408
	ds_read_b128 v[176:179], v156 offset:18432
	ds_read_b128 v[180:183], v156 offset:19456
	ds_read_b128 v[184:187], v156 offset:20480
	ds_read_b128 v[188:191], v156 offset:21504
	ds_read_b128 v[192:195], v156 offset:22528
	ds_read_b128 v[196:199], v156 offset:23552
	global_load_lds_dwordx4 v134, s[44:45]
	s_mov_b32 m0, s28
	s_nop 0
	global_load_lds_dwordx4 v130, s[44:45]
	s_barrier
	s_waitcnt lgkmcnt(0)
	s_waitcnt lgkmcnt(0)
	v_mfma_f32_16x16x32_bf16 v[60:63], v[144:147], v[168:171], v[60:63]
	v_mfma_f32_16x16x32_bf16 v[56:59], v[160:163], v[168:171], v[56:59]
	v_mfma_f32_16x16x32_bf16 v[44:47], v[144:147], v[176:179], v[44:47]
	v_mfma_f32_16x16x32_bf16 v[40:43], v[160:163], v[176:179], v[40:43]
	v_mfma_f32_16x16x32_bf16 v[28:31], v[144:147], v[184:187], v[28:31]
	v_mfma_f32_16x16x32_bf16 v[24:27], v[160:163], v[184:187], v[24:27]
	v_mfma_f32_16x16x32_bf16 v[12:15], v[144:147], v[192:195], v[12:15]
	v_mfma_f32_16x16x32_bf16 v[8:11], v[160:163], v[192:195], v[8:11]
	v_mfma_f32_16x16x32_bf16 v[60:63], v[148:151], v[172:175], v[60:63]
	v_mfma_f32_16x16x32_bf16 v[56:59], v[164:167], v[172:175], v[56:59]
	v_mfma_f32_16x16x32_bf16 v[44:47], v[148:151], v[180:183], v[44:47]
	v_mfma_f32_16x16x32_bf16 v[40:43], v[164:167], v[180:183], v[40:43]
	v_mfma_f32_16x16x32_bf16 v[28:31], v[148:151], v[188:191], v[28:31]
	v_mfma_f32_16x16x32_bf16 v[24:27], v[164:167], v[188:191], v[24:27]
	v_mfma_f32_16x16x32_bf16 v[12:15], v[148:151], v[196:199], v[12:15]
	v_mfma_f32_16x16x32_bf16 v[8:11], v[164:167], v[196:199], v[8:11]
	s_barrier
	s_add_u32 s60, s42, 0x80000
	s_addc_u32 s61, s43, 0
	s_add_i32 s59, s51, s23
	s_mov_b32 m0, s59
	s_nop 0
	global_load_lds_dwordx4 v132, s[60:61]
	s_add_i32 m0, s59, 0x2000
	s_nop 0
	global_load_lds_dwordx4 v128, s[60:61]
	s_waitcnt vmcnt(6)
	s_barrier
; #define PG8_STAGE(bufoff, gbase, voff) do { _Pragma("unroll") for (int _i = 0; _i < 2; ++_i) \
;         __builtin_amdgcn_global_load_lds((const unsigned*)((const char*)(gbase) + (voff)[_i]), (LAS unsigned*)(lds + (bufoff) + ldsw + _i * 8192), 16, 0, 0); } while (0)
; #define PG8_LDA(dst, b, h) do { _Pragma("unroll") for (int m = 0; m < 4; ++m) _Pragma("unroll") for (int k = 0; k < 2; ++k) dst[m][k] = *(const LAS bf16x8*)(lds + PG8_SA(b, h) + aoff + m * 2048 + k * 1024); } while (0)
; #define PG8_LDB(dst, b, h) do { _Pragma("unroll") for (int n = 0; n < 2; ++n) _Pragma("unroll") for (int k = 0; k < 2; ++k) dst[n][k] = *(const LAS bf16x8*)(lds + PG8_SB(b, h) + boff + n * 2048 + k * 1024); } while (0)
; #define PG8_MMA(ai, bj, At, Bt) do { __builtin_amdgcn_s_setprio(1); _Pragma("unroll") for (int m = 0; m < 4; ++m) _Pragma("unroll") for (int n = 0; n < 2; ++n) _Pragma("unroll") for (int k = 0; k < 2; ++k) \
;         acc[ai][bj][m][n] = __builtin_amdgcn_mfma_f32_16x16x32_bf16(Bt[n][k], At[m][k], acc[ai][bj][m][n], 0, 0, 0); __builtin_amdgcn_s_setprio(0); } while (0)
; #define PG8_WAIT_V(n) asm volatile("s_waitcnt vmcnt(" #n ")" ::: "memory")
; #define PG8_WAIT_L(n) asm volatile("s_waitcnt lgkmcnt(" #n ")" ::: "memory")
; #define PG8_BAR __builtin_amdgcn_s_barrier()
; #define PG8_SCHED __builtin_amdgcn_sched_barrier(0)
; template <class Epi>
; __device__ __forceinline__ void gemm_phase(LAS unsigned char* lds, const Gemm g, const StaticOrder& S, const Epi& E) {
;     ...
;             PG8_WAIT_V(6); PG8_BAR; PG8_MMA(1, 1, At, B1); PG8_BAR;
;             PG8_LDB(B0, 1, 0); PG8_SCHED; PG8_LDA(At, 1, 0); PG8_STAGE(PG8_SA(0, 1), a2 + hstep, voffA);
;             PG8_WAIT_L(8); PG8_BAR; PG8_WAIT_L(0); PG8_MMA(0, 0, At, B0); PG8_BAR; PG8_SCHED;
;             PG8_LDB(B1, 1, 1); PG8_STAGE(PG8_SB(1, 0), b3, voffB);
;             PG8_BAR; PG8_WAIT_L(0); PG8_MMA(0, 1, At, B1); PG8_BAR;
;             PG8_LDA(At, 1, 1); PG8_STAGE(PG8_SA(1, 0), a3, voffA);
	v_mfma_f32_16x16x32_bf16 v[52:55], v[200:203], v[168:171], v[52:55]
	v_mfma_f32_16x16x32_bf16 v[48:51], v[208:211], v[168:171], v[48:51]
	v_mfma_f32_16x16x32_bf16 v[36:39], v[200:203], v[176:179], v[36:39]
	v_mfma_f32_16x16x32_bf16 v[32:35], v[208:211], v[176:179], v[32:35]
	v_mfma_f32_16x16x32_bf16 v[20:23], v[200:203], v[184:187], v[20:23]
	v_mfma_f32_16x16x32_bf16 v[16:19], v[208:211], v[184:187], v[16:19]
	v_mfma_f32_16x16x32_bf16 v[4:7], v[200:203], v[192:195], v[4:7]
	v_mfma_f32_16x16x32_bf16 v[0:3], v[208:211], v[192:195], v[0:3]
	v_mfma_f32_16x16x32_bf16 v[52:55], v[204:207], v[172:175], v[52:55]
	v_mfma_f32_16x16x32_bf16 v[48:51], v[212:215], v[172:175], v[48:51]
	v_mfma_f32_16x16x32_bf16 v[36:39], v[204:207], v[180:183], v[36:39]
	v_mfma_f32_16x16x32_bf16 v[32:35], v[212:215], v[180:183], v[32:35]
	v_mfma_f32_16x16x32_bf16 v[20:23], v[204:207], v[188:191], v[20:23]
	v_mfma_f32_16x16x32_bf16 v[16:19], v[212:215], v[188:191], v[16:19]
	v_mfma_f32_16x16x32_bf16 v[4:7], v[204:207], v[196:199], v[4:7]
	v_mfma_f32_16x16x32_bf16 v[0:3], v[212:215], v[196:199], v[0:3]
	s_add_i32 s59, 0, 0x18000
	v_add_u32_e32 v164, s59, v153
	s_barrier
	ds_read_b128 v[144:147], v164
	ds_read_b128 v[148:151], v164 offset:1024
	ds_read_b128 v[160:163], v164 offset:2048
	ds_read_b128 v[164:167], v164 offset:3072
	s_add_u32 s44, s44, 0x80000
	s_addc_u32 s45, s45, 0
	s_mov_b32 m0, s29
	ds_read_b128 v[168:171], v156 offset:32768
	ds_read_b128 v[172:175], v156 offset:33792
	ds_read_b128 v[176:179], v156 offset:34816
	ds_read_b128 v[180:183], v156 offset:35840
	ds_read_b128 v[184:187], v156 offset:36864
	ds_read_b128 v[188:191], v156 offset:37888
	ds_read_b128 v[192:195], v156 offset:38912
	ds_read_b128 v[196:199], v156 offset:39936
	global_load_lds_dwordx4 v134, s[44:45]
	s_mov_b32 m0, s33
	s_nop 0
	global_load_lds_dwordx4 v130, s[44:45]
	s_waitcnt lgkmcnt(8)
	s_barrier
	s_waitcnt lgkmcnt(0)
	s_waitcnt lgkmcnt(0)
	v_mfma_f32_16x16x32_bf16 v[124:127], v[144:147], v[168:171], v[124:127]
	v_mfma_f32_16x16x32_bf16 v[120:123], v[160:163], v[168:171], v[120:123]
	v_mfma_f32_16x16x32_bf16 v[108:111], v[144:147], v[176:179], v[108:111]
	v_mfma_f32_16x16x32_bf16 v[104:107], v[160:163], v[176:179], v[104:107]
	v_mfma_f32_16x16x32_bf16 v[92:95], v[144:147], v[184:187], v[92:95]
	v_mfma_f32_16x16x32_bf16 v[88:91], v[160:163], v[184:187], v[88:91]
	v_mfma_f32_16x16x32_bf16 v[76:79], v[144:147], v[192:195], v[76:79]
	v_mfma_f32_16x16x32_bf16 v[72:75], v[160:163], v[192:195], v[72:75]
	v_mfma_f32_16x16x32_bf16 v[124:127], v[148:151], v[172:175], v[124:127]
	v_mfma_f32_16x16x32_bf16 v[120:123], v[164:167], v[172:175], v[120:123]
	v_mfma_f32_16x16x32_bf16 v[108:111], v[148:151], v[180:183], v[108:111]
	v_mfma_f32_16x16x32_bf16 v[104:107], v[164:167], v[180:183], v[104:107]
	v_mfma_f32_16x16x32_bf16 v[92:95], v[148:151], v[188:191], v[92:95]
	v_mfma_f32_16x16x32_bf16 v[88:91], v[164:167], v[188:191], v[88:91]
	v_mfma_f32_16x16x32_bf16 v[76:79], v[148:151], v[196:199], v[76:79]
	v_mfma_f32_16x16x32_bf16 v[72:75], v[164:167], v[196:199], v[72:75]
	s_barrier
	s_add_i32 s44, 0, 0x1c000
	s_add_i32 s45, s59, s23
	v_add_u32_e32 v212, s44, v153
	s_mov_b32 m0, s45
	ds_read_b128 v[200:203], v212
	ds_read_b128 v[204:207], v212 offset:1024
	ds_read_b128 v[208:211], v212 offset:2048
	ds_read_b128 v[212:215], v212 offset:3072
	global_load_lds_dwordx4 v132, s[98:99]
	s_add_i32 m0, s45, 0x2000
	s_nop 0
	global_load_lds_dwordx4 v128, s[98:99]
	s_barrier
	s_waitcnt lgkmcnt(0)
	s_waitcnt lgkmcnt(0)
	v_mfma_f32_16x16x32_bf16 v[116:119], v[200:203], v[168:171], v[116:119]
	v_mfma_f32_16x16x32_bf16 v[112:115], v[208:211], v[168:171], v[112:115]
	v_mfma_f32_16x16x32_bf16 v[100:103], v[200:203], v[176:179], v[100:103]
	v_mfma_f32_16x16x32_bf16 v[96:99], v[208:211], v[176:179], v[96:99]
	v_mfma_f32_16x16x32_bf16 v[84:87], v[200:203], v[184:187], v[84:87]
	v_mfma_f32_16x16x32_bf16 v[80:83], v[208:211], v[184:187], v[80:83]
	v_mfma_f32_16x16x32_bf16 v[68:71], v[200:203], v[192:195], v[68:71]
	v_mfma_f32_16x16x32_bf16 v[64:67], v[208:211], v[192:195], v[64:67]
	v_mfma_f32_16x16x32_bf16 v[116:119], v[204:207], v[172:175], v[116:119]
	v_mfma_f32_16x16x32_bf16 v[112:115], v[212:215], v[172:175], v[112:115]
	v_mfma_f32_16x16x32_bf16 v[100:103], v[204:207], v[180:183], v[100:103]
	v_mfma_f32_16x16x32_bf16 v[96:99], v[212:215], v[180:183], v[96:99]
	v_mfma_f32_16x16x32_bf16 v[84:87], v[204:207], v[188:191], v[84:87]
	v_mfma_f32_16x16x32_bf16 v[80:83], v[212:215], v[188:191], v[80:83]
	v_mfma_f32_16x16x32_bf16 v[68:71], v[204:207], v[196:199], v[68:71]
	v_mfma_f32_16x16x32_bf16 v[64:67], v[212:215], v[196:199], v[64:67]
	s_mov_b32 m0, s46
	s_barrier
	ds_read_b128 v[168:171], v156 offset:49152
	ds_read_b128 v[172:175], v156 offset:50176
	ds_read_b128 v[176:179], v156 offset:51200
	ds_read_b128 v[180:183], v156 offset:52224
	ds_read_b128 v[184:187], v156 offset:53248
	ds_read_b128 v[188:191], v156 offset:54272
	ds_read_b128 v[192:195], v156 offset:55296
	ds_read_b128 v[196:199], v156 offset:56320
	global_load_lds_dwordx4 v134, s[100:101]
	s_mov_b32 m0, s47
	s_nop 0
	global_load_lds_dwordx4 v130, s[100:101]
	s_barrier
; __device__ __forceinline__ float fast_rcp(float x) { return __builtin_amdgcn_rcpf(x); }
; __device__ __forceinline__ float fast_exp2(float x) { return __builtin_amdgcn_exp2f(x); }
; #define PG8_STAGE(bufoff, gbase, voff) do { _Pragma("unroll") for (int _i = 0; _i < 2; ++_i) \
;         __builtin_amdgcn_global_load_lds((const unsigned*)((const char*)(gbase) + (voff)[_i]), (LAS unsigned*)(lds + (bufoff) + ldsw + _i * 8192), 16, 0, 0); } while (0)
; #define PG8_MMA(ai, bj, At, Bt) do { __builtin_amdgcn_s_setprio(1); _Pragma("unroll") for (int m = 0; m < 4; ++m) _Pragma("unroll") for (int n = 0; n < 2; ++n) _Pragma("unroll") for (int k = 0; k < 2; ++k) \
;         acc[ai][bj][m][n] = __builtin_amdgcn_mfma_f32_16x16x32_bf16(Bt[n][k], At[m][k], acc[ai][bj][m][n], 0, 0, 0); __builtin_amdgcn_s_setprio(0); } while (0)
; #define PG8_WAIT_V(n) asm volatile("s_waitcnt vmcnt(" #n ")" ::: "memory")
; #define PG8_WAIT_L(n) asm volatile("s_waitcnt lgkmcnt(" #n ")" ::: "memory")
; #define PG8_BAR __builtin_amdgcn_s_barrier()
; #define PG8_SCHED __builtin_amdgcn_sched_barrier(0)
; template <class Epi>
; __device__ __forceinline__ void gemm_phase(LAS unsigned char* lds, const Gemm g, const StaticOrder& S, const Epi& E) {
;     ...
;             PG8_BAR; PG8_WAIT_L(0); PG8_MMA(1, 0, At, B0); PG8_BAR; PG8_SCHED;
;             PG8_STAGE(PG8_SB(1, 1), b3 + hstep, voffB);
;             PG8_WAIT_V(6); PG8_BAR; PG8_MMA(1, 1, At, B1); PG8_BAR;
;     __device__ __forceinline__ void operator()(const f32x4 (&acc)[2][2][4][2], const Unit& u, int wr, int wc, int fr, int fq) const {
;     ...
;             for (int m = 0; m < 4; ++m) { bf16_t* rowp = O + (size_t)(row0 + ai * HALF + m * 16) * DFF + col0;
;                 const float r = rs[row0 + ai * HALF + m * 16], r2 = r * r;
;                 f32x4 h0, h1;
; #pragma unroll
;                 for (int j = 0; j < 4; ++j) {
;                     const float g0 = acc[ai][0][m][0][j], g1 = acc[ai][0][m][1][j];
;                     h0[j] = g0 * r2 * fast_rcp(1.0f + fast_exp2(g0 * (-LOG2E * r))) * acc[ai][1][m][0][j];
;                     h1[j] = g1 * r2 * fast_rcp(1.0f + fast_exp2(g1 * (-LOG2E * r))) * acc[ai][1][m][1][j]; }
	s_waitcnt lgkmcnt(0)
	s_waitcnt lgkmcnt(0)
	v_mfma_f32_16x16x32_bf16 v[60:63], v[144:147], v[168:171], v[60:63]
	v_mfma_f32_16x16x32_bf16 v[56:59], v[160:163], v[168:171], v[56:59]
	v_mfma_f32_16x16x32_bf16 v[44:47], v[144:147], v[176:179], v[44:47]
	v_mfma_f32_16x16x32_bf16 v[40:43], v[160:163], v[176:179], v[40:43]
	v_mfma_f32_16x16x32_bf16 v[28:31], v[144:147], v[184:187], v[28:31]
	v_mfma_f32_16x16x32_bf16 v[24:27], v[160:163], v[184:187], v[24:27]
	v_mfma_f32_16x16x32_bf16 v[12:15], v[144:147], v[192:195], v[12:15]
	v_mfma_f32_16x16x32_bf16 v[8:11], v[160:163], v[192:195], v[8:11]
	v_mfma_f32_16x16x32_bf16 v[60:63], v[148:151], v[172:175], v[60:63]
	v_mfma_f32_16x16x32_bf16 v[56:59], v[164:167], v[172:175], v[56:59]
	v_mfma_f32_16x16x32_bf16 v[44:47], v[148:151], v[180:183], v[44:47]
	v_mfma_f32_16x16x32_bf16 v[40:43], v[164:167], v[180:183], v[40:43]
	v_mfma_f32_16x16x32_bf16 v[28:31], v[148:151], v[188:191], v[28:31]
	v_mfma_f32_16x16x32_bf16 v[24:27], v[164:167], v[188:191], v[24:27]
	v_mfma_f32_16x16x32_bf16 v[12:15], v[148:151], v[196:199], v[12:15]
	v_mfma_f32_16x16x32_bf16 v[8:11], v[164:167], v[196:199], v[8:11]
	s_barrier
	s_add_u32 s42, s42, 0x80080
	s_addc_u32 s43, s43, 0
	s_add_i32 s44, s44, s23
	s_mov_b32 m0, s44
	s_nop 0
	global_load_lds_dwordx4 v132, s[42:43]
	s_add_i32 m0, s44, 0x2000
	s_nop 0
	global_load_lds_dwordx4 v128, s[42:43]
	s_waitcnt vmcnt(6)
	s_barrier
	v_mfma_f32_16x16x32_bf16 v[52:55], v[200:203], v[168:171], v[52:55]
	v_mfma_f32_16x16x32_bf16 v[48:51], v[208:211], v[168:171], v[48:51]
	v_mfma_f32_16x16x32_bf16 v[36:39], v[200:203], v[176:179], v[36:39]
	v_mfma_f32_16x16x32_bf16 v[32:35], v[208:211], v[176:179], v[32:35]
	v_mfma_f32_16x16x32_bf16 v[20:23], v[200:203], v[184:187], v[20:23]
	v_mfma_f32_16x16x32_bf16 v[16:19], v[208:211], v[184:187], v[16:19]
	v_mfma_f32_16x16x32_bf16 v[4:7], v[200:203], v[192:195], v[4:7]
	v_mfma_f32_16x16x32_bf16 v[0:3], v[208:211], v[192:195], v[0:3]
	v_mfma_f32_16x16x32_bf16 v[52:55], v[204:207], v[172:175], v[52:55]
	v_mfma_f32_16x16x32_bf16 v[48:51], v[212:215], v[172:175], v[48:51]
	v_mfma_f32_16x16x32_bf16 v[36:39], v[204:207], v[180:183], v[36:39]
	v_mfma_f32_16x16x32_bf16 v[32:35], v[212:215], v[180:183], v[32:35]
	v_mfma_f32_16x16x32_bf16 v[20:23], v[204:207], v[188:191], v[20:23]
	v_mfma_f32_16x16x32_bf16 v[16:19], v[212:215], v[188:191], v[16:19]
	v_mfma_f32_16x16x32_bf16 v[4:7], v[204:207], v[196:199], v[4:7]
	v_mfma_f32_16x16x32_bf16 v[0:3], v[212:215], v[196:199], v[0:3]
	s_add_i32 s58, s58, 2
	s_add_u32 s40, s40, 0x100
	s_addc_u32 s41, s41, 0
	s_add_u32 s56, s56, 0x100
	s_addc_u32 s57, s57, 0
	s_cmp_gt_u32 s58, 29
	s_barrier
	s_cbranch_scc0 .LBB0_796
	v_lshl_add_u32 v144, s38, 8, v152
	v_ashrrev_i32_e32 v145, 31, v144
	v_lshl_add_u64 v[150:151], v[144:145], 2, s[14:15]
	v_mov_b32_e32 v145, v224
	v_mov_b32_e32 v204, v225
	v_mov_b32_e32 v205, v226
	v_mov_b32_e32 v206, v227
	v_mov_b32_e32 v207, v228
	v_mov_b32_e32 v208, v229
	v_mov_b32_e32 v209, v230
	v_mov_b32_e32 v210, v231
	v_lshl_or_b32 v148, s53, 7, v154
	v_mov_b64_e32 v[146:147], s[20:21]
	v_ashrrev_i32_e32 v149, 31, v148
	v_mad_i64_i32 v[160:161], s[40:41], v144, s52, v[146:147]
	v_lshlrev_b64 v[148:149], 1, v[148:149]
	v_lshl_add_u64 v[160:161], v[160:161], 0, v[148:149]
	s_and_b64 vcc, exec, s[6:7]
	s_mov_b32 s53, s8
	s_mov_b32 s38, s30
	s_mov_b64 s[42:43], s[36:37]
	v_mul_f32_e32 v162, v145, v145
	v_mul_f32_e32 v145, 0xbfb8aa3b, v145
	v_mul_f32_e32 v163, v124, v162
	v_mul_f32_e32 v164, v120, v162
	v_mul_f32_e32 v120, v120, v145
	v_mul_f32_e32 v165, v125, v162
	v_mul_f32_e32 v125, v125, v145
	v_mul_f32_e32 v166, v121, v162
	v_mul_f32_e32 v121, v121, v145
	v_mul_f32_e32 v167, v126, v162
	v_mul_f32_e32 v126, v126, v145
	v_mul_f32_e32 v168, v122, v162
	v_mul_f32_e32 v122, v122, v145
	v_mul_f32_e32 v169, v127, v162
	v_mul_f32_e32 v127, v127, v145
	v_mul_f32_e32 v162, v123, v162
	v_mul_f32_e32 v123, v123, v145
	v_mul_f32_e32 v124, v124, v145
	v_exp_f32_e32 v120, v120
	v_exp_f32_e32 v125, v125
	v_exp_f32_e32 v121, v121
	v_exp_f32_e32 v126, v126
	v_exp_f32_e32 v122, v122
	v_exp_f32_e32 v127, v127
	v_exp_f32_e32 v123, v123
	v_exp_f32_e32 v124, v124
	v_add_f32_e32 v120, 1.0, v120
	v_add_f32_e32 v125, 1.0, v125
	v_add_f32_e32 v121, 1.0, v121
	v_add_f32_e32 v126, 1.0, v126
	v_add_f32_e32 v122, 1.0, v122
	v_add_f32_e32 v127, 1.0, v127
	v_add_f32_e32 v123, 1.0, v123
	v_add_f32_e32 v124, 1.0, v124
	v_rcp_f32_e32 v120, v120
	v_rcp_f32_e32 v125, v125
	v_rcp_f32_e32 v121, v121
	v_rcp_f32_e32 v126, v126
	v_rcp_f32_e32 v122, v122
	v_rcp_f32_e32 v127, v127
	v_rcp_f32_e32 v123, v123
	v_rcp_f32_e32 v124, v124
	v_mul_f32_e32 v120, v164, v120
	v_mul_f32_e32 v125, v165, v125
	v_mul_f32_e32 v121, v166, v121
	v_mul_f32_e32 v126, v167, v126
	v_mul_f32_e32 v122, v168, v122
	v_mul_f32_e32 v127, v169, v127
	v_mul_f32_e32 v123, v162, v123
	v_mul_f32_e32 v124, v163, v124
	v_mul_f32_e32 v120, v112, v120
	v_mul_f32_e32 v112, v117, v125
	v_mul_f32_e32 v117, v113, v121
	v_mul_f32_e32 v113, v118, v126
	v_mul_f32_e32 v118, v114, v122
	v_mul_f32_e32 v114, v119, v127
	v_mul_f32_e32 v115, v115, v123
	v_mul_f32_e32 v116, v116, v124
	v_cvt_pk_bf16_f32 v112, v116, v112
	v_cvt_pk_bf16_f32 v113, v113, v114
	v_cvt_pk_bf16_f32 v114, v120, v117
	v_cvt_pk_bf16_f32 v115, v118, v115
	global_store_dwordx4 v[160:161], v[112:115], off
	s_nop 1
	v_mov_b32_e32 v114, v204
	s_nop 0
	v_or_b32_e32 v112, 16, v144
	v_mad_i64_i32 v[112:113], s[40:41], v112, s52, v[146:147]
	v_lshl_add_u64 v[112:113], v[112:113], 0, v[148:149]
	v_mul_f32_e32 v115, v114, v114
	v_mul_f32_e32 v114, 0xbfb8aa3b, v114
	v_mul_f32_e32 v116, v108, v115
	v_mul_f32_e32 v117, v104, v115
; __device__ __forceinline__ float fast_rcp(float x) { return __builtin_amdgcn_rcpf(x); }
; __device__ __forceinline__ float fast_exp2(float x) { return __builtin_amdgcn_exp2f(x); }
; __device__ __forceinline__ u32x4 pack8(f32x4 v0, f32x4 v1) { u32x4 w; w.x = cvt_pk_bf16(v0[0], v0[1]); w.y = cvt_pk_bf16(v0[2], v0[3]); w.z = cvt_pk_bf16(v1[0], v1[1]); w.w = cvt_pk_bf16(v1[2], v1[3]); return w; }
;     __device__ __forceinline__ void operator()(const f32x4 (&acc)[2][2][4][2], const Unit& u, int wr, int wc, int fr, int fq) const {
;     ...
;             for (int m = 0; m < 4; ++m) { bf16_t* rowp = O + (size_t)(row0 + ai * HALF + m * 16) * DFF + col0;
;                 const float r = rs[row0 + ai * HALF + m * 16], r2 = r * r;
;                 f32x4 h0, h1;
; #pragma unroll
;                 for (int j = 0; j < 4; ++j) {
;                     const float g0 = acc[ai][0][m][0][j], g1 = acc[ai][0][m][1][j];
;                     h0[j] = g0 * r2 * fast_rcp(1.0f + fast_exp2(g0 * (-LOG2E * r))) * acc[ai][1][m][0][j];
;                     h1[j] = g1 * r2 * fast_rcp(1.0f + fast_exp2(g1 * (-LOG2E * r))) * acc[ai][1][m][1][j]; }
;                 *(u32x4*)rowp = pack8(h0, h1); }
	v_mul_f32_e32 v104, v104, v114
	v_mul_f32_e32 v118, v109, v115
	v_mul_f32_e32 v109, v109, v114
	v_mul_f32_e32 v119, v105, v115
	v_mul_f32_e32 v105, v105, v114
	v_mul_f32_e32 v120, v110, v115
	v_mul_f32_e32 v110, v110, v114
	v_mul_f32_e32 v121, v106, v115
	v_mul_f32_e32 v106, v106, v114
	v_mul_f32_e32 v122, v111, v115
	v_mul_f32_e32 v111, v111, v114
	v_mul_f32_e32 v115, v107, v115
	v_mul_f32_e32 v107, v107, v114
	v_mul_f32_e32 v108, v108, v114
	v_exp_f32_e32 v104, v104
	v_exp_f32_e32 v109, v109
	v_exp_f32_e32 v105, v105
	v_exp_f32_e32 v110, v110
	v_exp_f32_e32 v106, v106
	v_exp_f32_e32 v111, v111
	v_exp_f32_e32 v107, v107
	v_exp_f32_e32 v108, v108
	v_add_f32_e32 v104, 1.0, v104
	v_add_f32_e32 v109, 1.0, v109
	v_add_f32_e32 v105, 1.0, v105
	v_add_f32_e32 v110, 1.0, v110
	v_add_f32_e32 v106, 1.0, v106
	v_add_f32_e32 v111, 1.0, v111
	v_add_f32_e32 v107, 1.0, v107
	v_add_f32_e32 v108, 1.0, v108
	v_rcp_f32_e32 v104, v104
	v_rcp_f32_e32 v109, v109
	v_rcp_f32_e32 v105, v105
	v_rcp_f32_e32 v110, v110
	v_rcp_f32_e32 v106, v106
	v_rcp_f32_e32 v111, v111
	v_rcp_f32_e32 v107, v107
	v_rcp_f32_e32 v108, v108
	v_mul_f32_e32 v104, v117, v104
	v_mul_f32_e32 v109, v118, v109
	v_mul_f32_e32 v105, v119, v105
	v_mul_f32_e32 v110, v120, v110
	v_mul_f32_e32 v106, v121, v106
	v_mul_f32_e32 v111, v122, v111
	v_mul_f32_e32 v107, v115, v107
	v_mul_f32_e32 v108, v116, v108
	v_mul_f32_e32 v104, v96, v104
	v_mul_f32_e32 v96, v101, v109
	v_mul_f32_e32 v101, v97, v105
	v_mul_f32_e32 v97, v102, v110
	v_mul_f32_e32 v102, v98, v106
	v_mul_f32_e32 v98, v103, v111
	v_mul_f32_e32 v99, v99, v107
	v_mul_f32_e32 v100, v100, v108
	v_cvt_pk_bf16_f32 v96, v100, v96
	v_cvt_pk_bf16_f32 v97, v97, v98
	v_cvt_pk_bf16_f32 v98, v104, v101
	v_cvt_pk_bf16_f32 v99, v102, v99
	global_store_dwordx4 v[112:113], v[96:99], off
	s_nop 1
	v_mov_b32_e32 v98, v205
	s_nop 0
	v_or_b32_e32 v96, 32, v144
	v_mad_i64_i32 v[96:97], s[40:41], v96, s52, v[146:147]
	v_lshl_add_u64 v[96:97], v[96:97], 0, v[148:149]
	v_mul_f32_e32 v99, v98, v98
	v_mul_f32_e32 v98, 0xbfb8aa3b, v98
	v_mul_f32_e32 v100, v92, v99
	v_mul_f32_e32 v101, v88, v99
	v_mul_f32_e32 v88, v88, v98
	v_mul_f32_e32 v102, v93, v99
	v_mul_f32_e32 v93, v93, v98
	v_mul_f32_e32 v103, v89, v99
	v_mul_f32_e32 v89, v89, v98
	v_mul_f32_e32 v104, v94, v99
	v_mul_f32_e32 v94, v94, v98
	v_mul_f32_e32 v105, v90, v99
	v_mul_f32_e32 v90, v90, v98
	v_mul_f32_e32 v106, v95, v99
	v_mul_f32_e32 v95, v95, v98
	v_mul_f32_e32 v99, v91, v99
	v_mul_f32_e32 v91, v91, v98
	v_mul_f32_e32 v92, v92, v98
	v_exp_f32_e32 v88, v88
	v_exp_f32_e32 v93, v93
	v_exp_f32_e32 v89, v89
	v_exp_f32_e32 v94, v94
	v_exp_f32_e32 v90, v90
	v_exp_f32_e32 v95, v95
	v_exp_f32_e32 v91, v91
	v_exp_f32_e32 v92, v92
	v_add_f32_e32 v88, 1.0, v88
	v_add_f32_e32 v93, 1.0, v93
	v_add_f32_e32 v89, 1.0, v89
	v_add_f32_e32 v94, 1.0, v94
	v_add_f32_e32 v90, 1.0, v90
	v_add_f32_e32 v95, 1.0, v95
	v_add_f32_e32 v91, 1.0, v91
	v_add_f32_e32 v92, 1.0, v92
	v_rcp_f32_e32 v88, v88
	v_rcp_f32_e32 v93, v93
	v_rcp_f32_e32 v89, v89
	v_rcp_f32_e32 v94, v94
	v_rcp_f32_e32 v90, v90
	v_rcp_f32_e32 v95, v95
	v_rcp_f32_e32 v91, v91
	v_rcp_f32_e32 v92, v92
	v_mul_f32_e32 v88, v101, v88
	v_mul_f32_e32 v93, v102, v93
	v_mul_f32_e32 v89, v103, v89
	v_mul_f32_e32 v94, v104, v94
	v_mul_f32_e32 v90, v105, v90
	v_mul_f32_e32 v95, v106, v95
	v_mul_f32_e32 v91, v99, v91
	v_mul_f32_e32 v92, v100, v92
	v_mul_f32_e32 v88, v80, v88
	v_mul_f32_e32 v80, v85, v93
	v_mul_f32_e32 v85, v81, v89
	v_mul_f32_e32 v81, v86, v94
	v_mul_f32_e32 v86, v82, v90
	v_mul_f32_e32 v82, v87, v95
	v_mul_f32_e32 v83, v83, v91
	v_mul_f32_e32 v84, v84, v92
	v_cvt_pk_bf16_f32 v80, v84, v80
	v_cvt_pk_bf16_f32 v81, v81, v82
	v_cvt_pk_bf16_f32 v82, v88, v85
	v_cvt_pk_bf16_f32 v83, v86, v83
	global_store_dwordx4 v[96:97], v[80:83], off
	s_nop 1
	v_mov_b32_e32 v82, v206
	s_nop 0
	v_or_b32_e32 v80, 48, v144
	v_mad_i64_i32 v[80:81], s[40:41], v80, s52, v[146:147]
	v_lshl_add_u64 v[80:81], v[80:81], 0, v[148:149]
	v_mul_f32_e32 v83, v82, v82
	v_mul_f32_e32 v82, 0xbfb8aa3b, v82
	v_mul_f32_e32 v84, v76, v83
	v_mul_f32_e32 v85, v72, v83
	v_mul_f32_e32 v72, v72, v82
	v_mul_f32_e32 v86, v77, v83
	v_mul_f32_e32 v77, v77, v82
	v_mul_f32_e32 v87, v73, v83
	v_mul_f32_e32 v73, v73, v82
	v_mul_f32_e32 v88, v78, v83
	v_mul_f32_e32 v78, v78, v82
	v_mul_f32_e32 v89, v74, v83
	v_mul_f32_e32 v74, v74, v82
	v_mul_f32_e32 v90, v79, v83
	v_mul_f32_e32 v79, v79, v82
	v_mul_f32_e32 v83, v75, v83
	v_mul_f32_e32 v75, v75, v82
	v_mul_f32_e32 v76, v76, v82
	v_exp_f32_e32 v72, v72
	v_exp_f32_e32 v77, v77
	v_exp_f32_e32 v73, v73
	v_exp_f32_e32 v78, v78
	v_exp_f32_e32 v74, v74
	v_exp_f32_e32 v79, v79
	v_exp_f32_e32 v75, v75
	v_exp_f32_e32 v76, v76
	v_add_f32_e32 v72, 1.0, v72
	v_add_f32_e32 v77, 1.0, v77
	v_add_f32_e32 v73, 1.0, v73
	v_add_f32_e32 v78, 1.0, v78
	v_add_f32_e32 v74, 1.0, v74
	v_add_f32_e32 v79, 1.0, v79
	v_add_f32_e32 v75, 1.0, v75
	v_add_f32_e32 v76, 1.0, v76
	v_rcp_f32_e32 v72, v72
	v_rcp_f32_e32 v77, v77
	v_rcp_f32_e32 v73, v73
	v_rcp_f32_e32 v78, v78
	v_rcp_f32_e32 v74, v74
	v_rcp_f32_e32 v79, v79
	v_rcp_f32_e32 v75, v75
	v_rcp_f32_e32 v76, v76
	v_mul_f32_e32 v72, v85, v72
	v_mul_f32_e32 v77, v86, v77
	v_mul_f32_e32 v73, v87, v73
	v_mul_f32_e32 v78, v88, v78
	v_mul_f32_e32 v74, v89, v74
	v_mul_f32_e32 v79, v90, v79
	v_mul_f32_e32 v75, v83, v75
	v_mul_f32_e32 v76, v84, v76
	v_mul_f32_e32 v72, v64, v72
	v_mul_f32_e32 v64, v69, v77
	v_mul_f32_e32 v69, v65, v73
	v_mul_f32_e32 v65, v70, v78
	v_mul_f32_e32 v70, v66, v74
	v_mul_f32_e32 v66, v71, v79
	v_mul_f32_e32 v67, v67, v75
	v_mul_f32_e32 v68, v68, v76
	v_cvt_pk_bf16_f32 v64, v68, v64
	v_cvt_pk_bf16_f32 v65, v65, v66
; __device__ __forceinline__ float fast_rcp(float x) { return __builtin_amdgcn_rcpf(x); }
; __device__ __forceinline__ float fast_exp2(float x) { return __builtin_amdgcn_exp2f(x); }
; __device__ __forceinline__ u32x4 pack8(f32x4 v0, f32x4 v1) { u32x4 w; w.x = cvt_pk_bf16(v0[0], v0[1]); w.y = cvt_pk_bf16(v0[2], v0[3]); w.z = cvt_pk_bf16(v1[0], v1[1]); w.w = cvt_pk_bf16(v1[2], v1[3]); return w; }
;     __device__ __forceinline__ void operator()(const f32x4 (&acc)[2][2][4][2], const Unit& u, int wr, int wc, int fr, int fq) const {
;     ...
;             for (int m = 0; m < 4; ++m) { bf16_t* rowp = O + (size_t)(row0 + ai * HALF + m * 16) * DFF + col0;
;                 const float r = rs[row0 + ai * HALF + m * 16], r2 = r * r;
;                 f32x4 h0, h1;
; #pragma unroll
;                 for (int j = 0; j < 4; ++j) {
;                     const float g0 = acc[ai][0][m][0][j], g1 = acc[ai][0][m][1][j];
;                     h0[j] = g0 * r2 * fast_rcp(1.0f + fast_exp2(g0 * (-LOG2E * r))) * acc[ai][1][m][0][j];
;                     h1[j] = g1 * r2 * fast_rcp(1.0f + fast_exp2(g1 * (-LOG2E * r))) * acc[ai][1][m][1][j]; }
;                 *(u32x4*)rowp = pack8(h0, h1); }
	v_cvt_pk_bf16_f32 v66, v72, v69
	v_cvt_pk_bf16_f32 v67, v70, v67
	global_store_dwordx4 v[80:81], v[64:67], off
	s_nop 1
	v_mov_b32_e32 v66, v207
	s_nop 0
	v_add_u32_e32 v64, 0x80, v144
	v_mad_i64_i32 v[64:65], s[40:41], v64, s52, v[146:147]
	v_lshl_add_u64 v[64:65], v[64:65], 0, v[148:149]
	v_mul_f32_e32 v67, v66, v66
	v_mul_f32_e32 v66, 0xbfb8aa3b, v66
	v_mul_f32_e32 v68, v60, v67
	v_mul_f32_e32 v69, v56, v67
	v_mul_f32_e32 v56, v56, v66
	v_mul_f32_e32 v70, v61, v67
	v_mul_f32_e32 v61, v61, v66
	v_mul_f32_e32 v71, v57, v67
	v_mul_f32_e32 v57, v57, v66
	v_mul_f32_e32 v72, v62, v67
	v_mul_f32_e32 v62, v62, v66
	v_mul_f32_e32 v73, v58, v67
	v_mul_f32_e32 v58, v58, v66
	v_mul_f32_e32 v74, v63, v67
	v_mul_f32_e32 v63, v63, v66
	v_mul_f32_e32 v67, v59, v67
	v_mul_f32_e32 v59, v59, v66
	v_mul_f32_e32 v60, v60, v66
	v_exp_f32_e32 v56, v56
	v_exp_f32_e32 v61, v61
	v_exp_f32_e32 v57, v57
	v_exp_f32_e32 v62, v62
	v_exp_f32_e32 v58, v58
	v_exp_f32_e32 v63, v63
	v_exp_f32_e32 v59, v59
	v_exp_f32_e32 v60, v60
	v_add_f32_e32 v56, 1.0, v56
	v_add_f32_e32 v61, 1.0, v61
	v_add_f32_e32 v57, 1.0, v57
	v_add_f32_e32 v62, 1.0, v62
	v_add_f32_e32 v58, 1.0, v58
	v_add_f32_e32 v63, 1.0, v63
	v_add_f32_e32 v59, 1.0, v59
	v_add_f32_e32 v60, 1.0, v60
	v_rcp_f32_e32 v56, v56
	v_rcp_f32_e32 v61, v61
	v_rcp_f32_e32 v57, v57
	v_rcp_f32_e32 v62, v62
	v_rcp_f32_e32 v58, v58
	v_rcp_f32_e32 v63, v63
	v_rcp_f32_e32 v59, v59
	v_rcp_f32_e32 v60, v60
	v_mul_f32_e32 v56, v69, v56
	v_mul_f32_e32 v61, v70, v61
	v_mul_f32_e32 v57, v71, v57
	v_mul_f32_e32 v62, v72, v62
	v_mul_f32_e32 v58, v73, v58
	v_mul_f32_e32 v63, v74, v63
	v_mul_f32_e32 v59, v67, v59
	v_mul_f32_e32 v60, v68, v60
	v_mul_f32_e32 v56, v48, v56
	v_mul_f32_e32 v48, v53, v61
	v_mul_f32_e32 v53, v49, v57
	v_mul_f32_e32 v49, v54, v62
	v_mul_f32_e32 v54, v50, v58
	v_mul_f32_e32 v50, v55, v63
	v_mul_f32_e32 v51, v51, v59
	v_mul_f32_e32 v52, v52, v60
	v_cvt_pk_bf16_f32 v48, v52, v48
	v_cvt_pk_bf16_f32 v49, v49, v50
	v_cvt_pk_bf16_f32 v50, v56, v53
	v_cvt_pk_bf16_f32 v51, v54, v51
	global_store_dwordx4 v[64:65], v[48:51], off
	s_nop 1
	v_mov_b32_e32 v50, v208
	s_nop 0
	v_add_u32_e32 v48, 0x90, v144
	v_mad_i64_i32 v[48:49], s[40:41], v48, s52, v[146:147]
	v_lshl_add_u64 v[48:49], v[48:49], 0, v[148:149]
	v_mul_f32_e32 v51, v50, v50
	v_mul_f32_e32 v50, 0xbfb8aa3b, v50
	v_mul_f32_e32 v52, v44, v51
	v_mul_f32_e32 v53, v40, v51
	v_mul_f32_e32 v40, v40, v50
	v_mul_f32_e32 v54, v45, v51
	v_mul_f32_e32 v45, v45, v50
	v_mul_f32_e32 v55, v41, v51
	v_mul_f32_e32 v41, v41, v50
	v_mul_f32_e32 v56, v46, v51
	v_mul_f32_e32 v46, v46, v50
	v_mul_f32_e32 v57, v42, v51
	v_mul_f32_e32 v42, v42, v50
	v_mul_f32_e32 v58, v47, v51
	v_mul_f32_e32 v47, v47, v50
	v_mul_f32_e32 v51, v43, v51
	v_mul_f32_e32 v43, v43, v50
	v_mul_f32_e32 v44, v44, v50
	v_exp_f32_e32 v40, v40
	v_exp_f32_e32 v45, v45
	v_exp_f32_e32 v41, v41
	v_exp_f32_e32 v46, v46
	v_exp_f32_e32 v42, v42
	v_exp_f32_e32 v47, v47
	v_exp_f32_e32 v43, v43
	v_exp_f32_e32 v44, v44
	v_add_f32_e32 v40, 1.0, v40
	v_add_f32_e32 v45, 1.0, v45
	v_add_f32_e32 v41, 1.0, v41
	v_add_f32_e32 v46, 1.0, v46
	v_add_f32_e32 v42, 1.0, v42
	v_add_f32_e32 v47, 1.0, v47
	v_add_f32_e32 v43, 1.0, v43
	v_add_f32_e32 v44, 1.0, v44
	v_rcp_f32_e32 v40, v40
	v_rcp_f32_e32 v45, v45
	v_rcp_f32_e32 v41, v41
	v_rcp_f32_e32 v46, v46
	v_rcp_f32_e32 v42, v42
	v_rcp_f32_e32 v47, v47
	v_rcp_f32_e32 v43, v43
	v_rcp_f32_e32 v44, v44
	v_mul_f32_e32 v40, v53, v40
	v_mul_f32_e32 v45, v54, v45
	v_mul_f32_e32 v41, v55, v41
	v_mul_f32_e32 v46, v56, v46
	v_mul_f32_e32 v42, v57, v42
	v_mul_f32_e32 v47, v58, v47
	v_mul_f32_e32 v43, v51, v43
	v_mul_f32_e32 v44, v52, v44
	v_mul_f32_e32 v40, v32, v40
	v_mul_f32_e32 v32, v37, v45
	v_mul_f32_e32 v37, v33, v41
	v_mul_f32_e32 v33, v38, v46
	v_mul_f32_e32 v38, v34, v42
	v_mul_f32_e32 v34, v39, v47
	v_mul_f32_e32 v35, v35, v43
	v_mul_f32_e32 v36, v36, v44
	v_cvt_pk_bf16_f32 v32, v36, v32
	v_cvt_pk_bf16_f32 v33, v33, v34
	v_cvt_pk_bf16_f32 v34, v40, v37
	v_cvt_pk_bf16_f32 v35, v38, v35
	global_store_dwordx4 v[48:49], v[32:35], off
; __device__ __forceinline__ float fast_rcp(float x) { return __builtin_amdgcn_rcpf(x); }
; __device__ __forceinline__ float fast_exp2(float x) { return __builtin_amdgcn_exp2f(x); }
; #define PG8_WAIT_V(n) asm volatile("s_waitcnt vmcnt(" #n ")" ::: "memory")
; #define PG8_BAR __builtin_amdgcn_s_barrier()
; __device__ __forceinline__ u32x4 pack8(f32x4 v0, f32x4 v1) { u32x4 w; w.x = cvt_pk_bf16(v0[0], v0[1]); w.y = cvt_pk_bf16(v0[2], v0[3]); w.z = cvt_pk_bf16(v1[0], v1[1]); w.w = cvt_pk_bf16(v1[2], v1[3]); return w; }
; template <class Epi>
; __device__ __forceinline__ void gemm_phase(LAS unsigned char* lds, const Gemm g, const StaticOrder& S, const Epi& E) {
;     ...
;         cur = nxt; cA = nA; cB = nB; ++ui;
;     }
;     PG8_WAIT_V(0);
;     if (wr == 0) PG8_BAR;
;     PG8_BAR;
;     __device__ __forceinline__ void operator()(const f32x4 (&acc)[2][2][4][2], const Unit& u, int wr, int wc, int fr, int fq) const {
;     ...
;             for (int m = 0; m < 4; ++m) { bf16_t* rowp = O + (size_t)(row0 + ai * HALF + m * 16) * DFF + col0;
;                 const float r = rs[row0 + ai * HALF + m * 16], r2 = r * r;
;                 f32x4 h0, h1;
; #pragma unroll
;                 for (int j = 0; j < 4; ++j) {
;                     const float g0 = acc[ai][0][m][0][j], g1 = acc[ai][0][m][1][j];
;                     h0[j] = g0 * r2 * fast_rcp(1.0f + fast_exp2(g0 * (-LOG2E * r))) * acc[ai][1][m][0][j];
;                     h1[j] = g1 * r2 * fast_rcp(1.0f + fast_exp2(g1 * (-LOG2E * r))) * acc[ai][1][m][1][j]; }
;                 *(u32x4*)rowp = pack8(h0, h1); }
	s_nop 1
	v_mov_b32_e32 v34, v209
	s_nop 0
	v_add_u32_e32 v32, 0xa0, v144
	v_mad_i64_i32 v[32:33], s[40:41], v32, s52, v[146:147]
	v_lshl_add_u64 v[32:33], v[32:33], 0, v[148:149]
	s_mov_b64 s[40:41], s[34:35]
	v_mul_f32_e32 v35, v34, v34
	v_mul_f32_e32 v34, 0xbfb8aa3b, v34
	v_mul_f32_e32 v36, v28, v35
	v_mul_f32_e32 v37, v24, v35
	v_mul_f32_e32 v24, v24, v34
	v_mul_f32_e32 v38, v29, v35
	v_mul_f32_e32 v29, v29, v34
	v_mul_f32_e32 v39, v25, v35
	v_mul_f32_e32 v25, v25, v34
	v_mul_f32_e32 v40, v30, v35
	v_mul_f32_e32 v30, v30, v34
	v_mul_f32_e32 v41, v26, v35
	v_mul_f32_e32 v26, v26, v34
	v_mul_f32_e32 v42, v31, v35
	v_mul_f32_e32 v31, v31, v34
	v_mul_f32_e32 v35, v27, v35
	v_mul_f32_e32 v27, v27, v34
	v_mul_f32_e32 v28, v28, v34
	v_exp_f32_e32 v24, v24
	v_exp_f32_e32 v29, v29
	v_exp_f32_e32 v25, v25
	v_exp_f32_e32 v30, v30
	v_exp_f32_e32 v26, v26
	v_exp_f32_e32 v31, v31
	v_exp_f32_e32 v27, v27
	v_exp_f32_e32 v28, v28
	v_add_f32_e32 v24, 1.0, v24
	v_add_f32_e32 v29, 1.0, v29
	v_add_f32_e32 v25, 1.0, v25
	v_add_f32_e32 v30, 1.0, v30
	v_add_f32_e32 v26, 1.0, v26
	v_add_f32_e32 v31, 1.0, v31
	v_add_f32_e32 v27, 1.0, v27
	v_add_f32_e32 v28, 1.0, v28
	v_rcp_f32_e32 v24, v24
	v_rcp_f32_e32 v29, v29
	v_rcp_f32_e32 v25, v25
	v_rcp_f32_e32 v30, v30
	v_rcp_f32_e32 v26, v26
	v_rcp_f32_e32 v31, v31
	v_rcp_f32_e32 v27, v27
	v_rcp_f32_e32 v28, v28
	v_mul_f32_e32 v24, v37, v24
	v_mul_f32_e32 v29, v38, v29
	v_mul_f32_e32 v25, v39, v25
	v_mul_f32_e32 v30, v40, v30
	v_mul_f32_e32 v26, v41, v26
	v_mul_f32_e32 v31, v42, v31
	v_mul_f32_e32 v27, v35, v27
	v_mul_f32_e32 v28, v36, v28
	v_mul_f32_e32 v24, v16, v24
	v_mul_f32_e32 v16, v21, v29
	v_mul_f32_e32 v21, v17, v25
	v_mul_f32_e32 v17, v22, v30
	v_mul_f32_e32 v22, v18, v26
	v_mul_f32_e32 v18, v23, v31
	v_mul_f32_e32 v19, v19, v27
	v_mul_f32_e32 v20, v20, v28
	v_cvt_pk_bf16_f32 v16, v20, v16
	v_cvt_pk_bf16_f32 v17, v17, v18
	v_cvt_pk_bf16_f32 v18, v24, v21
	v_cvt_pk_bf16_f32 v19, v22, v19
	global_store_dwordx4 v[32:33], v[16:19], off
	s_nop 1
	v_mov_b32_e32 v18, v210
	s_nop 0
	v_add_u32_e32 v16, 0xb0, v144
	v_mad_i64_i32 v[16:17], s[6:7], v16, s52, v[146:147]
	v_lshl_add_u64 v[16:17], v[16:17], 0, v[148:149]
	v_mul_f32_e32 v19, v18, v18
	v_mul_f32_e32 v18, 0xbfb8aa3b, v18
	v_mul_f32_e32 v20, v12, v19
	v_mul_f32_e32 v21, v8, v19
	v_mul_f32_e32 v8, v8, v18
	v_mul_f32_e32 v22, v13, v19
	v_mul_f32_e32 v13, v13, v18
	v_mul_f32_e32 v23, v9, v19
	v_mul_f32_e32 v9, v9, v18
	v_mul_f32_e32 v24, v14, v19
	v_mul_f32_e32 v14, v14, v18
	v_mul_f32_e32 v25, v10, v19
	v_mul_f32_e32 v10, v10, v18
	v_mul_f32_e32 v26, v15, v19
	v_mul_f32_e32 v15, v15, v18
	v_mul_f32_e32 v19, v11, v19
	v_mul_f32_e32 v11, v11, v18
	v_mul_f32_e32 v12, v12, v18
	v_exp_f32_e32 v8, v8
	v_exp_f32_e32 v13, v13
	v_exp_f32_e32 v9, v9
	v_exp_f32_e32 v14, v14
	v_exp_f32_e32 v10, v10
	v_exp_f32_e32 v15, v15
	v_exp_f32_e32 v11, v11
	v_exp_f32_e32 v12, v12
	v_add_f32_e32 v8, 1.0, v8
	v_add_f32_e32 v13, 1.0, v13
	v_add_f32_e32 v9, 1.0, v9
	v_add_f32_e32 v14, 1.0, v14
	v_add_f32_e32 v10, 1.0, v10
	v_add_f32_e32 v15, 1.0, v15
	v_add_f32_e32 v11, 1.0, v11
	v_add_f32_e32 v12, 1.0, v12
	v_rcp_f32_e32 v8, v8
	v_rcp_f32_e32 v13, v13
	v_rcp_f32_e32 v9, v9
	v_rcp_f32_e32 v14, v14
	v_rcp_f32_e32 v10, v10
	v_rcp_f32_e32 v15, v15
	v_rcp_f32_e32 v11, v11
	v_rcp_f32_e32 v12, v12
	v_mul_f32_e32 v8, v21, v8
	v_mul_f32_e32 v13, v22, v13
	v_mul_f32_e32 v9, v23, v9
	v_mul_f32_e32 v14, v24, v14
	v_mul_f32_e32 v10, v25, v10
	v_mul_f32_e32 v15, v26, v15
	v_mul_f32_e32 v11, v19, v11
	v_mul_f32_e32 v12, v20, v12
	v_mul_f32_e32 v8, v0, v8
	v_mul_f32_e32 v0, v5, v13
	v_mul_f32_e32 v5, v1, v9
	v_mul_f32_e32 v1, v6, v14
	v_mul_f32_e32 v6, v2, v10
	v_mul_f32_e32 v2, v7, v15
	v_mul_f32_e32 v3, v3, v11
	v_mul_f32_e32 v4, v4, v12
	v_cvt_pk_bf16_f32 v0, v4, v0
	v_cvt_pk_bf16_f32 v1, v1, v2
	v_cvt_pk_bf16_f32 v2, v8, v5
	v_cvt_pk_bf16_f32 v3, v6, v3
	global_store_dwordx4 v[16:17], v[0:3], off
	s_cbranch_vccz .LBB0_793
	s_waitcnt vmcnt(0)
	s_cmpk_gt_u32 s10, 0xff
	s_cbranch_scc1 .LBB0_800
	s_barrier

; #define PG8_STAGE(bufoff, gbase, voff) do { _Pragma("unroll") for (int _i = 0; _i < 2; ++_i) \
;         __builtin_amdgcn_global_load_lds((const unsigned*)((const char*)(gbase) + (voff)[_i]), (LAS unsigned*)(lds + (bufoff) + ldsw + _i * 8192), 16, 0, 0); } while (0)
; #define PG8_LDA(dst, b, h) do { _Pragma("unroll") for (int m = 0; m < 4; ++m) _Pragma("unroll") for (int k = 0; k < 2; ++k) dst[m][k] = *(const LAS bf16x8*)(lds + PG8_SA(b, h) + aoff + m * 2048 + k * 1024); } while (0)
; #define PG8_LDB(dst, b, h) do { _Pragma("unroll") for (int n = 0; n < 2; ++n) _Pragma("unroll") for (int k = 0; k < 2; ++k) dst[n][k] = *(const LAS bf16x8*)(lds + PG8_SB(b, h) + boff + n * 2048 + k * 1024); } while (0)
; #define PG8_MMA(ai, bj, At, Bt) do { __builtin_amdgcn_s_setprio(1); _Pragma("unroll") for (int m = 0; m < 4; ++m) _Pragma("unroll") for (int n = 0; n < 2; ++n) _Pragma("unroll") for (int k = 0; k < 2; ++k) \
;         acc[ai][bj][m][n] = __builtin_amdgcn_mfma_f32_16x16x32_bf16(Bt[n][k], At[m][k], acc[ai][bj][m][n], 0, 0, 0); __builtin_amdgcn_s_setprio(0); } while (0)
; #define PG8_WAIT_V(n) asm volatile("s_waitcnt vmcnt(" #n ")" ::: "memory")
; #define PG8_WAIT_L(n) asm volatile("s_waitcnt lgkmcnt(" #n ")" ::: "memory")
; template <class Epi>
; __device__ __forceinline__ void gemm_phase(LAS unsigned char* lds, const Gemm g, const StaticOrder& S, const Epi& E) {
;     ...
;         for (int t = 0; t < nt; t += 2) {
;             const bool last = (t == nt - 2);
;             const char* a1 = cA + (size_t)(t + 1) * kstep;
;             const char* a2 = last ? nA : cA + (size_t)(t + 2) * kstep; const char* b2 = last ? nB : cB + (size_t)(t + 2) * kstep;
;             const char* a3 = a2 + kstep; const char* b3 = b2 + kstep;
;             PG8_LDB(B0, 0, 0); PG8_SCHED; PG8_LDA(At, 0, 0); PG8_STAGE(PG8_SA(1, 1), a1 + hstep, voffA);
;             PG8_WAIT_L(8); PG8_BAR; PG8_WAIT_L(0); PG8_MMA(0, 0, At, B0); PG8_BAR; PG8_SCHED;
;             PG8_LDB(B1, 0, 1); PG8_STAGE(PG8_SB(0, 0), b2, voffB);
;             PG8_BAR; PG8_WAIT_L(0); PG8_MMA(0, 1, At, B1); PG8_BAR;
;             PG8_LDA(At, 0, 1); PG8_STAGE(PG8_SA(0, 0), a2, voffA);
;             PG8_BAR; PG8_WAIT_L(0); PG8_MMA(1, 0, At, B0); PG8_BAR; PG8_SCHED;
;             PG8_STAGE(PG8_SB(0, 1), b2 + hstep, voffB);
;             PG8_WAIT_V(6); PG8_BAR; PG8_MMA(1, 1, At, B1); PG8_BAR;
.LBB0_864:
	ds_read_b128 v[148:151], v145
	ds_read_b128 v[152:155], v145 offset:1024
	ds_read_b128 v[160:163], v145 offset:2048
	ds_read_b128 v[164:167], v145 offset:3072
	s_add_u32 s44, s42, 0x100
	s_addc_u32 s45, s43, 0
	s_cmpk_eq_i32 s67, 0x54
	s_cselect_b32 s49, s41, s45
	s_cselect_b32 s48, s40, s44
	s_cselect_b32 s47, s7, s66
	s_cselect_b32 s46, s6, s65
	s_add_i32 m0, s28, 0xc000
	ds_read_b128 v[168:171], v146
	ds_read_b128 v[172:175], v146 offset:1024
	ds_read_b128 v[176:179], v146 offset:2048
	ds_read_b128 v[180:183], v146 offset:3072
	ds_read_b128 v[184:187], v146 offset:4096
	ds_read_b128 v[188:191], v146 offset:5120
	ds_read_b128 v[192:195], v146 offset:6144
	ds_read_b128 v[196:199], v146 offset:7168
	global_load_lds_dwordx4 v136, s[42:43]
	s_add_i32 m0, s28, 0xe000
	s_nop 0
	global_load_lds_dwordx4 v138, s[42:43]
	s_waitcnt lgkmcnt(8)
	s_barrier
	s_waitcnt lgkmcnt(0)
	s_waitcnt lgkmcnt(0)
	v_mfma_f32_16x16x32_bf16 v[124:127], v[148:151], v[168:171], v[124:127]
	v_mfma_f32_16x16x32_bf16 v[120:123], v[160:163], v[168:171], v[120:123]
	v_mfma_f32_16x16x32_bf16 v[112:115], v[148:151], v[176:179], v[112:115]
	v_mfma_f32_16x16x32_bf16 v[104:107], v[160:163], v[176:179], v[104:107]
	v_mfma_f32_16x16x32_bf16 v[96:99], v[148:151], v[184:187], v[96:99]
	v_mfma_f32_16x16x32_bf16 v[88:91], v[160:163], v[184:187], v[88:91]
	v_mfma_f32_16x16x32_bf16 v[80:83], v[148:151], v[192:195], v[80:83]
	v_mfma_f32_16x16x32_bf16 v[72:75], v[160:163], v[192:195], v[72:75]
	v_mfma_f32_16x16x32_bf16 v[124:127], v[152:155], v[172:175], v[124:127]
	v_mfma_f32_16x16x32_bf16 v[120:123], v[164:167], v[172:175], v[120:123]
	v_mfma_f32_16x16x32_bf16 v[112:115], v[152:155], v[180:183], v[112:115]
	v_mfma_f32_16x16x32_bf16 v[104:107], v[164:167], v[180:183], v[104:107]
	v_mfma_f32_16x16x32_bf16 v[96:99], v[152:155], v[188:191], v[96:99]
	v_mfma_f32_16x16x32_bf16 v[88:91], v[164:167], v[188:191], v[88:91]
	v_mfma_f32_16x16x32_bf16 v[80:83], v[152:155], v[196:199], v[80:83]
	v_mfma_f32_16x16x32_bf16 v[72:75], v[164:167], v[196:199], v[72:75]
	s_barrier
	s_add_i32 s42, s55, s23
	s_add_u32 s98, s46, s2
	s_addc_u32 s99, s47, s3
	s_mov_b32 m0, s42
	ds_read_b128 v[200:203], v147
	ds_read_b128 v[204:207], v147 offset:1024
	ds_read_b128 v[208:211], v147 offset:2048
	ds_read_b128 v[212:215], v147 offset:3072
	global_load_lds_dwordx4 v132, s[46:47]
	s_add_i32 m0, s42, 0x2000
	s_nop 0
	global_load_lds_dwordx4 v128, s[46:47]
	s_barrier
	s_waitcnt lgkmcnt(0)
	s_waitcnt lgkmcnt(0)
	v_mfma_f32_16x16x32_bf16 v[116:119], v[200:203], v[168:171], v[116:119]
	v_mfma_f32_16x16x32_bf16 v[108:111], v[208:211], v[168:171], v[108:111]
	v_mfma_f32_16x16x32_bf16 v[100:103], v[200:203], v[176:179], v[100:103]
	v_mfma_f32_16x16x32_bf16 v[92:95], v[208:211], v[176:179], v[92:95]
	v_mfma_f32_16x16x32_bf16 v[84:87], v[200:203], v[184:187], v[84:87]
	v_mfma_f32_16x16x32_bf16 v[76:79], v[208:211], v[184:187], v[76:79]
	v_mfma_f32_16x16x32_bf16 v[68:71], v[200:203], v[192:195], v[68:71]
	v_mfma_f32_16x16x32_bf16 v[64:67], v[208:211], v[192:195], v[64:67]
	v_mfma_f32_16x16x32_bf16 v[116:119], v[204:207], v[172:175], v[116:119]
	v_mfma_f32_16x16x32_bf16 v[108:111], v[212:215], v[172:175], v[108:111]
	v_mfma_f32_16x16x32_bf16 v[100:103], v[204:207], v[180:183], v[100:103]
	v_mfma_f32_16x16x32_bf16 v[92:95], v[212:215], v[180:183], v[92:95]
	v_mfma_f32_16x16x32_bf16 v[84:87], v[204:207], v[188:191], v[84:87]
	v_mfma_f32_16x16x32_bf16 v[76:79], v[212:215], v[188:191], v[76:79]
	v_mfma_f32_16x16x32_bf16 v[68:71], v[204:207], v[196:199], v[68:71]
	v_mfma_f32_16x16x32_bf16 v[64:67], v[212:215], v[196:199], v[64:67]
	s_mov_b32 m0, s28
	s_add_u32 s100, s48, s2
	s_addc_u32 s101, s49, s3
	s_barrier
	ds_read_b128 v[168:171], v146 offset:16384
	ds_read_b128 v[172:175], v146 offset:17408
	ds_read_b128 v[176:179], v146 offset:18432
	ds_read_b128 v[180:183], v146 offset:19456
	ds_read_b128 v[184:187], v146 offset:20480
	ds_read_b128 v[188:191], v146 offset:21504
	ds_read_b128 v[192:195], v146 offset:22528
	ds_read_b128 v[196:199], v146 offset:23552
	global_load_lds_dwordx4 v134, s[48:49]
	s_mov_b32 m0, s29
	s_nop 0
	global_load_lds_dwordx4 v130, s[48:49]
	s_barrier
	s_waitcnt lgkmcnt(0)
	s_waitcnt lgkmcnt(0)
	v_mfma_f32_16x16x32_bf16 v[60:63], v[148:151], v[168:171], v[60:63]
	v_mfma_f32_16x16x32_bf16 v[56:59], v[160:163], v[168:171], v[56:59]
	v_mfma_f32_16x16x32_bf16 v[52:55], v[148:151], v[176:179], v[52:55]
	v_mfma_f32_16x16x32_bf16 v[44:47], v[160:163], v[176:179], v[44:47]
	v_mfma_f32_16x16x32_bf16 v[36:39], v[148:151], v[184:187], v[36:39]
	v_mfma_f32_16x16x32_bf16 v[28:31], v[160:163], v[184:187], v[28:31]
	v_mfma_f32_16x16x32_bf16 v[20:23], v[148:151], v[192:195], v[20:23]
	v_mfma_f32_16x16x32_bf16 v[12:15], v[160:163], v[192:195], v[12:15]
	v_mfma_f32_16x16x32_bf16 v[60:63], v[152:155], v[172:175], v[60:63]
	v_mfma_f32_16x16x32_bf16 v[56:59], v[164:167], v[172:175], v[56:59]
	v_mfma_f32_16x16x32_bf16 v[52:55], v[152:155], v[180:183], v[52:55]
	v_mfma_f32_16x16x32_bf16 v[44:47], v[164:167], v[180:183], v[44:47]
	v_mfma_f32_16x16x32_bf16 v[36:39], v[152:155], v[188:191], v[36:39]
	v_mfma_f32_16x16x32_bf16 v[28:31], v[164:167], v[188:191], v[28:31]
	v_mfma_f32_16x16x32_bf16 v[20:23], v[152:155], v[196:199], v[20:23]
	v_mfma_f32_16x16x32_bf16 v[12:15], v[164:167], v[196:199], v[12:15]
	s_barrier
	s_add_u32 s42, s46, 0x160000
	s_addc_u32 s43, s47, 0
	s_add_i32 s68, s56, s23
	s_mov_b32 m0, s68
	s_nop 0
	global_load_lds_dwordx4 v132, s[42:43]
	s_add_i32 m0, s68, 0x2000
	s_nop 0
	global_load_lds_dwordx4 v128, s[42:43]
	s_waitcnt vmcnt(6)
	s_barrier
; #define PG8_STAGE(bufoff, gbase, voff) do { _Pragma("unroll") for (int _i = 0; _i < 2; ++_i) \
;         __builtin_amdgcn_global_load_lds((const unsigned*)((const char*)(gbase) + (voff)[_i]), (LAS unsigned*)(lds + (bufoff) + ldsw + _i * 8192), 16, 0, 0); } while (0)
; #define PG8_LDA(dst, b, h) do { _Pragma("unroll") for (int m = 0; m < 4; ++m) _Pragma("unroll") for (int k = 0; k < 2; ++k) dst[m][k] = *(const LAS bf16x8*)(lds + PG8_SA(b, h) + aoff + m * 2048 + k * 1024); } while (0)
; #define PG8_LDB(dst, b, h) do { _Pragma("unroll") for (int n = 0; n < 2; ++n) _Pragma("unroll") for (int k = 0; k < 2; ++k) dst[n][k] = *(const LAS bf16x8*)(lds + PG8_SB(b, h) + boff + n * 2048 + k * 1024); } while (0)
; #define PG8_MMA(ai, bj, At, Bt) do { __builtin_amdgcn_s_setprio(1); _Pragma("unroll") for (int m = 0; m < 4; ++m) _Pragma("unroll") for (int n = 0; n < 2; ++n) _Pragma("unroll") for (int k = 0; k < 2; ++k) \
;         acc[ai][bj][m][n] = __builtin_amdgcn_mfma_f32_16x16x32_bf16(Bt[n][k], At[m][k], acc[ai][bj][m][n], 0, 0, 0); __builtin_amdgcn_s_setprio(0); } while (0)
; #define PG8_WAIT_V(n) asm volatile("s_waitcnt vmcnt(" #n ")" ::: "memory")
; #define PG8_WAIT_L(n) asm volatile("s_waitcnt lgkmcnt(" #n ")" ::: "memory")
; #define PG8_BAR __builtin_amdgcn_s_barrier()
; #define PG8_SCHED __builtin_amdgcn_sched_barrier(0)
; template <class Epi>
; __device__ __forceinline__ void gemm_phase(LAS unsigned char* lds, const Gemm g, const StaticOrder& S, const Epi& E) {
;     ...
;             PG8_WAIT_V(6); PG8_BAR; PG8_MMA(1, 1, At, B1); PG8_BAR;
;             PG8_LDB(B0, 1, 0); PG8_SCHED; PG8_LDA(At, 1, 0); PG8_STAGE(PG8_SA(0, 1), a2 + hstep, voffA);
;             PG8_WAIT_L(8); PG8_BAR; PG8_WAIT_L(0); PG8_MMA(0, 0, At, B0); PG8_BAR; PG8_SCHED;
;             PG8_LDB(B1, 1, 1); PG8_STAGE(PG8_SB(1, 0), b3, voffB);
;             PG8_BAR; PG8_WAIT_L(0); PG8_MMA(0, 1, At, B1); PG8_BAR;
;             PG8_LDA(At, 1, 1); PG8_STAGE(PG8_SA(1, 0), a3, voffA);
	v_mfma_f32_16x16x32_bf16 v[48:51], v[200:203], v[168:171], v[48:51]
	v_mfma_f32_16x16x32_bf16 v[40:43], v[208:211], v[168:171], v[40:43]
	v_mfma_f32_16x16x32_bf16 v[32:35], v[200:203], v[176:179], v[32:35]
	v_mfma_f32_16x16x32_bf16 v[24:27], v[208:211], v[176:179], v[24:27]
	v_mfma_f32_16x16x32_bf16 v[16:19], v[200:203], v[184:187], v[16:19]
	v_mfma_f32_16x16x32_bf16 v[8:11], v[208:211], v[184:187], v[8:11]
	v_mfma_f32_16x16x32_bf16 v[4:7], v[200:203], v[192:195], v[4:7]
	v_mfma_f32_16x16x32_bf16 v[0:3], v[208:211], v[192:195], v[0:3]
	v_mfma_f32_16x16x32_bf16 v[48:51], v[204:207], v[172:175], v[48:51]
	v_mfma_f32_16x16x32_bf16 v[40:43], v[212:215], v[172:175], v[40:43]
	v_mfma_f32_16x16x32_bf16 v[32:35], v[204:207], v[180:183], v[32:35]
	v_mfma_f32_16x16x32_bf16 v[24:27], v[212:215], v[180:183], v[24:27]
	v_mfma_f32_16x16x32_bf16 v[16:19], v[204:207], v[188:191], v[16:19]
	v_mfma_f32_16x16x32_bf16 v[8:11], v[212:215], v[188:191], v[8:11]
	v_mfma_f32_16x16x32_bf16 v[4:7], v[204:207], v[196:199], v[4:7]
	v_mfma_f32_16x16x32_bf16 v[0:3], v[212:215], v[196:199], v[0:3]
	s_add_i32 s68, 0, 0x18000
	v_add_u32_e32 v164, s68, v143
	s_barrier
	ds_read_b128 v[148:151], v164
	ds_read_b128 v[152:155], v164 offset:1024
	ds_read_b128 v[160:163], v164 offset:2048
	ds_read_b128 v[164:167], v164 offset:3072
	s_add_u32 s42, s48, 0x160000
	s_addc_u32 s43, s49, 0
	s_mov_b32 m0, s33
	ds_read_b128 v[168:171], v146 offset:32768
	ds_read_b128 v[172:175], v146 offset:33792
	ds_read_b128 v[176:179], v146 offset:34816
	ds_read_b128 v[180:183], v146 offset:35840
	ds_read_b128 v[184:187], v146 offset:36864
	ds_read_b128 v[188:191], v146 offset:37888
	ds_read_b128 v[192:195], v146 offset:38912
	ds_read_b128 v[196:199], v146 offset:39936
	global_load_lds_dwordx4 v134, s[42:43]
	s_mov_b32 m0, s50
	s_nop 0
	global_load_lds_dwordx4 v130, s[42:43]
	s_waitcnt lgkmcnt(8)
	s_barrier
	s_waitcnt lgkmcnt(0)
	s_waitcnt lgkmcnt(0)
	v_mfma_f32_16x16x32_bf16 v[124:127], v[148:151], v[168:171], v[124:127]
	v_mfma_f32_16x16x32_bf16 v[120:123], v[160:163], v[168:171], v[120:123]
	v_mfma_f32_16x16x32_bf16 v[112:115], v[148:151], v[176:179], v[112:115]
	v_mfma_f32_16x16x32_bf16 v[104:107], v[160:163], v[176:179], v[104:107]
	v_mfma_f32_16x16x32_bf16 v[96:99], v[148:151], v[184:187], v[96:99]
	v_mfma_f32_16x16x32_bf16 v[88:91], v[160:163], v[184:187], v[88:91]
	v_mfma_f32_16x16x32_bf16 v[80:83], v[148:151], v[192:195], v[80:83]
	v_mfma_f32_16x16x32_bf16 v[72:75], v[160:163], v[192:195], v[72:75]
	v_mfma_f32_16x16x32_bf16 v[124:127], v[152:155], v[172:175], v[124:127]
	v_mfma_f32_16x16x32_bf16 v[120:123], v[164:167], v[172:175], v[120:123]
	v_mfma_f32_16x16x32_bf16 v[112:115], v[152:155], v[180:183], v[112:115]
	v_mfma_f32_16x16x32_bf16 v[104:107], v[164:167], v[180:183], v[104:107]
	v_mfma_f32_16x16x32_bf16 v[96:99], v[152:155], v[188:191], v[96:99]
	v_mfma_f32_16x16x32_bf16 v[88:91], v[164:167], v[188:191], v[88:91]
	v_mfma_f32_16x16x32_bf16 v[80:83], v[152:155], v[196:199], v[80:83]
	v_mfma_f32_16x16x32_bf16 v[72:75], v[164:167], v[196:199], v[72:75]
	s_barrier
	s_add_i32 s48, 0, 0x1c000
	s_add_i32 s42, s68, s23
	v_add_u32_e32 v212, s48, v143
	s_mov_b32 m0, s42
	ds_read_b128 v[200:203], v212
	ds_read_b128 v[204:207], v212 offset:1024
	ds_read_b128 v[208:211], v212 offset:2048
	ds_read_b128 v[212:215], v212 offset:3072
	global_load_lds_dwordx4 v132, s[98:99]
	s_add_i32 m0, s42, 0x2000
	s_nop 0
	global_load_lds_dwordx4 v128, s[98:99]
	s_barrier
	s_waitcnt lgkmcnt(0)
	s_waitcnt lgkmcnt(0)
	v_mfma_f32_16x16x32_bf16 v[116:119], v[200:203], v[168:171], v[116:119]
	v_mfma_f32_16x16x32_bf16 v[108:111], v[208:211], v[168:171], v[108:111]
	v_mfma_f32_16x16x32_bf16 v[100:103], v[200:203], v[176:179], v[100:103]
	v_mfma_f32_16x16x32_bf16 v[92:95], v[208:211], v[176:179], v[92:95]
	v_mfma_f32_16x16x32_bf16 v[84:87], v[200:203], v[184:187], v[84:87]
	v_mfma_f32_16x16x32_bf16 v[76:79], v[208:211], v[184:187], v[76:79]
	v_mfma_f32_16x16x32_bf16 v[68:71], v[200:203], v[192:195], v[68:71]
	v_mfma_f32_16x16x32_bf16 v[64:67], v[208:211], v[192:195], v[64:67]
	v_mfma_f32_16x16x32_bf16 v[116:119], v[204:207], v[172:175], v[116:119]
	v_mfma_f32_16x16x32_bf16 v[108:111], v[212:215], v[172:175], v[108:111]
	v_mfma_f32_16x16x32_bf16 v[100:103], v[204:207], v[180:183], v[100:103]
	v_mfma_f32_16x16x32_bf16 v[92:95], v[212:215], v[180:183], v[92:95]
	v_mfma_f32_16x16x32_bf16 v[84:87], v[204:207], v[188:191], v[84:87]
	v_mfma_f32_16x16x32_bf16 v[76:79], v[212:215], v[188:191], v[76:79]
	v_mfma_f32_16x16x32_bf16 v[68:71], v[204:207], v[196:199], v[68:71]
	v_mfma_f32_16x16x32_bf16 v[64:67], v[212:215], v[196:199], v[64:67]
	s_mov_b32 m0, s52
	s_barrier
	ds_read_b128 v[168:171], v146 offset:49152
	ds_read_b128 v[172:175], v146 offset:50176
	ds_read_b128 v[176:179], v146 offset:51200
	ds_read_b128 v[180:183], v146 offset:52224
	ds_read_b128 v[184:187], v146 offset:53248
	ds_read_b128 v[188:191], v146 offset:54272
	ds_read_b128 v[192:195], v146 offset:55296
	ds_read_b128 v[196:199], v146 offset:56320
	global_load_lds_dwordx4 v134, s[100:101]
	s_mov_b32 m0, s53
	s_nop 0
	global_load_lds_dwordx4 v130, s[100:101]
	s_barrier
; #define PG8_STAGE(bufoff, gbase, voff) do { _Pragma("unroll") for (int _i = 0; _i < 2; ++_i) \
;         __builtin_amdgcn_global_load_lds((const unsigned*)((const char*)(gbase) + (voff)[_i]), (LAS unsigned*)(lds + (bufoff) + ldsw + _i * 8192), 16, 0, 0); } while (0)
; #define PG8_MMA(ai, bj, At, Bt) do { __builtin_amdgcn_s_setprio(1); _Pragma("unroll") for (int m = 0; m < 4; ++m) _Pragma("unroll") for (int n = 0; n < 2; ++n) _Pragma("unroll") for (int k = 0; k < 2; ++k) \
;         acc[ai][bj][m][n] = __builtin_amdgcn_mfma_f32_16x16x32_bf16(Bt[n][k], At[m][k], acc[ai][bj][m][n], 0, 0, 0); __builtin_amdgcn_s_setprio(0); } while (0)
; #define PG8_WAIT_V(n) asm volatile("s_waitcnt vmcnt(" #n ")" ::: "memory")
; #define PG8_WAIT_L(n) asm volatile("s_waitcnt lgkmcnt(" #n ")" ::: "memory")
; #define PG8_BAR __builtin_amdgcn_s_barrier()
; #define PG8_SCHED __builtin_amdgcn_sched_barrier(0)
; template <class Epi>
; __device__ __forceinline__ void gemm_phase(LAS unsigned char* lds, const Gemm g, const StaticOrder& S, const Epi& E) {
;     ...
;             PG8_BAR; PG8_WAIT_L(0); PG8_MMA(1, 0, At, B0); PG8_BAR; PG8_SCHED;
;             PG8_STAGE(PG8_SB(1, 1), b3 + hstep, voffB);
;             PG8_WAIT_V(6); PG8_BAR; PG8_MMA(1, 1, At, B1); PG8_BAR;
;         }
	s_waitcnt lgkmcnt(0)
	s_waitcnt lgkmcnt(0)
	v_mfma_f32_16x16x32_bf16 v[60:63], v[148:151], v[168:171], v[60:63]
	v_mfma_f32_16x16x32_bf16 v[56:59], v[160:163], v[168:171], v[56:59]
	v_mfma_f32_16x16x32_bf16 v[52:55], v[148:151], v[176:179], v[52:55]
	v_mfma_f32_16x16x32_bf16 v[44:47], v[160:163], v[176:179], v[44:47]
	v_mfma_f32_16x16x32_bf16 v[36:39], v[148:151], v[184:187], v[36:39]
	v_mfma_f32_16x16x32_bf16 v[28:31], v[160:163], v[184:187], v[28:31]
	v_mfma_f32_16x16x32_bf16 v[20:23], v[148:151], v[192:195], v[20:23]
	v_mfma_f32_16x16x32_bf16 v[12:15], v[160:163], v[192:195], v[12:15]
	v_mfma_f32_16x16x32_bf16 v[60:63], v[152:155], v[172:175], v[60:63]
	v_mfma_f32_16x16x32_bf16 v[56:59], v[164:167], v[172:175], v[56:59]
	v_mfma_f32_16x16x32_bf16 v[52:55], v[152:155], v[180:183], v[52:55]
	v_mfma_f32_16x16x32_bf16 v[44:47], v[164:167], v[180:183], v[44:47]
	v_mfma_f32_16x16x32_bf16 v[36:39], v[152:155], v[188:191], v[36:39]
	v_mfma_f32_16x16x32_bf16 v[28:31], v[164:167], v[188:191], v[28:31]
	v_mfma_f32_16x16x32_bf16 v[20:23], v[152:155], v[196:199], v[20:23]
	v_mfma_f32_16x16x32_bf16 v[12:15], v[164:167], v[196:199], v[12:15]
	s_barrier
	s_add_u32 s42, s46, 0x160080
	s_addc_u32 s43, s47, 0
	s_add_i32 s46, s48, s23
	s_mov_b32 m0, s46
	s_nop 0
	global_load_lds_dwordx4 v132, s[42:43]
	s_add_i32 m0, s46, 0x2000
	s_nop 0
	global_load_lds_dwordx4 v128, s[42:43]
	s_waitcnt vmcnt(6)
	s_barrier
	v_mfma_f32_16x16x32_bf16 v[48:51], v[200:203], v[168:171], v[48:51]
	v_mfma_f32_16x16x32_bf16 v[40:43], v[208:211], v[168:171], v[40:43]
	v_mfma_f32_16x16x32_bf16 v[32:35], v[200:203], v[176:179], v[32:35]
	v_mfma_f32_16x16x32_bf16 v[24:27], v[208:211], v[176:179], v[24:27]
	v_mfma_f32_16x16x32_bf16 v[16:19], v[200:203], v[184:187], v[16:19]
	v_mfma_f32_16x16x32_bf16 v[8:11], v[208:211], v[184:187], v[8:11]
	v_mfma_f32_16x16x32_bf16 v[4:7], v[200:203], v[192:195], v[4:7]
	v_mfma_f32_16x16x32_bf16 v[0:3], v[208:211], v[192:195], v[0:3]
	v_mfma_f32_16x16x32_bf16 v[48:51], v[204:207], v[172:175], v[48:51]
	v_mfma_f32_16x16x32_bf16 v[40:43], v[212:215], v[172:175], v[40:43]
	v_mfma_f32_16x16x32_bf16 v[32:35], v[204:207], v[180:183], v[32:35]
	v_mfma_f32_16x16x32_bf16 v[24:27], v[212:215], v[180:183], v[24:27]
	v_mfma_f32_16x16x32_bf16 v[16:19], v[204:207], v[188:191], v[16:19]
	v_mfma_f32_16x16x32_bf16 v[8:11], v[212:215], v[188:191], v[8:11]
	v_mfma_f32_16x16x32_bf16 v[4:7], v[204:207], v[196:199], v[4:7]
	v_mfma_f32_16x16x32_bf16 v[0:3], v[212:215], v[196:199], v[0:3]
	s_add_i32 s67, s67, 2
	s_add_u32 s65, s65, 0x100
	s_addc_u32 s66, s66, 0
	s_cmpk_gt_u32 s67, 0x55
	s_mov_b64 s[42:43], s[44:45]
	s_barrier
	s_cbranch_scc0 .LBB0_864
; #define PG8_WAIT_V(n) asm volatile("s_waitcnt vmcnt(" #n ")" ::: "memory")
; #define PG8_BAR __builtin_amdgcn_s_barrier()
; __device__ __forceinline__ u32x4 pack8(f32x4 v0, f32x4 v1) { u32x4 w; w.x = cvt_pk_bf16(v0[0], v0[1]); w.y = cvt_pk_bf16(v0[2], v0[3]); w.z = cvt_pk_bf16(v1[0], v1[1]); w.w = cvt_pk_bf16(v1[2], v1[3]); return w; }
; template <class Epi>
; __device__ __forceinline__ void gemm_phase(LAS unsigned char* lds, const Gemm g, const StaticOrder& S, const Epi& E) {
;     ...
;         cur = nxt; cA = nA; cB = nB; ++ui;
;     }
;     PG8_WAIT_V(0);
;     if (wr == 0) PG8_BAR;
;     PG8_BAR;
;     __device__ __forceinline__ void operator()(const f32x4 (&acc)[2][2][4][2], const Unit& u, int wr, int wc, int fr, int fq) const {
;         const int row0 = u.pm * BM + wr * 64 + fr, col0 = u.pn * BM + wc * 32 + 8 * fq;
; #pragma unroll
;         for (int ai = 0; ai < 2; ++ai)
; #pragma unroll
;             for (int m = 0; m < 4; ++m) { bf16_t* rowp = O + (size_t)(row0 + ai * HALF + m * 16) * ldc + col0;
; #pragma unroll
;                 for (int bj = 0; bj < 2; ++bj) *(u32x4*)(rowp + bj * HALF) = pack8(acc[ai][bj][m][0], acc[ai][bj][m][1]); }
;     }
	v_lshl_add_u32 v148, s63, 8, v142
	v_lshl_or_b32 v140, s64, 8, v144
	v_ashrrev_i32_e32 v149, 31, v148
	v_ashrrev_i32_e32 v141, 31, v140
	v_lshlrev_b64 v[150:151], 12, v[148:149]
	v_lshl_add_u64 v[150:151], s[24:25], 0, v[150:151]
	v_lshlrev_b64 v[152:153], 1, v[140:141]
	v_lshl_add_u64 v[140:141], v[150:151], 0, v[152:153]
	v_cvt_pk_bf16_f32 v124, v124, v125
	v_cvt_pk_bf16_f32 v125, v126, v127
	v_cvt_pk_bf16_f32 v126, v120, v121
	v_cvt_pk_bf16_f32 v127, v122, v123
	global_store_dwordx4 v[140:141], v[124:127], off
	v_cvt_pk_bf16_f32 v116, v116, v117
	v_cvt_pk_bf16_f32 v117, v118, v119
	v_cvt_pk_bf16_f32 v118, v108, v109
	v_or_b32_e32 v108, 16, v148
	v_ashrrev_i32_e32 v109, 31, v108
	v_lshlrev_b64 v[108:109], 12, v[108:109]
	v_lshl_add_u64 v[108:109], s[24:25], 0, v[108:109]
	v_cvt_pk_bf16_f32 v119, v110, v111
	global_store_dwordx4 v[140:141], v[116:119], off offset:256
	s_mov_b32 s64, s61
	s_mov_b32 s63, s62
	v_lshl_add_u64 v[116:117], v[108:109], 0, v[152:153]
	v_cvt_pk_bf16_f32 v108, v112, v113
	v_cvt_pk_bf16_f32 v109, v114, v115
	v_cvt_pk_bf16_f32 v110, v104, v105
	v_cvt_pk_bf16_f32 v111, v106, v107
	global_store_dwordx4 v[116:117], v[108:111], off
	v_cvt_pk_bf16_f32 v100, v100, v101
	v_cvt_pk_bf16_f32 v101, v102, v103
	v_cvt_pk_bf16_f32 v102, v92, v93
	v_or_b32_e32 v92, 32, v148
	v_ashrrev_i32_e32 v93, 31, v92
	v_lshlrev_b64 v[92:93], 12, v[92:93]
	v_lshl_add_u64 v[92:93], s[24:25], 0, v[92:93]
	v_cvt_pk_bf16_f32 v103, v94, v95
	global_store_dwordx4 v[116:117], v[100:103], off offset:256
	s_mov_b64 s[44:45], s[6:7]
	s_mov_b64 s[42:43], s[40:41]
	v_lshl_add_u64 v[100:101], v[92:93], 0, v[152:153]
	v_cvt_pk_bf16_f32 v92, v96, v97
	v_cvt_pk_bf16_f32 v93, v98, v99
	v_cvt_pk_bf16_f32 v94, v88, v89
	v_cvt_pk_bf16_f32 v95, v90, v91
	global_store_dwordx4 v[100:101], v[92:95], off
	v_cvt_pk_bf16_f32 v84, v84, v85
	v_cvt_pk_bf16_f32 v85, v86, v87
	v_cvt_pk_bf16_f32 v86, v76, v77
	v_or_b32_e32 v76, 48, v148
	v_ashrrev_i32_e32 v77, 31, v76
	v_lshlrev_b64 v[76:77], 12, v[76:77]
	v_lshl_add_u64 v[76:77], s[24:25], 0, v[76:77]
	v_cvt_pk_bf16_f32 v87, v78, v79
	global_store_dwordx4 v[100:101], v[84:87], off offset:256
	s_nop 1
	v_lshl_add_u64 v[84:85], v[76:77], 0, v[152:153]
	v_cvt_pk_bf16_f32 v76, v80, v81
	v_cvt_pk_bf16_f32 v77, v82, v83
	v_cvt_pk_bf16_f32 v78, v72, v73
	v_cvt_pk_bf16_f32 v79, v74, v75
	global_store_dwordx4 v[84:85], v[76:79], off
	v_cvt_pk_bf16_f32 v68, v68, v69
	v_cvt_pk_bf16_f32 v69, v70, v71
	v_cvt_pk_bf16_f32 v70, v64, v65
	v_cvt_pk_bf16_f32 v71, v66, v67
	global_store_dwordx4 v[84:85], v[68:71], off offset:256
	v_cvt_pk_bf16_f32 v60, v60, v61
	v_cvt_pk_bf16_f32 v61, v62, v63
	v_cvt_pk_bf16_f32 v62, v56, v57
	v_add_co_u32_e32 v56, vcc, s57, v140
	v_lshl_add_u64 v[64:65], v[140:141], 0, s[8:9]
	s_nop 0
	v_addc_co_u32_e32 v57, vcc, 0, v141, vcc
	v_cvt_pk_bf16_f32 v63, v58, v59
	global_store_dwordx4 v[56:57], v[60:63], off
	v_cvt_pk_bf16_f32 v48, v48, v49
	v_cvt_pk_bf16_f32 v49, v50, v51
	v_cvt_pk_bf16_f32 v50, v40, v41
	v_cvt_pk_bf16_f32 v51, v42, v43
	global_store_dwordx4 v[64:65], v[48:51], off offset:256
	v_cvt_pk_bf16_f32 v40, v52, v53
	v_cvt_pk_bf16_f32 v41, v54, v55
	v_cvt_pk_bf16_f32 v42, v44, v45
	v_add_co_u32_e32 v44, vcc, s58, v140
	s_nop 0
	v_lshl_add_u64 v[48:49], v[140:141], 0, s[30:31]
	v_addc_co_u32_e32 v45, vcc, 0, v141, vcc
	v_cvt_pk_bf16_f32 v43, v46, v47
	global_store_dwordx4 v[44:45], v[40:43], off
	v_cvt_pk_bf16_f32 v32, v32, v33
	v_cvt_pk_bf16_f32 v33, v34, v35
	v_cvt_pk_bf16_f32 v34, v24, v25
	v_cvt_pk_bf16_f32 v35, v26, v27
	global_store_dwordx4 v[48:49], v[32:35], off offset:256
	v_cvt_pk_bf16_f32 v24, v36, v37
	v_cvt_pk_bf16_f32 v25, v38, v39
	v_cvt_pk_bf16_f32 v26, v28, v29
	v_add_co_u32_e32 v28, vcc, s59, v140
	s_nop 0
	v_lshl_add_u64 v[32:33], v[140:141], 0, s[34:35]
	v_addc_co_u32_e32 v29, vcc, 0, v141, vcc
	v_cvt_pk_bf16_f32 v27, v30, v31
	global_store_dwordx4 v[28:29], v[24:27], off
	v_cvt_pk_bf16_f32 v16, v16, v17
	v_cvt_pk_bf16_f32 v17, v18, v19
	v_cvt_pk_bf16_f32 v18, v8, v9
	v_cvt_pk_bf16_f32 v19, v10, v11
	global_store_dwordx4 v[32:33], v[16:19], off offset:256
	v_cvt_pk_bf16_f32 v8, v20, v21
	v_cvt_pk_bf16_f32 v9, v22, v23
	v_cvt_pk_bf16_f32 v10, v12, v13
	v_add_co_u32_e32 v12, vcc, s60, v140
	s_nop 0
	v_lshl_add_u64 v[16:17], v[140:141], 0, s[36:37]
	v_addc_co_u32_e32 v13, vcc, 0, v141, vcc
	s_and_b64 vcc, exec, s[38:39]
	v_cvt_pk_bf16_f32 v11, v14, v15
	global_store_dwordx4 v[12:13], v[8:11], off
	v_cvt_pk_bf16_f32 v4, v4, v5
	v_cvt_pk_bf16_f32 v5, v6, v7
	v_cvt_pk_bf16_f32 v6, v0, v1
	v_cvt_pk_bf16_f32 v7, v2, v3
	global_store_dwordx4 v[16:17], v[4:7], off offset:256
	s_cbranch_vccz .LBB0_857
	s_waitcnt vmcnt(0)
	s_cmpk_gt_u32 s10, 0xff
	v_readlane_b32 s62, v232, 20
	v_readlane_b32 s61, v232, 21
	s_cbranch_scc1 .LBB0_868
	s_barrier

; #define PG8_STAGE(bufoff, gbase, voff) do { _Pragma("unroll") for (int _i = 0; _i < 2; ++_i) \
;         __builtin_amdgcn_global_load_lds((const unsigned*)((const char*)(gbase) + (voff)[_i]), (LAS unsigned*)(lds + (bufoff) + ldsw + _i * 8192), 16, 0, 0); } while (0)
; #define PG8_LDA(dst, b, h) do { _Pragma("unroll") for (int m = 0; m < 4; ++m) _Pragma("unroll") for (int k = 0; k < 2; ++k) dst[m][k] = *(const LAS bf16x8*)(lds + PG8_SA(b, h) + aoff + m * 2048 + k * 1024); } while (0)
; #define PG8_LDB(dst, b, h) do { _Pragma("unroll") for (int n = 0; n < 2; ++n) _Pragma("unroll") for (int k = 0; k < 2; ++k) dst[n][k] = *(const LAS bf16x8*)(lds + PG8_SB(b, h) + boff + n * 2048 + k * 1024); } while (0)
; #define PG8_MMA(ai, bj, At, Bt) do { __builtin_amdgcn_s_setprio(1); _Pragma("unroll") for (int m = 0; m < 4; ++m) _Pragma("unroll") for (int n = 0; n < 2; ++n) _Pragma("unroll") for (int k = 0; k < 2; ++k) \
;         acc[ai][bj][m][n] = __builtin_amdgcn_mfma_f32_16x16x32_bf16(Bt[n][k], At[m][k], acc[ai][bj][m][n], 0, 0, 0); __builtin_amdgcn_s_setprio(0); } while (0)
; #define PG8_WAIT_V(n) asm volatile("s_waitcnt vmcnt(" #n ")" ::: "memory")
; #define PG8_WAIT_L(n) asm volatile("s_waitcnt lgkmcnt(" #n ")" ::: "memory")
; template <class Epi>
; __device__ __forceinline__ void gemm_phase(LAS unsigned char* lds, const Gemm g, const StaticOrder& S, const Epi& E) {
;     ...
;         for (int t = 0; t < nt; t += 2) {
;             const bool last = (t == nt - 2);
;             const char* a1 = cA + (size_t)(t + 1) * kstep;
;             const char* a2 = last ? nA : cA + (size_t)(t + 2) * kstep; const char* b2 = last ? nB : cB + (size_t)(t + 2) * kstep;
;             const char* a3 = a2 + kstep; const char* b3 = b2 + kstep;
;             PG8_LDB(B0, 0, 0); PG8_SCHED; PG8_LDA(At, 0, 0); PG8_STAGE(PG8_SA(1, 1), a1 + hstep, voffA);
;             PG8_WAIT_L(8); PG8_BAR; PG8_WAIT_L(0); PG8_MMA(0, 0, At, B0); PG8_BAR; PG8_SCHED;
;             PG8_LDB(B1, 0, 1); PG8_STAGE(PG8_SB(0, 0), b2, voffB);
;             PG8_BAR; PG8_WAIT_L(0); PG8_MMA(0, 1, At, B1); PG8_BAR;
;             PG8_LDA(At, 0, 1); PG8_STAGE(PG8_SA(0, 0), a2, voffA);
;             PG8_BAR; PG8_WAIT_L(0); PG8_MMA(1, 0, At, B0); PG8_BAR; PG8_SCHED;
;             PG8_STAGE(PG8_SB(0, 1), b2 + hstep, voffB);
;             PG8_WAIT_V(6); PG8_BAR; PG8_MMA(1, 1, At, B1); PG8_BAR;
.LBB0_999:
	ds_read_b128 v[140:143], v151
	ds_read_b128 v[144:147], v151 offset:1024
	ds_read_b128 v[154:157], v151 offset:2048
	ds_read_b128 v[160:163], v151 offset:3072
	s_add_u32 s48, s46, 0xfff80080
	s_addc_u32 s49, s47, -1
	s_cmp_eq_u32 s63, 28
	s_cselect_b32 s51, s37, s49
	s_cselect_b32 s50, s59, s48
	s_cselect_b32 s49, s35, s62
	s_cselect_b32 s48, s60, s61
	s_add_i32 m0, s28, 0xc000
	ds_read_b128 v[164:167], v152
	ds_read_b128 v[168:171], v152 offset:1024
	ds_read_b128 v[172:175], v152 offset:2048
	ds_read_b128 v[176:179], v152 offset:3072
	ds_read_b128 v[180:183], v152 offset:4096
	ds_read_b128 v[184:187], v152 offset:5120
	ds_read_b128 v[188:191], v152 offset:6144
	ds_read_b128 v[192:195], v152 offset:7168
	global_load_lds_dwordx4 v136, s[46:47]
	s_add_i32 m0, s28, 0xe000
	s_nop 0
	global_load_lds_dwordx4 v138, s[46:47]
	s_waitcnt lgkmcnt(8)
	s_barrier
	s_waitcnt lgkmcnt(0)
	s_waitcnt lgkmcnt(0)
	v_mfma_f32_16x16x32_bf16 v[124:127], v[140:143], v[164:167], v[124:127]
	v_mfma_f32_16x16x32_bf16 v[120:123], v[154:157], v[164:167], v[120:123]
	v_mfma_f32_16x16x32_bf16 v[108:111], v[140:143], v[172:175], v[108:111]
	v_mfma_f32_16x16x32_bf16 v[104:107], v[154:157], v[172:175], v[104:107]
	v_mfma_f32_16x16x32_bf16 v[92:95], v[140:143], v[180:183], v[92:95]
	v_mfma_f32_16x16x32_bf16 v[88:91], v[154:157], v[180:183], v[88:91]
	v_mfma_f32_16x16x32_bf16 v[76:79], v[140:143], v[188:191], v[76:79]
	v_mfma_f32_16x16x32_bf16 v[72:75], v[154:157], v[188:191], v[72:75]
	v_mfma_f32_16x16x32_bf16 v[124:127], v[144:147], v[168:171], v[124:127]
	v_mfma_f32_16x16x32_bf16 v[120:123], v[160:163], v[168:171], v[120:123]
	v_mfma_f32_16x16x32_bf16 v[108:111], v[144:147], v[176:179], v[108:111]
	v_mfma_f32_16x16x32_bf16 v[104:107], v[160:163], v[176:179], v[104:107]
	v_mfma_f32_16x16x32_bf16 v[92:95], v[144:147], v[184:187], v[92:95]
	v_mfma_f32_16x16x32_bf16 v[88:91], v[160:163], v[184:187], v[88:91]
	v_mfma_f32_16x16x32_bf16 v[76:79], v[144:147], v[192:195], v[76:79]
	v_mfma_f32_16x16x32_bf16 v[72:75], v[160:163], v[192:195], v[72:75]
	s_barrier
	s_add_i32 s64, s56, s23
	s_add_u32 s98, s48, s4
	s_addc_u32 s99, s49, s5
	s_mov_b32 m0, s64
	ds_read_b128 v[196:199], v153
	ds_read_b128 v[200:203], v153 offset:1024
	ds_read_b128 v[204:207], v153 offset:2048
	ds_read_b128 v[208:211], v153 offset:3072
	global_load_lds_dwordx4 v132, s[48:49]
	s_add_i32 m0, s64, 0x2000
	s_nop 0
	global_load_lds_dwordx4 v128, s[48:49]
	s_barrier
	s_waitcnt lgkmcnt(0)
	s_waitcnt lgkmcnt(0)
	v_mfma_f32_16x16x32_bf16 v[116:119], v[196:199], v[164:167], v[116:119]
	v_mfma_f32_16x16x32_bf16 v[112:115], v[204:207], v[164:167], v[112:115]
	v_mfma_f32_16x16x32_bf16 v[100:103], v[196:199], v[172:175], v[100:103]
	v_mfma_f32_16x16x32_bf16 v[96:99], v[204:207], v[172:175], v[96:99]
	v_mfma_f32_16x16x32_bf16 v[84:87], v[196:199], v[180:183], v[84:87]
	v_mfma_f32_16x16x32_bf16 v[80:83], v[204:207], v[180:183], v[80:83]
	v_mfma_f32_16x16x32_bf16 v[68:71], v[196:199], v[188:191], v[68:71]
	v_mfma_f32_16x16x32_bf16 v[64:67], v[204:207], v[188:191], v[64:67]
	v_mfma_f32_16x16x32_bf16 v[116:119], v[200:203], v[168:171], v[116:119]
	v_mfma_f32_16x16x32_bf16 v[112:115], v[208:211], v[168:171], v[112:115]
	v_mfma_f32_16x16x32_bf16 v[100:103], v[200:203], v[176:179], v[100:103]
	v_mfma_f32_16x16x32_bf16 v[96:99], v[208:211], v[176:179], v[96:99]
	v_mfma_f32_16x16x32_bf16 v[84:87], v[200:203], v[184:187], v[84:87]
	v_mfma_f32_16x16x32_bf16 v[80:83], v[208:211], v[184:187], v[80:83]
	v_mfma_f32_16x16x32_bf16 v[68:71], v[200:203], v[192:195], v[68:71]
	v_mfma_f32_16x16x32_bf16 v[64:67], v[208:211], v[192:195], v[64:67]
	s_mov_b32 m0, s28
	s_add_u32 s100, s50, s4
	s_addc_u32 s101, s51, s5
	s_barrier
	ds_read_b128 v[164:167], v152 offset:16384
	ds_read_b128 v[168:171], v152 offset:17408
	ds_read_b128 v[172:175], v152 offset:18432
	ds_read_b128 v[176:179], v152 offset:19456
	ds_read_b128 v[180:183], v152 offset:20480
	ds_read_b128 v[184:187], v152 offset:21504
	ds_read_b128 v[188:191], v152 offset:22528
	ds_read_b128 v[192:195], v152 offset:23552
	global_load_lds_dwordx4 v134, s[50:51]
	s_mov_b32 m0, s29
	s_nop 0
	global_load_lds_dwordx4 v130, s[50:51]
	s_barrier
	s_waitcnt lgkmcnt(0)
	s_waitcnt lgkmcnt(0)
	v_mfma_f32_16x16x32_bf16 v[60:63], v[140:143], v[164:167], v[60:63]
	v_mfma_f32_16x16x32_bf16 v[56:59], v[154:157], v[164:167], v[56:59]
	v_mfma_f32_16x16x32_bf16 v[44:47], v[140:143], v[172:175], v[44:47]
	v_mfma_f32_16x16x32_bf16 v[40:43], v[154:157], v[172:175], v[40:43]
	v_mfma_f32_16x16x32_bf16 v[28:31], v[140:143], v[180:183], v[28:31]
	v_mfma_f32_16x16x32_bf16 v[24:27], v[154:157], v[180:183], v[24:27]
	v_mfma_f32_16x16x32_bf16 v[12:15], v[140:143], v[188:191], v[12:15]
	v_mfma_f32_16x16x32_bf16 v[8:11], v[154:157], v[188:191], v[8:11]
	v_mfma_f32_16x16x32_bf16 v[60:63], v[144:147], v[168:171], v[60:63]
	v_mfma_f32_16x16x32_bf16 v[56:59], v[160:163], v[168:171], v[56:59]
	v_mfma_f32_16x16x32_bf16 v[44:47], v[144:147], v[176:179], v[44:47]
	v_mfma_f32_16x16x32_bf16 v[40:43], v[160:163], v[176:179], v[40:43]
	v_mfma_f32_16x16x32_bf16 v[28:31], v[144:147], v[184:187], v[28:31]
	v_mfma_f32_16x16x32_bf16 v[24:27], v[160:163], v[184:187], v[24:27]
	v_mfma_f32_16x16x32_bf16 v[12:15], v[144:147], v[192:195], v[12:15]
	v_mfma_f32_16x16x32_bf16 v[8:11], v[160:163], v[192:195], v[8:11]
	s_barrier
	s_add_u32 s64, s48, 0x80000
	s_addc_u32 s65, s49, 0
	s_add_i32 s66, s57, s23
	s_mov_b32 m0, s66
	s_nop 0
	global_load_lds_dwordx4 v132, s[64:65]
	s_add_i32 m0, s66, 0x2000
	s_nop 0
	global_load_lds_dwordx4 v128, s[64:65]
	s_waitcnt vmcnt(6)
	s_barrier
; #define PG8_STAGE(bufoff, gbase, voff) do { _Pragma("unroll") for (int _i = 0; _i < 2; ++_i) \
;         __builtin_amdgcn_global_load_lds((const unsigned*)((const char*)(gbase) + (voff)[_i]), (LAS unsigned*)(lds + (bufoff) + ldsw + _i * 8192), 16, 0, 0); } while (0)
; #define PG8_LDA(dst, b, h) do { _Pragma("unroll") for (int m = 0; m < 4; ++m) _Pragma("unroll") for (int k = 0; k < 2; ++k) dst[m][k] = *(const LAS bf16x8*)(lds + PG8_SA(b, h) + aoff + m * 2048 + k * 1024); } while (0)
; #define PG8_LDB(dst, b, h) do { _Pragma("unroll") for (int n = 0; n < 2; ++n) _Pragma("unroll") for (int k = 0; k < 2; ++k) dst[n][k] = *(const LAS bf16x8*)(lds + PG8_SB(b, h) + boff + n * 2048 + k * 1024); } while (0)
; #define PG8_MMA(ai, bj, At, Bt) do { __builtin_amdgcn_s_setprio(1); _Pragma("unroll") for (int m = 0; m < 4; ++m) _Pragma("unroll") for (int n = 0; n < 2; ++n) _Pragma("unroll") for (int k = 0; k < 2; ++k) \
;         acc[ai][bj][m][n] = __builtin_amdgcn_mfma_f32_16x16x32_bf16(Bt[n][k], At[m][k], acc[ai][bj][m][n], 0, 0, 0); __builtin_amdgcn_s_setprio(0); } while (0)
; #define PG8_WAIT_V(n) asm volatile("s_waitcnt vmcnt(" #n ")" ::: "memory")
; #define PG8_WAIT_L(n) asm volatile("s_waitcnt lgkmcnt(" #n ")" ::: "memory")
; #define PG8_BAR __builtin_amdgcn_s_barrier()
; #define PG8_SCHED __builtin_amdgcn_sched_barrier(0)
; template <class Epi>
; __device__ __forceinline__ void gemm_phase(LAS unsigned char* lds, const Gemm g, const StaticOrder& S, const Epi& E) {
;     ...
;             PG8_WAIT_V(6); PG8_BAR; PG8_MMA(1, 1, At, B1); PG8_BAR;
;             PG8_LDB(B0, 1, 0); PG8_SCHED; PG8_LDA(At, 1, 0); PG8_STAGE(PG8_SA(0, 1), a2 + hstep, voffA);
;             PG8_WAIT_L(8); PG8_BAR; PG8_WAIT_L(0); PG8_MMA(0, 0, At, B0); PG8_BAR; PG8_SCHED;
;             PG8_LDB(B1, 1, 1); PG8_STAGE(PG8_SB(1, 0), b3, voffB);
;             PG8_BAR; PG8_WAIT_L(0); PG8_MMA(0, 1, At, B1); PG8_BAR;
;             PG8_LDA(At, 1, 1); PG8_STAGE(PG8_SA(1, 0), a3, voffA);
	v_mfma_f32_16x16x32_bf16 v[52:55], v[196:199], v[164:167], v[52:55]
	v_mfma_f32_16x16x32_bf16 v[48:51], v[204:207], v[164:167], v[48:51]
	v_mfma_f32_16x16x32_bf16 v[36:39], v[196:199], v[172:175], v[36:39]
	v_mfma_f32_16x16x32_bf16 v[32:35], v[204:207], v[172:175], v[32:35]
	v_mfma_f32_16x16x32_bf16 v[20:23], v[196:199], v[180:183], v[20:23]
	v_mfma_f32_16x16x32_bf16 v[16:19], v[204:207], v[180:183], v[16:19]
	v_mfma_f32_16x16x32_bf16 v[4:7], v[196:199], v[188:191], v[4:7]
	v_mfma_f32_16x16x32_bf16 v[0:3], v[204:207], v[188:191], v[0:3]
	v_mfma_f32_16x16x32_bf16 v[52:55], v[200:203], v[168:171], v[52:55]
	v_mfma_f32_16x16x32_bf16 v[48:51], v[208:211], v[168:171], v[48:51]
	v_mfma_f32_16x16x32_bf16 v[36:39], v[200:203], v[176:179], v[36:39]
	v_mfma_f32_16x16x32_bf16 v[32:35], v[208:211], v[176:179], v[32:35]
	v_mfma_f32_16x16x32_bf16 v[20:23], v[200:203], v[184:187], v[20:23]
	v_mfma_f32_16x16x32_bf16 v[16:19], v[208:211], v[184:187], v[16:19]
	v_mfma_f32_16x16x32_bf16 v[4:7], v[200:203], v[192:195], v[4:7]
	v_mfma_f32_16x16x32_bf16 v[0:3], v[208:211], v[192:195], v[0:3]
	s_add_i32 s64, 0, 0x18000
	v_add_u32_e32 v160, s64, v149
	s_barrier
	ds_read_b128 v[140:143], v160
	ds_read_b128 v[144:147], v160 offset:1024
	ds_read_b128 v[154:157], v160 offset:2048
	ds_read_b128 v[160:163], v160 offset:3072
	s_add_u32 s50, s50, 0x80000
	s_addc_u32 s51, s51, 0
	s_mov_b32 m0, s33
	ds_read_b128 v[164:167], v152 offset:32768
	ds_read_b128 v[168:171], v152 offset:33792
	ds_read_b128 v[172:175], v152 offset:34816
	ds_read_b128 v[176:179], v152 offset:35840
	ds_read_b128 v[180:183], v152 offset:36864
	ds_read_b128 v[184:187], v152 offset:37888
	ds_read_b128 v[188:191], v152 offset:38912
	ds_read_b128 v[192:195], v152 offset:39936
	global_load_lds_dwordx4 v134, s[50:51]
	s_mov_b32 m0, s45
	s_nop 0
	global_load_lds_dwordx4 v130, s[50:51]
	s_waitcnt lgkmcnt(8)
	s_barrier
	s_waitcnt lgkmcnt(0)
	s_waitcnt lgkmcnt(0)
	v_mfma_f32_16x16x32_bf16 v[124:127], v[140:143], v[164:167], v[124:127]
	v_mfma_f32_16x16x32_bf16 v[120:123], v[154:157], v[164:167], v[120:123]
	v_mfma_f32_16x16x32_bf16 v[108:111], v[140:143], v[172:175], v[108:111]
	v_mfma_f32_16x16x32_bf16 v[104:107], v[154:157], v[172:175], v[104:107]
	v_mfma_f32_16x16x32_bf16 v[92:95], v[140:143], v[180:183], v[92:95]
	v_mfma_f32_16x16x32_bf16 v[88:91], v[154:157], v[180:183], v[88:91]
	v_mfma_f32_16x16x32_bf16 v[76:79], v[140:143], v[188:191], v[76:79]
	v_mfma_f32_16x16x32_bf16 v[72:75], v[154:157], v[188:191], v[72:75]
	v_mfma_f32_16x16x32_bf16 v[124:127], v[144:147], v[168:171], v[124:127]
	v_mfma_f32_16x16x32_bf16 v[120:123], v[160:163], v[168:171], v[120:123]
	v_mfma_f32_16x16x32_bf16 v[108:111], v[144:147], v[176:179], v[108:111]
	v_mfma_f32_16x16x32_bf16 v[104:107], v[160:163], v[176:179], v[104:107]
	v_mfma_f32_16x16x32_bf16 v[92:95], v[144:147], v[184:187], v[92:95]
	v_mfma_f32_16x16x32_bf16 v[88:91], v[160:163], v[184:187], v[88:91]
	v_mfma_f32_16x16x32_bf16 v[76:79], v[144:147], v[192:195], v[76:79]
	v_mfma_f32_16x16x32_bf16 v[72:75], v[160:163], v[192:195], v[72:75]
	s_barrier
	s_add_i32 s50, 0, 0x1c000
	s_add_i32 s51, s64, s23
	v_add_u32_e32 v208, s50, v149
	s_mov_b32 m0, s51
	ds_read_b128 v[196:199], v208
	ds_read_b128 v[200:203], v208 offset:1024
	ds_read_b128 v[204:207], v208 offset:2048
	ds_read_b128 v[208:211], v208 offset:3072
	global_load_lds_dwordx4 v132, s[98:99]
	s_add_i32 m0, s51, 0x2000
	s_nop 0
	global_load_lds_dwordx4 v128, s[98:99]
	s_barrier
	s_waitcnt lgkmcnt(0)
	s_waitcnt lgkmcnt(0)
	v_mfma_f32_16x16x32_bf16 v[116:119], v[196:199], v[164:167], v[116:119]
	v_mfma_f32_16x16x32_bf16 v[112:115], v[204:207], v[164:167], v[112:115]
	v_mfma_f32_16x16x32_bf16 v[100:103], v[196:199], v[172:175], v[100:103]
	v_mfma_f32_16x16x32_bf16 v[96:99], v[204:207], v[172:175], v[96:99]
	v_mfma_f32_16x16x32_bf16 v[84:87], v[196:199], v[180:183], v[84:87]
	v_mfma_f32_16x16x32_bf16 v[80:83], v[204:207], v[180:183], v[80:83]
	v_mfma_f32_16x16x32_bf16 v[68:71], v[196:199], v[188:191], v[68:71]
	v_mfma_f32_16x16x32_bf16 v[64:67], v[204:207], v[188:191], v[64:67]
	v_mfma_f32_16x16x32_bf16 v[116:119], v[200:203], v[168:171], v[116:119]
	v_mfma_f32_16x16x32_bf16 v[112:115], v[208:211], v[168:171], v[112:115]
	v_mfma_f32_16x16x32_bf16 v[100:103], v[200:203], v[176:179], v[100:103]
	v_mfma_f32_16x16x32_bf16 v[96:99], v[208:211], v[176:179], v[96:99]
	v_mfma_f32_16x16x32_bf16 v[84:87], v[200:203], v[184:187], v[84:87]
	v_mfma_f32_16x16x32_bf16 v[80:83], v[208:211], v[184:187], v[80:83]
	v_mfma_f32_16x16x32_bf16 v[68:71], v[200:203], v[192:195], v[68:71]
	v_mfma_f32_16x16x32_bf16 v[64:67], v[208:211], v[192:195], v[64:67]
	s_mov_b32 m0, s53
	s_barrier
	ds_read_b128 v[164:167], v152 offset:49152
	ds_read_b128 v[168:171], v152 offset:50176
	ds_read_b128 v[172:175], v152 offset:51200
	ds_read_b128 v[176:179], v152 offset:52224
	ds_read_b128 v[180:183], v152 offset:53248
	ds_read_b128 v[184:187], v152 offset:54272
	ds_read_b128 v[188:191], v152 offset:55296
	ds_read_b128 v[192:195], v152 offset:56320
	global_load_lds_dwordx4 v134, s[100:101]
	s_mov_b32 m0, s54
	s_nop 0
	global_load_lds_dwordx4 v130, s[100:101]
	s_barrier
; __device__ __forceinline__ float bf_lo(unsigned w) { return __uint_as_float(w << 16); }
; __device__ __forceinline__ float bf_hi(unsigned w) { return __uint_as_float(w & 0xffff0000u); }
; __device__ __forceinline__ float fast_rcp(float x) { return __builtin_amdgcn_rcpf(x); }
; __device__ __forceinline__ float fast_exp2(float x) { return __builtin_amdgcn_exp2f(x); }
; #define PG8_STAGE(bufoff, gbase, voff) do { _Pragma("unroll") for (int _i = 0; _i < 2; ++_i) \
;         __builtin_amdgcn_global_load_lds((const unsigned*)((const char*)(gbase) + (voff)[_i]), (LAS unsigned*)(lds + (bufoff) + ldsw + _i * 8192), 16, 0, 0); } while (0)
; #define PG8_WAIT_V(n) asm volatile("s_waitcnt vmcnt(" #n ")" ::: "memory")
; #define PG8_WAIT_L(n) asm volatile("s_waitcnt lgkmcnt(" #n ")" ::: "memory")
; #define PG8_BAR __builtin_amdgcn_s_barrier()
; #define PG8_SCHED __builtin_amdgcn_sched_barrier(0)
; template <class Epi>
; __device__ __forceinline__ void gemm_phase(LAS unsigned char* lds, const Gemm g, const StaticOrder& S, const Epi& E) {
;     ...
;             PG8_BAR; PG8_WAIT_L(0); PG8_MMA(1, 0, At, B0); PG8_BAR; PG8_SCHED;
;             PG8_STAGE(PG8_SB(1, 1), b3 + hstep, voffB);
;             PG8_WAIT_V(6); PG8_BAR; PG8_MMA(1, 1, At, B1); PG8_BAR;
;     __device__ __forceinline__ void operator()(const f32x4 (&acc)[2][2][4][2], const Unit& u, int wr, int wc, int fr, int fq) const {
;         const int row0 = u.pm * BM + wr * 64 + fr, col0 = u.pn * BM + wc * 32 + 8 * fq;
; #pragma unroll
;         for (int ai = 0; ai < 2; ++ai)
; #pragma unroll
;             for (int m = 0; m < 4; ++m) { const size_t ro = (size_t)(row0 + ai * HALF + m * 16) * DM + col0; const float nr = -LOG2E * rs[row0 + ai * HALF + m * 16];
; #pragma unroll
;                 for (int bj = 0; bj < 2; ++bj) {
;                     const u32x4 pw = *(const u32x4*)(PP + ro + bj * HALF);
;                     const float pv[8] = {bf_lo(pw.x), bf_hi(pw.x), bf_lo(pw.y), bf_hi(pw.y), bf_lo(pw.z), bf_hi(pw.z), bf_lo(pw.w), bf_hi(pw.w)};
;                     f32x4 t0, t1;
; #pragma unroll
;                     for (int j = 0; j < 4; ++j) {
;                         t0[j] = fast_rcp(1.0f + fast_exp2(acc[ai][bj][m][0][j] * nr)) * pv[j];
;                         t1[j] = fast_rcp(1.0f + fast_exp2(acc[ai][bj][m][1][j] * nr)) * pv[4 + j]; }
;                     *(u32x4*)(O + ro + bj * HALF) = pack8(t0, t1); } }
	s_waitcnt lgkmcnt(0)
	s_waitcnt lgkmcnt(0)
	v_mfma_f32_16x16x32_bf16 v[60:63], v[140:143], v[164:167], v[60:63]
	v_mfma_f32_16x16x32_bf16 v[56:59], v[154:157], v[164:167], v[56:59]
	v_mfma_f32_16x16x32_bf16 v[44:47], v[140:143], v[172:175], v[44:47]
	v_mfma_f32_16x16x32_bf16 v[40:43], v[154:157], v[172:175], v[40:43]
	v_mfma_f32_16x16x32_bf16 v[28:31], v[140:143], v[180:183], v[28:31]
	v_mfma_f32_16x16x32_bf16 v[24:27], v[154:157], v[180:183], v[24:27]
	v_mfma_f32_16x16x32_bf16 v[12:15], v[140:143], v[188:191], v[12:15]
	v_mfma_f32_16x16x32_bf16 v[8:11], v[154:157], v[188:191], v[8:11]
	v_mfma_f32_16x16x32_bf16 v[60:63], v[144:147], v[168:171], v[60:63]
	v_mfma_f32_16x16x32_bf16 v[56:59], v[160:163], v[168:171], v[56:59]
	v_mfma_f32_16x16x32_bf16 v[44:47], v[144:147], v[176:179], v[44:47]
	v_mfma_f32_16x16x32_bf16 v[40:43], v[160:163], v[176:179], v[40:43]
	v_mfma_f32_16x16x32_bf16 v[28:31], v[144:147], v[184:187], v[28:31]
	v_mfma_f32_16x16x32_bf16 v[24:27], v[160:163], v[184:187], v[24:27]
	v_mfma_f32_16x16x32_bf16 v[12:15], v[144:147], v[192:195], v[12:15]
	v_mfma_f32_16x16x32_bf16 v[8:11], v[160:163], v[192:195], v[8:11]
	s_barrier
	s_add_u32 s48, s48, 0x80080
	s_addc_u32 s49, s49, 0
	s_add_i32 s50, s50, s23
	s_mov_b32 m0, s50
	s_nop 0
	global_load_lds_dwordx4 v132, s[48:49]
	s_add_i32 m0, s50, 0x2000
	s_nop 0
	global_load_lds_dwordx4 v128, s[48:49]
	s_waitcnt vmcnt(6)
	s_barrier
	v_mfma_f32_16x16x32_bf16 v[52:55], v[196:199], v[164:167], v[52:55]
	v_mfma_f32_16x16x32_bf16 v[48:51], v[204:207], v[164:167], v[48:51]
	v_mfma_f32_16x16x32_bf16 v[36:39], v[196:199], v[172:175], v[36:39]
	v_mfma_f32_16x16x32_bf16 v[32:35], v[204:207], v[172:175], v[32:35]
	v_mfma_f32_16x16x32_bf16 v[20:23], v[196:199], v[180:183], v[20:23]
	v_mfma_f32_16x16x32_bf16 v[16:19], v[204:207], v[180:183], v[16:19]
	v_mfma_f32_16x16x32_bf16 v[4:7], v[196:199], v[188:191], v[4:7]
	v_mfma_f32_16x16x32_bf16 v[0:3], v[204:207], v[188:191], v[0:3]
	v_mfma_f32_16x16x32_bf16 v[52:55], v[200:203], v[168:171], v[52:55]
	v_mfma_f32_16x16x32_bf16 v[48:51], v[208:211], v[168:171], v[48:51]
	v_mfma_f32_16x16x32_bf16 v[36:39], v[200:203], v[176:179], v[36:39]
	v_mfma_f32_16x16x32_bf16 v[32:35], v[208:211], v[176:179], v[32:35]
	v_mfma_f32_16x16x32_bf16 v[20:23], v[200:203], v[184:187], v[20:23]
	v_mfma_f32_16x16x32_bf16 v[16:19], v[208:211], v[184:187], v[16:19]
	v_mfma_f32_16x16x32_bf16 v[4:7], v[200:203], v[192:195], v[4:7]
	v_mfma_f32_16x16x32_bf16 v[0:3], v[208:211], v[192:195], v[0:3]
	s_add_i32 s63, s63, 2
	s_add_u32 s46, s46, 0x100
	s_addc_u32 s47, s47, 0
	s_add_u32 s61, s61, 0x100
	s_addc_u32 s62, s62, 0
	s_cmp_gt_u32 s63, 29
	s_barrier
	s_cbranch_scc0 .LBB0_999
	v_lshl_add_u32 v144, s44, 8, v148
	v_ashrrev_i32_e32 v145, 31, v144
	v_lshl_add_u64 v[140:141], v[144:145], 2, s[14:15]
	global_load_dword v164, v[140:141], off
	v_lshl_or_b32 v146, s58, 8, v150
	v_ashrrev_i32_e32 v147, 31, v146
	v_lshlrev_b64 v[142:143], 11, v[144:145]
	v_lshl_add_u64 v[142:143], v[142:143], 0, v[146:147]
	v_lshlrev_b64 v[142:143], 1, v[142:143]
	v_lshl_add_u64 v[160:161], s[20:21], 0, v[142:143]
	global_load_dwordx4 v[154:157], v[160:161], off
	global_load_dwordx4 v[220:223], v[160:161], off offset:256
	v_lshl_add_u64 v[162:163], s[24:25], 0, v[142:143]
	s_and_b64 vcc, exec, s[38:39]
	s_mov_b32 s58, s34
	s_mov_b32 s44, s36
	s_mov_b64 s[48:49], s[42:43]
	s_mov_b64 s[46:47], s[40:41]
	s_waitcnt vmcnt(0)
	v_mul_f32_e32 v145, 0xbfb8aa3b, v164
	v_mul_f32_e32 v124, v124, v145
	v_mul_f32_e32 v120, v120, v145
	v_mul_f32_e32 v125, v125, v145
	v_mul_f32_e32 v121, v121, v145
	v_mul_f32_e32 v126, v126, v145
	v_mul_f32_e32 v122, v122, v145
	v_mul_f32_e32 v127, v127, v145
	v_mul_f32_e32 v123, v123, v145
	v_exp_f32_e32 v124, v124
	v_exp_f32_e32 v120, v120
	v_exp_f32_e32 v125, v125
	v_exp_f32_e32 v121, v121
	v_exp_f32_e32 v126, v126
	v_exp_f32_e32 v122, v122
	v_exp_f32_e32 v127, v127
	v_exp_f32_e32 v123, v123
	v_add_f32_e32 v124, 1.0, v124
	v_add_f32_e32 v120, 1.0, v120
	v_add_f32_e32 v125, 1.0, v125
	v_add_f32_e32 v121, 1.0, v121
	v_add_f32_e32 v126, 1.0, v126
	v_add_f32_e32 v122, 1.0, v122
	v_add_f32_e32 v127, 1.0, v127
	v_add_f32_e32 v123, 1.0, v123
	v_rcp_f32_e32 v124, v124
	v_rcp_f32_e32 v120, v120
	v_rcp_f32_e32 v125, v125
	v_rcp_f32_e32 v121, v121
	v_rcp_f32_e32 v126, v126
	v_rcp_f32_e32 v122, v122
	v_rcp_f32_e32 v127, v127
	v_rcp_f32_e32 v123, v123
	v_lshlrev_b32_e32 v164, 16, v154
	v_and_b32_e32 v154, 0xffff0000, v154
	v_lshlrev_b32_e32 v165, 16, v155
	v_and_b32_e32 v155, 0xffff0000, v155
	v_lshlrev_b32_e32 v166, 16, v156
	v_and_b32_e32 v156, 0xffff0000, v156
	v_lshlrev_b32_e32 v167, 16, v157
	v_and_b32_e32 v157, 0xffff0000, v157
	v_mul_f32_e32 v124, v124, v164
	v_mul_f32_e32 v164, v120, v166
	v_mul_f32_e32 v120, v125, v154
	v_mul_f32_e32 v125, v121, v156
	v_mul_f32_e32 v121, v126, v165
	v_mul_f32_e32 v126, v122, v167
	v_mul_f32_e32 v122, v127, v155
	v_mul_f32_e32 v123, v123, v157
	v_cvt_pk_bf16_f32 v120, v124, v120
	v_cvt_pk_bf16_f32 v121, v121, v122
	v_cvt_pk_bf16_f32 v122, v164, v125
	v_cvt_pk_bf16_f32 v123, v126, v123
	global_store_dwordx4 v[162:163], v[120:123], off
	v_mul_f32_e32 v116, v116, v145
	v_mul_f32_e32 v112, v112, v145
	v_mul_f32_e32 v117, v117, v145
	v_mul_f32_e32 v113, v113, v145
	v_mul_f32_e32 v118, v118, v145
	v_mul_f32_e32 v114, v114, v145
	v_mul_f32_e32 v119, v119, v145
	v_mul_f32_e32 v115, v115, v145
	v_exp_f32_e32 v116, v116
	v_exp_f32_e32 v112, v112
	v_exp_f32_e32 v117, v117
	v_exp_f32_e32 v113, v113
	v_exp_f32_e32 v118, v118
	v_exp_f32_e32 v114, v114
	v_exp_f32_e32 v119, v119
	v_exp_f32_e32 v115, v115
	v_add_f32_e32 v116, 1.0, v116
	v_add_f32_e32 v112, 1.0, v112
; __device__ __forceinline__ float bf_lo(unsigned w) { return __uint_as_float(w << 16); }
; __device__ __forceinline__ float bf_hi(unsigned w) { return __uint_as_float(w & 0xffff0000u); }
; __device__ __forceinline__ float fast_rcp(float x) { return __builtin_amdgcn_rcpf(x); }
; __device__ __forceinline__ float fast_exp2(float x) { return __builtin_amdgcn_exp2f(x); }
; __device__ __forceinline__ u32x4 pack8(f32x4 v0, f32x4 v1) { u32x4 w; w.x = cvt_pk_bf16(v0[0], v0[1]); w.y = cvt_pk_bf16(v0[2], v0[3]); w.z = cvt_pk_bf16(v1[0], v1[1]); w.w = cvt_pk_bf16(v1[2], v1[3]); return w; }
;     __device__ __forceinline__ void operator()(const f32x4 (&acc)[2][2][4][2], const Unit& u, int wr, int wc, int fr, int fq) const {
;         const int row0 = u.pm * BM + wr * 64 + fr, col0 = u.pn * BM + wc * 32 + 8 * fq;
; #pragma unroll
;         for (int ai = 0; ai < 2; ++ai)
; #pragma unroll
;             for (int m = 0; m < 4; ++m) { const size_t ro = (size_t)(row0 + ai * HALF + m * 16) * DM + col0; const float nr = -LOG2E * rs[row0 + ai * HALF + m * 16];
; #pragma unroll
;                 for (int bj = 0; bj < 2; ++bj) {
;                     const u32x4 pw = *(const u32x4*)(PP + ro + bj * HALF);
;                     const float pv[8] = {bf_lo(pw.x), bf_hi(pw.x), bf_lo(pw.y), bf_hi(pw.y), bf_lo(pw.z), bf_hi(pw.z), bf_lo(pw.w), bf_hi(pw.w)};
;                     f32x4 t0, t1;
; #pragma unroll
;                     for (int j = 0; j < 4; ++j) {
;                         t0[j] = fast_rcp(1.0f + fast_exp2(acc[ai][bj][m][0][j] * nr)) * pv[j];
;                         t1[j] = fast_rcp(1.0f + fast_exp2(acc[ai][bj][m][1][j] * nr)) * pv[4 + j]; }
;                     *(u32x4*)(O + ro + bj * HALF) = pack8(t0, t1); } }
	v_add_f32_e32 v117, 1.0, v117
	v_add_f32_e32 v113, 1.0, v113
	v_add_f32_e32 v118, 1.0, v118
	v_add_f32_e32 v114, 1.0, v114
	v_add_f32_e32 v119, 1.0, v119
	v_add_f32_e32 v115, 1.0, v115
	v_rcp_f32_e32 v116, v116
	v_rcp_f32_e32 v112, v112
	v_rcp_f32_e32 v117, v117
	v_rcp_f32_e32 v113, v113
	v_rcp_f32_e32 v118, v118
	v_rcp_f32_e32 v114, v114
	v_rcp_f32_e32 v119, v119
	v_rcp_f32_e32 v115, v115
	v_or_b32_e32 v124, 16, v144
	v_ashrrev_i32_e32 v125, 31, v124
	v_lshlrev_b64 v[124:125], 11, v[124:125]
	v_lshl_add_u64 v[124:125], v[124:125], 0, v[146:147]
	v_lshlrev_b64 v[124:125], 1, v[124:125]
	v_lshl_add_u64 v[126:127], s[20:21], 0, v[124:125]
	v_lshlrev_b32_e32 v145, 16, v220
	v_and_b32_e32 v120, 0xffff0000, v220
	v_lshlrev_b32_e32 v154, 16, v221
	v_and_b32_e32 v121, 0xffff0000, v221
	v_lshlrev_b32_e32 v155, 16, v222
	v_and_b32_e32 v122, 0xffff0000, v222
	v_lshlrev_b32_e32 v156, 16, v223
	v_and_b32_e32 v123, 0xffff0000, v223
	v_mul_f32_e32 v116, v116, v145
	v_mul_f32_e32 v145, v112, v155
	v_mul_f32_e32 v112, v117, v120
	v_mul_f32_e32 v117, v113, v122
	v_mul_f32_e32 v113, v118, v154
	v_mul_f32_e32 v118, v114, v156
	v_mul_f32_e32 v114, v119, v121
	v_mul_f32_e32 v115, v115, v123
	v_cvt_pk_bf16_f32 v112, v116, v112
	v_cvt_pk_bf16_f32 v113, v113, v114
	v_cvt_pk_bf16_f32 v114, v145, v117
	v_cvt_pk_bf16_f32 v115, v118, v115
	global_store_dwordx4 v[162:163], v[112:115], off offset:256
	global_load_dword v118, v[140:141], off offset:64
	s_nop 0
	global_load_dwordx4 v[112:115], v[126:127], off
	global_load_dwordx4 v[224:227], v[126:127], off offset:256
	v_lshl_add_u64 v[116:117], s[24:25], 0, v[124:125]
	s_waitcnt vmcnt(0)
	v_mul_f32_e32 v118, 0xbfb8aa3b, v118
	v_mul_f32_e32 v108, v108, v118
	v_mul_f32_e32 v104, v104, v118
	v_mul_f32_e32 v109, v109, v118
	v_mul_f32_e32 v105, v105, v118
	v_mul_f32_e32 v110, v110, v118
	v_mul_f32_e32 v106, v106, v118
	v_mul_f32_e32 v111, v111, v118
	v_mul_f32_e32 v107, v107, v118
	v_exp_f32_e32 v108, v108
	v_exp_f32_e32 v104, v104
	v_exp_f32_e32 v109, v109
	v_exp_f32_e32 v105, v105
	v_exp_f32_e32 v110, v110
	v_exp_f32_e32 v106, v106
	v_exp_f32_e32 v111, v111
	v_exp_f32_e32 v107, v107
	v_add_f32_e32 v108, 1.0, v108
	v_add_f32_e32 v104, 1.0, v104
	v_add_f32_e32 v109, 1.0, v109
	v_add_f32_e32 v105, 1.0, v105
	v_add_f32_e32 v110, 1.0, v110
	v_add_f32_e32 v106, 1.0, v106
	v_add_f32_e32 v111, 1.0, v111
	v_add_f32_e32 v107, 1.0, v107
	v_rcp_f32_e32 v108, v108
	v_rcp_f32_e32 v104, v104
	v_rcp_f32_e32 v109, v109
	v_rcp_f32_e32 v105, v105
	v_rcp_f32_e32 v110, v110
	v_rcp_f32_e32 v106, v106
	v_rcp_f32_e32 v111, v111
	v_rcp_f32_e32 v107, v107
	v_lshlrev_b32_e32 v119, 16, v112
	v_and_b32_e32 v112, 0xffff0000, v112
	v_lshlrev_b32_e32 v120, 16, v113
	v_and_b32_e32 v113, 0xffff0000, v113
	v_lshlrev_b32_e32 v121, 16, v114
	v_and_b32_e32 v114, 0xffff0000, v114
	v_lshlrev_b32_e32 v122, 16, v115
	v_and_b32_e32 v115, 0xffff0000, v115
	v_mul_f32_e32 v108, v108, v119
	v_mul_f32_e32 v119, v104, v121
	v_mul_f32_e32 v104, v109, v112
	v_mul_f32_e32 v109, v105, v114
	v_mul_f32_e32 v105, v110, v120
	v_mul_f32_e32 v110, v106, v122
	v_mul_f32_e32 v106, v111, v113
	v_mul_f32_e32 v107, v107, v115
	v_cvt_pk_bf16_f32 v104, v108, v104
	v_cvt_pk_bf16_f32 v105, v105, v106
	v_cvt_pk_bf16_f32 v106, v119, v109
	v_cvt_pk_bf16_f32 v107, v110, v107
	global_store_dwordx4 v[116:117], v[104:107], off
	v_mul_f32_e32 v100, v100, v118
	v_mul_f32_e32 v96, v96, v118
	v_mul_f32_e32 v101, v101, v118
	v_mul_f32_e32 v97, v97, v118
	v_mul_f32_e32 v102, v102, v118
	v_mul_f32_e32 v98, v98, v118
	v_mul_f32_e32 v103, v103, v118
	v_mul_f32_e32 v99, v99, v118
	v_exp_f32_e32 v100, v100
	v_exp_f32_e32 v96, v96
	v_exp_f32_e32 v101, v101
	v_exp_f32_e32 v97, v97
	v_exp_f32_e32 v102, v102
	v_exp_f32_e32 v98, v98
	v_exp_f32_e32 v103, v103
	v_exp_f32_e32 v99, v99
	v_add_f32_e32 v100, 1.0, v100
	v_add_f32_e32 v96, 1.0, v96
	v_add_f32_e32 v101, 1.0, v101
	v_add_f32_e32 v97, 1.0, v97
	v_add_f32_e32 v102, 1.0, v102
	v_add_f32_e32 v98, 1.0, v98
	v_add_f32_e32 v103, 1.0, v103
	v_add_f32_e32 v99, 1.0, v99
	v_rcp_f32_e32 v100, v100
	v_rcp_f32_e32 v96, v96
	v_rcp_f32_e32 v101, v101
	v_rcp_f32_e32 v97, v97
	v_rcp_f32_e32 v102, v102
	v_rcp_f32_e32 v98, v98
	v_rcp_f32_e32 v103, v103
	v_rcp_f32_e32 v99, v99
	v_or_b32_e32 v108, 32, v144
	v_ashrrev_i32_e32 v109, 31, v108
	v_lshlrev_b64 v[108:109], 11, v[108:109]
	v_lshl_add_u64 v[108:109], v[108:109], 0, v[146:147]
	v_lshlrev_b64 v[108:109], 1, v[108:109]
	v_lshl_add_u64 v[110:111], s[20:21], 0, v[108:109]
	v_lshlrev_b32_e32 v112, 16, v224
	v_and_b32_e32 v104, 0xffff0000, v224
	v_lshlrev_b32_e32 v113, 16, v225
	v_and_b32_e32 v105, 0xffff0000, v225
	v_lshlrev_b32_e32 v114, 16, v226
	v_and_b32_e32 v106, 0xffff0000, v226
	v_lshlrev_b32_e32 v115, 16, v227
	v_and_b32_e32 v107, 0xffff0000, v227
	v_mul_f32_e32 v100, v100, v112
	v_mul_f32_e32 v112, v96, v114
	v_mul_f32_e32 v96, v101, v104
	v_mul_f32_e32 v101, v97, v106
	v_mul_f32_e32 v97, v102, v113
	v_mul_f32_e32 v102, v98, v115
	v_mul_f32_e32 v98, v103, v105
	v_mul_f32_e32 v99, v99, v107
	v_cvt_pk_bf16_f32 v96, v100, v96
	v_cvt_pk_bf16_f32 v97, v97, v98
	v_cvt_pk_bf16_f32 v98, v112, v101
	v_cvt_pk_bf16_f32 v99, v102, v99
	global_store_dwordx4 v[116:117], v[96:99], off offset:256
	global_load_dword v102, v[140:141], off offset:128
	s_nop 0
	global_load_dwordx4 v[96:99], v[110:111], off
	global_load_dwordx4 v[220:223], v[110:111], off offset:256
	v_lshl_add_u64 v[100:101], s[24:25], 0, v[108:109]
	s_waitcnt vmcnt(0)
; __device__ __forceinline__ float bf_lo(unsigned w) { return __uint_as_float(w << 16); }
; __device__ __forceinline__ float bf_hi(unsigned w) { return __uint_as_float(w & 0xffff0000u); }
; __device__ __forceinline__ float fast_rcp(float x) { return __builtin_amdgcn_rcpf(x); }
; __device__ __forceinline__ float fast_exp2(float x) { return __builtin_amdgcn_exp2f(x); }
; __device__ __forceinline__ u32x4 pack8(f32x4 v0, f32x4 v1) { u32x4 w; w.x = cvt_pk_bf16(v0[0], v0[1]); w.y = cvt_pk_bf16(v0[2], v0[3]); w.z = cvt_pk_bf16(v1[0], v1[1]); w.w = cvt_pk_bf16(v1[2], v1[3]); return w; }
;     __device__ __forceinline__ void operator()(const f32x4 (&acc)[2][2][4][2], const Unit& u, int wr, int wc, int fr, int fq) const {
;         const int row0 = u.pm * BM + wr * 64 + fr, col0 = u.pn * BM + wc * 32 + 8 * fq;
; #pragma unroll
;         for (int ai = 0; ai < 2; ++ai)
; #pragma unroll
;             for (int m = 0; m < 4; ++m) { const size_t ro = (size_t)(row0 + ai * HALF + m * 16) * DM + col0; const float nr = -LOG2E * rs[row0 + ai * HALF + m * 16];
; #pragma unroll
;                 for (int bj = 0; bj < 2; ++bj) {
;                     const u32x4 pw = *(const u32x4*)(PP + ro + bj * HALF);
;                     const float pv[8] = {bf_lo(pw.x), bf_hi(pw.x), bf_lo(pw.y), bf_hi(pw.y), bf_lo(pw.z), bf_hi(pw.z), bf_lo(pw.w), bf_hi(pw.w)};
;                     f32x4 t0, t1;
; #pragma unroll
;                     for (int j = 0; j < 4; ++j) {
;                         t0[j] = fast_rcp(1.0f + fast_exp2(acc[ai][bj][m][0][j] * nr)) * pv[j];
;                         t1[j] = fast_rcp(1.0f + fast_exp2(acc[ai][bj][m][1][j] * nr)) * pv[4 + j]; }
;                     *(u32x4*)(O + ro + bj * HALF) = pack8(t0, t1); } }
	v_mul_f32_e32 v102, 0xbfb8aa3b, v102
	v_mul_f32_e32 v92, v92, v102
	v_mul_f32_e32 v88, v88, v102
	v_mul_f32_e32 v93, v93, v102
	v_mul_f32_e32 v89, v89, v102
	v_mul_f32_e32 v94, v94, v102
	v_mul_f32_e32 v90, v90, v102
	v_mul_f32_e32 v95, v95, v102
	v_mul_f32_e32 v91, v91, v102
	v_exp_f32_e32 v92, v92
	v_exp_f32_e32 v88, v88
	v_exp_f32_e32 v93, v93
	v_exp_f32_e32 v89, v89
	v_exp_f32_e32 v94, v94
	v_exp_f32_e32 v90, v90
	v_exp_f32_e32 v95, v95
	v_exp_f32_e32 v91, v91
	v_add_f32_e32 v92, 1.0, v92
	v_add_f32_e32 v88, 1.0, v88
	v_add_f32_e32 v93, 1.0, v93
	v_add_f32_e32 v89, 1.0, v89
	v_add_f32_e32 v94, 1.0, v94
	v_add_f32_e32 v90, 1.0, v90
	v_add_f32_e32 v95, 1.0, v95
	v_add_f32_e32 v91, 1.0, v91
	v_rcp_f32_e32 v92, v92
	v_rcp_f32_e32 v88, v88
	v_rcp_f32_e32 v93, v93
	v_rcp_f32_e32 v89, v89
	v_rcp_f32_e32 v94, v94
	v_rcp_f32_e32 v90, v90
	v_rcp_f32_e32 v95, v95
	v_rcp_f32_e32 v91, v91
	v_lshlrev_b32_e32 v103, 16, v96
	v_and_b32_e32 v96, 0xffff0000, v96
	v_lshlrev_b32_e32 v104, 16, v97
	v_and_b32_e32 v97, 0xffff0000, v97
	v_lshlrev_b32_e32 v105, 16, v98
	v_and_b32_e32 v98, 0xffff0000, v98
	v_lshlrev_b32_e32 v106, 16, v99
	v_and_b32_e32 v99, 0xffff0000, v99
	v_mul_f32_e32 v92, v92, v103
	v_mul_f32_e32 v103, v88, v105
	v_mul_f32_e32 v88, v93, v96
	v_mul_f32_e32 v93, v89, v98
	v_mul_f32_e32 v89, v94, v104
	v_mul_f32_e32 v94, v90, v106
	v_mul_f32_e32 v90, v95, v97
	v_mul_f32_e32 v91, v91, v99
	v_cvt_pk_bf16_f32 v88, v92, v88
	v_cvt_pk_bf16_f32 v89, v89, v90
	v_cvt_pk_bf16_f32 v90, v103, v93
	v_cvt_pk_bf16_f32 v91, v94, v91
	global_store_dwordx4 v[100:101], v[88:91], off
	v_mul_f32_e32 v84, v84, v102
	v_mul_f32_e32 v80, v80, v102
	v_mul_f32_e32 v85, v85, v102
	v_mul_f32_e32 v81, v81, v102
	v_mul_f32_e32 v86, v86, v102
	v_mul_f32_e32 v82, v82, v102
	v_mul_f32_e32 v87, v87, v102
	v_mul_f32_e32 v83, v83, v102
	v_exp_f32_e32 v84, v84
	v_exp_f32_e32 v80, v80
	v_exp_f32_e32 v85, v85
	v_exp_f32_e32 v81, v81
	v_exp_f32_e32 v86, v86
	v_exp_f32_e32 v82, v82
	v_exp_f32_e32 v87, v87
	v_exp_f32_e32 v83, v83
	v_add_f32_e32 v84, 1.0, v84
	v_add_f32_e32 v80, 1.0, v80
	v_add_f32_e32 v85, 1.0, v85
	v_add_f32_e32 v81, 1.0, v81
	v_add_f32_e32 v86, 1.0, v86
	v_add_f32_e32 v82, 1.0, v82
	v_add_f32_e32 v87, 1.0, v87
	v_add_f32_e32 v83, 1.0, v83
	v_rcp_f32_e32 v84, v84
	v_rcp_f32_e32 v80, v80
	v_rcp_f32_e32 v85, v85
	v_rcp_f32_e32 v81, v81
	v_rcp_f32_e32 v86, v86
	v_rcp_f32_e32 v82, v82
	v_rcp_f32_e32 v87, v87
	v_rcp_f32_e32 v83, v83
	v_or_b32_e32 v92, 48, v144
	v_ashrrev_i32_e32 v93, 31, v92
	v_lshlrev_b64 v[92:93], 11, v[92:93]
	v_lshl_add_u64 v[92:93], v[92:93], 0, v[146:147]
	v_lshlrev_b64 v[92:93], 1, v[92:93]
	v_lshl_add_u64 v[94:95], s[20:21], 0, v[92:93]
	v_lshlrev_b32_e32 v96, 16, v220
	v_and_b32_e32 v88, 0xffff0000, v220
	v_lshlrev_b32_e32 v97, 16, v221
	v_and_b32_e32 v89, 0xffff0000, v221
	v_lshlrev_b32_e32 v98, 16, v222
	v_and_b32_e32 v90, 0xffff0000, v222
	v_lshlrev_b32_e32 v99, 16, v223
	v_and_b32_e32 v91, 0xffff0000, v223
	v_mul_f32_e32 v84, v84, v96
	v_mul_f32_e32 v96, v80, v98
	v_mul_f32_e32 v80, v85, v88
	v_mul_f32_e32 v85, v81, v90
	v_mul_f32_e32 v81, v86, v97
	v_mul_f32_e32 v86, v82, v99
	v_mul_f32_e32 v82, v87, v89
	v_mul_f32_e32 v83, v83, v91
	v_cvt_pk_bf16_f32 v80, v84, v80
	v_cvt_pk_bf16_f32 v81, v81, v82
	v_cvt_pk_bf16_f32 v82, v96, v85
	v_cvt_pk_bf16_f32 v83, v86, v83
	global_store_dwordx4 v[100:101], v[80:83], off offset:256
	global_load_dword v86, v[140:141], off offset:192
	s_nop 0
	global_load_dwordx4 v[80:83], v[94:95], off
	global_load_dwordx4 v[224:227], v[94:95], off offset:256
	v_lshl_add_u64 v[84:85], s[24:25], 0, v[92:93]
	s_waitcnt vmcnt(0)
	v_mul_f32_e32 v86, 0xbfb8aa3b, v86
	v_mul_f32_e32 v76, v76, v86
	v_mul_f32_e32 v72, v72, v86
	v_mul_f32_e32 v77, v77, v86
	v_mul_f32_e32 v73, v73, v86
	v_mul_f32_e32 v78, v78, v86
	v_mul_f32_e32 v74, v74, v86
	v_mul_f32_e32 v79, v79, v86
	v_mul_f32_e32 v75, v75, v86
	v_exp_f32_e32 v76, v76
	v_exp_f32_e32 v72, v72
	v_exp_f32_e32 v77, v77
	v_exp_f32_e32 v73, v73
	v_exp_f32_e32 v78, v78
	v_exp_f32_e32 v74, v74
	v_exp_f32_e32 v79, v79
	v_exp_f32_e32 v75, v75
	v_add_f32_e32 v76, 1.0, v76
	v_add_f32_e32 v72, 1.0, v72
	v_add_f32_e32 v77, 1.0, v77
	v_add_f32_e32 v73, 1.0, v73
	v_add_f32_e32 v78, 1.0, v78
	v_add_f32_e32 v74, 1.0, v74
	v_add_f32_e32 v79, 1.0, v79
	v_add_f32_e32 v75, 1.0, v75
	v_rcp_f32_e32 v76, v76
	v_rcp_f32_e32 v72, v72
	v_rcp_f32_e32 v77, v77
	v_rcp_f32_e32 v73, v73
	v_rcp_f32_e32 v78, v78
	v_rcp_f32_e32 v74, v74
	v_rcp_f32_e32 v79, v79
	v_rcp_f32_e32 v75, v75
	v_lshlrev_b32_e32 v87, 16, v80
	v_and_b32_e32 v80, 0xffff0000, v80
	v_lshlrev_b32_e32 v88, 16, v81
	v_and_b32_e32 v81, 0xffff0000, v81
	v_lshlrev_b32_e32 v89, 16, v82
	v_and_b32_e32 v82, 0xffff0000, v82
	v_lshlrev_b32_e32 v90, 16, v83
	v_and_b32_e32 v83, 0xffff0000, v83
	v_mul_f32_e32 v76, v76, v87
	v_mul_f32_e32 v87, v72, v89
	v_mul_f32_e32 v72, v77, v80
	v_mul_f32_e32 v77, v73, v82
	v_mul_f32_e32 v73, v78, v88
	v_mul_f32_e32 v78, v74, v90
	v_mul_f32_e32 v74, v79, v81
	v_mul_f32_e32 v75, v75, v83
	v_cvt_pk_bf16_f32 v72, v76, v72
	v_cvt_pk_bf16_f32 v73, v73, v74
	v_cvt_pk_bf16_f32 v74, v87, v77
	v_cvt_pk_bf16_f32 v75, v78, v75
	global_store_dwordx4 v[84:85], v[72:75], off
	v_mul_f32_e32 v68, v68, v86
	v_mul_f32_e32 v64, v64, v86
	v_mul_f32_e32 v69, v69, v86
	v_mul_f32_e32 v65, v65, v86
	v_mul_f32_e32 v70, v70, v86
	v_mul_f32_e32 v66, v66, v86
	v_mul_f32_e32 v71, v71, v86
	v_mul_f32_e32 v67, v67, v86
	v_exp_f32_e32 v68, v68
	v_exp_f32_e32 v64, v64
	v_exp_f32_e32 v69, v69
	v_exp_f32_e32 v65, v65
	v_exp_f32_e32 v70, v70
	v_exp_f32_e32 v66, v66
	v_exp_f32_e32 v71, v71
	v_exp_f32_e32 v67, v67
	v_add_f32_e32 v68, 1.0, v68
; __device__ __forceinline__ float bf_lo(unsigned w) { return __uint_as_float(w << 16); }
; __device__ __forceinline__ float bf_hi(unsigned w) { return __uint_as_float(w & 0xffff0000u); }
; __device__ __forceinline__ float fast_rcp(float x) { return __builtin_amdgcn_rcpf(x); }
; __device__ __forceinline__ float fast_exp2(float x) { return __builtin_amdgcn_exp2f(x); }
; __device__ __forceinline__ u32x4 pack8(f32x4 v0, f32x4 v1) { u32x4 w; w.x = cvt_pk_bf16(v0[0], v0[1]); w.y = cvt_pk_bf16(v0[2], v0[3]); w.z = cvt_pk_bf16(v1[0], v1[1]); w.w = cvt_pk_bf16(v1[2], v1[3]); return w; }
;     __device__ __forceinline__ void operator()(const f32x4 (&acc)[2][2][4][2], const Unit& u, int wr, int wc, int fr, int fq) const {
;         const int row0 = u.pm * BM + wr * 64 + fr, col0 = u.pn * BM + wc * 32 + 8 * fq;
; #pragma unroll
;         for (int ai = 0; ai < 2; ++ai)
; #pragma unroll
;             for (int m = 0; m < 4; ++m) { const size_t ro = (size_t)(row0 + ai * HALF + m * 16) * DM + col0; const float nr = -LOG2E * rs[row0 + ai * HALF + m * 16];
; #pragma unroll
;                 for (int bj = 0; bj < 2; ++bj) {
;                     const u32x4 pw = *(const u32x4*)(PP + ro + bj * HALF);
;                     const float pv[8] = {bf_lo(pw.x), bf_hi(pw.x), bf_lo(pw.y), bf_hi(pw.y), bf_lo(pw.z), bf_hi(pw.z), bf_lo(pw.w), bf_hi(pw.w)};
;                     f32x4 t0, t1;
; #pragma unroll
;                     for (int j = 0; j < 4; ++j) {
;                         t0[j] = fast_rcp(1.0f + fast_exp2(acc[ai][bj][m][0][j] * nr)) * pv[j];
;                         t1[j] = fast_rcp(1.0f + fast_exp2(acc[ai][bj][m][1][j] * nr)) * pv[4 + j]; }
;                     *(u32x4*)(O + ro + bj * HALF) = pack8(t0, t1); } }
	v_add_f32_e32 v64, 1.0, v64
	v_add_f32_e32 v69, 1.0, v69
	v_add_f32_e32 v65, 1.0, v65
	v_add_f32_e32 v70, 1.0, v70
	v_add_f32_e32 v66, 1.0, v66
	v_add_f32_e32 v71, 1.0, v71
	v_add_f32_e32 v67, 1.0, v67
	v_rcp_f32_e32 v68, v68
	v_rcp_f32_e32 v64, v64
	v_rcp_f32_e32 v69, v69
	v_rcp_f32_e32 v65, v65
	v_rcp_f32_e32 v70, v70
	v_rcp_f32_e32 v66, v66
	v_rcp_f32_e32 v71, v71
	v_rcp_f32_e32 v67, v67
	v_lshl_add_u64 v[76:77], v[142:143], 0, s[2:3]
	v_lshl_add_u64 v[78:79], s[20:21], 0, v[76:77]
	v_lshlrev_b32_e32 v80, 16, v224
	v_and_b32_e32 v72, 0xffff0000, v224
	v_lshlrev_b32_e32 v81, 16, v225
	v_and_b32_e32 v73, 0xffff0000, v225
	v_lshlrev_b32_e32 v82, 16, v226
	v_and_b32_e32 v74, 0xffff0000, v226
	v_lshlrev_b32_e32 v83, 16, v227
	v_and_b32_e32 v75, 0xffff0000, v227
	v_mul_f32_e32 v68, v68, v80
	v_mul_f32_e32 v80, v64, v82
	v_mul_f32_e32 v64, v69, v72
	v_mul_f32_e32 v69, v65, v74
	v_mul_f32_e32 v65, v70, v81
	v_mul_f32_e32 v70, v66, v83
	v_mul_f32_e32 v66, v71, v73
	v_mul_f32_e32 v67, v67, v75
	v_cvt_pk_bf16_f32 v64, v68, v64
	v_cvt_pk_bf16_f32 v65, v65, v66
	v_cvt_pk_bf16_f32 v66, v80, v69
	v_cvt_pk_bf16_f32 v67, v70, v67
	global_store_dwordx4 v[84:85], v[64:67], off offset:256
	global_load_dword v70, v[140:141], off offset:512
	s_nop 0
	global_load_dwordx4 v[64:67], v[78:79], off
	global_load_dwordx4 v[220:223], v[78:79], off offset:256
	v_lshl_add_u64 v[68:69], s[24:25], 0, v[76:77]
	s_waitcnt vmcnt(0)
	v_mul_f32_e32 v70, 0xbfb8aa3b, v70
	v_mul_f32_e32 v60, v60, v70
	v_mul_f32_e32 v56, v56, v70
	v_mul_f32_e32 v61, v61, v70
	v_mul_f32_e32 v57, v57, v70
	v_mul_f32_e32 v62, v62, v70
	v_mul_f32_e32 v58, v58, v70
	v_mul_f32_e32 v63, v63, v70
	v_mul_f32_e32 v59, v59, v70
	v_exp_f32_e32 v60, v60
	v_exp_f32_e32 v56, v56
	v_exp_f32_e32 v61, v61
	v_exp_f32_e32 v57, v57
	v_exp_f32_e32 v62, v62
	v_exp_f32_e32 v58, v58
	v_exp_f32_e32 v63, v63
	v_exp_f32_e32 v59, v59
	v_add_f32_e32 v60, 1.0, v60
	v_add_f32_e32 v56, 1.0, v56
	v_add_f32_e32 v61, 1.0, v61
	v_add_f32_e32 v57, 1.0, v57
	v_add_f32_e32 v62, 1.0, v62
	v_add_f32_e32 v58, 1.0, v58
	v_add_f32_e32 v63, 1.0, v63
	v_add_f32_e32 v59, 1.0, v59
	v_rcp_f32_e32 v60, v60
	v_rcp_f32_e32 v56, v56
	v_rcp_f32_e32 v61, v61
	v_rcp_f32_e32 v57, v57
	v_rcp_f32_e32 v62, v62
	v_rcp_f32_e32 v58, v58
	v_rcp_f32_e32 v63, v63
	v_rcp_f32_e32 v59, v59
	v_lshlrev_b32_e32 v71, 16, v64
	v_and_b32_e32 v64, 0xffff0000, v64
	v_lshlrev_b32_e32 v72, 16, v65
	v_and_b32_e32 v65, 0xffff0000, v65
	v_lshlrev_b32_e32 v73, 16, v66
	v_and_b32_e32 v66, 0xffff0000, v66
	v_lshlrev_b32_e32 v74, 16, v67
	v_and_b32_e32 v67, 0xffff0000, v67
	v_mul_f32_e32 v60, v60, v71
	v_mul_f32_e32 v71, v56, v73
	v_mul_f32_e32 v56, v61, v64
	v_mul_f32_e32 v61, v57, v66
	v_mul_f32_e32 v57, v62, v72
	v_mul_f32_e32 v62, v58, v74
	v_mul_f32_e32 v58, v63, v65
	v_mul_f32_e32 v59, v59, v67
	v_cvt_pk_bf16_f32 v56, v60, v56
	v_cvt_pk_bf16_f32 v57, v57, v58
	v_cvt_pk_bf16_f32 v58, v71, v61
	v_cvt_pk_bf16_f32 v59, v62, v59
	global_store_dwordx4 v[68:69], v[56:59], off
	v_mul_f32_e32 v52, v52, v70
	v_mul_f32_e32 v48, v48, v70
	v_mul_f32_e32 v53, v53, v70
	v_mul_f32_e32 v49, v49, v70
	v_mul_f32_e32 v54, v54, v70
	v_mul_f32_e32 v50, v50, v70
	v_mul_f32_e32 v55, v55, v70
	v_mul_f32_e32 v51, v51, v70
	v_exp_f32_e32 v52, v52
	v_exp_f32_e32 v48, v48
	v_exp_f32_e32 v53, v53
	v_exp_f32_e32 v49, v49
	v_exp_f32_e32 v54, v54
	v_exp_f32_e32 v50, v50
	v_exp_f32_e32 v55, v55
	v_exp_f32_e32 v51, v51
	v_add_f32_e32 v52, 1.0, v52
	v_add_f32_e32 v48, 1.0, v48
	v_add_f32_e32 v53, 1.0, v53
	v_add_f32_e32 v49, 1.0, v49
	v_add_f32_e32 v54, 1.0, v54
	v_add_f32_e32 v50, 1.0, v50
	v_add_f32_e32 v55, 1.0, v55
	v_add_f32_e32 v51, 1.0, v51
	v_rcp_f32_e32 v52, v52
	v_rcp_f32_e32 v48, v48
	v_rcp_f32_e32 v53, v53
	v_rcp_f32_e32 v49, v49
	v_rcp_f32_e32 v54, v54
	v_rcp_f32_e32 v50, v50
	v_rcp_f32_e32 v55, v55
	v_rcp_f32_e32 v51, v51
	v_lshl_add_u64 v[60:61], v[142:143], 0, s[6:7]
	v_lshl_add_u64 v[62:63], s[20:21], 0, v[60:61]
	v_lshlrev_b32_e32 v64, 16, v220
	v_and_b32_e32 v56, 0xffff0000, v220
	v_lshlrev_b32_e32 v65, 16, v221
	v_and_b32_e32 v57, 0xffff0000, v221
	v_lshlrev_b32_e32 v66, 16, v222
	v_and_b32_e32 v58, 0xffff0000, v222
	v_lshlrev_b32_e32 v67, 16, v223
	v_and_b32_e32 v59, 0xffff0000, v223
	v_mul_f32_e32 v52, v52, v64
	v_mul_f32_e32 v64, v48, v66
	v_mul_f32_e32 v48, v53, v56
	v_mul_f32_e32 v53, v49, v58
	v_mul_f32_e32 v49, v54, v65
	v_mul_f32_e32 v54, v50, v67
	v_mul_f32_e32 v50, v55, v57
	v_mul_f32_e32 v51, v51, v59
	v_cvt_pk_bf16_f32 v48, v52, v48
	v_cvt_pk_bf16_f32 v49, v49, v50
	v_cvt_pk_bf16_f32 v50, v64, v53
	v_cvt_pk_bf16_f32 v51, v54, v51
	global_store_dwordx4 v[68:69], v[48:51], off offset:256
	global_load_dword v54, v[140:141], off offset:576
	s_nop 0
	global_load_dwordx4 v[48:51], v[62:63], off
	global_load_dwordx4 v[224:227], v[62:63], off offset:256
	v_lshl_add_u64 v[52:53], s[24:25], 0, v[60:61]
	s_waitcnt vmcnt(0)
; __device__ __forceinline__ float bf_lo(unsigned w) { return __uint_as_float(w << 16); }
; __device__ __forceinline__ float bf_hi(unsigned w) { return __uint_as_float(w & 0xffff0000u); }
; __device__ __forceinline__ float fast_rcp(float x) { return __builtin_amdgcn_rcpf(x); }
; __device__ __forceinline__ float fast_exp2(float x) { return __builtin_amdgcn_exp2f(x); }
; __device__ __forceinline__ u32x4 pack8(f32x4 v0, f32x4 v1) { u32x4 w; w.x = cvt_pk_bf16(v0[0], v0[1]); w.y = cvt_pk_bf16(v0[2], v0[3]); w.z = cvt_pk_bf16(v1[0], v1[1]); w.w = cvt_pk_bf16(v1[2], v1[3]); return w; }
;     __device__ __forceinline__ void operator()(const f32x4 (&acc)[2][2][4][2], const Unit& u, int wr, int wc, int fr, int fq) const {
;         const int row0 = u.pm * BM + wr * 64 + fr, col0 = u.pn * BM + wc * 32 + 8 * fq;
; #pragma unroll
;         for (int ai = 0; ai < 2; ++ai)
; #pragma unroll
;             for (int m = 0; m < 4; ++m) { const size_t ro = (size_t)(row0 + ai * HALF + m * 16) * DM + col0; const float nr = -LOG2E * rs[row0 + ai * HALF + m * 16];
; #pragma unroll
;                 for (int bj = 0; bj < 2; ++bj) {
;                     const u32x4 pw = *(const u32x4*)(PP + ro + bj * HALF);
;                     const float pv[8] = {bf_lo(pw.x), bf_hi(pw.x), bf_lo(pw.y), bf_hi(pw.y), bf_lo(pw.z), bf_hi(pw.z), bf_lo(pw.w), bf_hi(pw.w)};
;                     f32x4 t0, t1;
; #pragma unroll
;                     for (int j = 0; j < 4; ++j) {
;                         t0[j] = fast_rcp(1.0f + fast_exp2(acc[ai][bj][m][0][j] * nr)) * pv[j];
;                         t1[j] = fast_rcp(1.0f + fast_exp2(acc[ai][bj][m][1][j] * nr)) * pv[4 + j]; }
;                     *(u32x4*)(O + ro + bj * HALF) = pack8(t0, t1); } }
	v_mul_f32_e32 v54, 0xbfb8aa3b, v54
	v_mul_f32_e32 v44, v44, v54
	v_mul_f32_e32 v40, v40, v54
	v_mul_f32_e32 v45, v45, v54
	v_mul_f32_e32 v41, v41, v54
	v_mul_f32_e32 v46, v46, v54
	v_mul_f32_e32 v42, v42, v54
	v_mul_f32_e32 v47, v47, v54
	v_mul_f32_e32 v43, v43, v54
	v_exp_f32_e32 v44, v44
	v_exp_f32_e32 v40, v40
	v_exp_f32_e32 v45, v45
	v_exp_f32_e32 v41, v41
	v_exp_f32_e32 v46, v46
	v_exp_f32_e32 v42, v42
	v_exp_f32_e32 v47, v47
	v_exp_f32_e32 v43, v43
	v_add_f32_e32 v44, 1.0, v44
	v_add_f32_e32 v40, 1.0, v40
	v_add_f32_e32 v45, 1.0, v45
	v_add_f32_e32 v41, 1.0, v41
	v_add_f32_e32 v46, 1.0, v46
	v_add_f32_e32 v42, 1.0, v42
	v_add_f32_e32 v47, 1.0, v47
	v_add_f32_e32 v43, 1.0, v43
	v_rcp_f32_e32 v44, v44
	v_rcp_f32_e32 v40, v40
	v_rcp_f32_e32 v45, v45
	v_rcp_f32_e32 v41, v41
	v_rcp_f32_e32 v46, v46
	v_rcp_f32_e32 v42, v42
	v_rcp_f32_e32 v47, v47
	v_rcp_f32_e32 v43, v43
	v_lshlrev_b32_e32 v55, 16, v48
	v_and_b32_e32 v48, 0xffff0000, v48
	v_lshlrev_b32_e32 v56, 16, v49
	v_and_b32_e32 v49, 0xffff0000, v49
	v_lshlrev_b32_e32 v57, 16, v50
	v_and_b32_e32 v50, 0xffff0000, v50
	v_lshlrev_b32_e32 v58, 16, v51
	v_and_b32_e32 v51, 0xffff0000, v51
	v_mul_f32_e32 v44, v44, v55
	v_mul_f32_e32 v55, v40, v57
	v_mul_f32_e32 v40, v45, v48
	v_mul_f32_e32 v45, v41, v50
	v_mul_f32_e32 v41, v46, v56
	v_mul_f32_e32 v46, v42, v58
	v_mul_f32_e32 v42, v47, v49
	v_mul_f32_e32 v43, v43, v51
	v_cvt_pk_bf16_f32 v40, v44, v40
	v_cvt_pk_bf16_f32 v41, v41, v42
	v_cvt_pk_bf16_f32 v42, v55, v45
	v_cvt_pk_bf16_f32 v43, v46, v43
	global_store_dwordx4 v[52:53], v[40:43], off
	v_mul_f32_e32 v36, v36, v54
	v_mul_f32_e32 v32, v32, v54
	v_mul_f32_e32 v37, v37, v54
	v_mul_f32_e32 v33, v33, v54
	v_mul_f32_e32 v38, v38, v54
	v_mul_f32_e32 v34, v34, v54
	v_mul_f32_e32 v39, v39, v54
	v_mul_f32_e32 v35, v35, v54
	v_exp_f32_e32 v36, v36
	v_exp_f32_e32 v32, v32
	v_exp_f32_e32 v37, v37
	v_exp_f32_e32 v33, v33
	v_exp_f32_e32 v38, v38
	v_exp_f32_e32 v34, v34
	v_exp_f32_e32 v39, v39
	v_exp_f32_e32 v35, v35
	v_add_f32_e32 v36, 1.0, v36
	v_add_f32_e32 v32, 1.0, v32
	v_add_f32_e32 v37, 1.0, v37
	v_add_f32_e32 v33, 1.0, v33
	v_add_f32_e32 v38, 1.0, v38
	v_add_f32_e32 v34, 1.0, v34
	v_add_f32_e32 v39, 1.0, v39
	v_add_f32_e32 v35, 1.0, v35
	v_rcp_f32_e32 v36, v36
	v_rcp_f32_e32 v32, v32
	v_rcp_f32_e32 v37, v37
	v_rcp_f32_e32 v33, v33
	v_rcp_f32_e32 v38, v38
	v_rcp_f32_e32 v34, v34
	v_rcp_f32_e32 v39, v39
	v_rcp_f32_e32 v35, v35
	v_lshl_add_u64 v[44:45], v[142:143], 0, s[8:9]
	v_lshl_add_u64 v[46:47], s[20:21], 0, v[44:45]
	v_lshlrev_b32_e32 v48, 16, v224
	v_and_b32_e32 v40, 0xffff0000, v224
	v_lshlrev_b32_e32 v49, 16, v225
	v_and_b32_e32 v41, 0xffff0000, v225
	v_lshlrev_b32_e32 v50, 16, v226
	v_and_b32_e32 v42, 0xffff0000, v226
	v_lshlrev_b32_e32 v51, 16, v227
	v_and_b32_e32 v43, 0xffff0000, v227
	v_mul_f32_e32 v36, v36, v48
	v_mul_f32_e32 v48, v32, v50
	v_mul_f32_e32 v32, v37, v40
	v_mul_f32_e32 v37, v33, v42
	v_mul_f32_e32 v33, v38, v49
	v_mul_f32_e32 v38, v34, v51
	v_mul_f32_e32 v34, v39, v41
	v_mul_f32_e32 v35, v35, v43
	v_cvt_pk_bf16_f32 v32, v36, v32
	v_cvt_pk_bf16_f32 v33, v33, v34
	v_cvt_pk_bf16_f32 v34, v48, v37
	v_cvt_pk_bf16_f32 v35, v38, v35
	global_store_dwordx4 v[52:53], v[32:35], off offset:256
	global_load_dword v38, v[140:141], off offset:640
	s_nop 0
	global_load_dwordx4 v[32:35], v[46:47], off
	global_load_dwordx4 v[220:223], v[46:47], off offset:256
	v_lshl_add_u64 v[36:37], s[24:25], 0, v[44:45]
	s_waitcnt vmcnt(0)
; __device__ __forceinline__ float bf_lo(unsigned w) { return __uint_as_float(w << 16); }
; __device__ __forceinline__ float bf_hi(unsigned w) { return __uint_as_float(w & 0xffff0000u); }
; __device__ __forceinline__ float fast_rcp(float x) { return __builtin_amdgcn_rcpf(x); }
; __device__ __forceinline__ float fast_exp2(float x) { return __builtin_amdgcn_exp2f(x); }
; #define PG8_WAIT_V(n) asm volatile("s_waitcnt vmcnt(" #n ")" ::: "memory")
; #define PG8_BAR __builtin_amdgcn_s_barrier()
; template <class Epi>
; __device__ __forceinline__ void gemm_phase(LAS unsigned char* lds, const Gemm g, const StaticOrder& S, const Epi& E) {
;     ...
;         if (!has_next) break;
; #pragma unroll
;         for (int a = 0; a < 2; ++a)
; #pragma unroll
;             for (int b = 0; b < 2; ++b)
; #pragma unroll
;                 for (int m = 0; m < 4; ++m)
; #pragma unroll
;                     for (int n = 0; n < 2; ++n) acc[a][b][m][n] = (f32x4){0.f, 0.f, 0.f, 0.f};
;         cur = nxt; cA = nA; cB = nB; ++ui;
;     }
;     PG8_WAIT_V(0);
;     if (wr == 0) PG8_BAR;
;     PG8_BAR;
;     __device__ __forceinline__ void operator()(const f32x4 (&acc)[2][2][4][2], const Unit& u, int wr, int wc, int fr, int fq) const {
;         const int row0 = u.pm * BM + wr * 64 + fr, col0 = u.pn * BM + wc * 32 + 8 * fq;
; #pragma unroll
;         for (int ai = 0; ai < 2; ++ai)
; #pragma unroll
;             for (int m = 0; m < 4; ++m) { const size_t ro = (size_t)(row0 + ai * HALF + m * 16) * DM + col0; const float nr = -LOG2E * rs[row0 + ai * HALF + m * 16];
; #pragma unroll
;                 for (int bj = 0; bj < 2; ++bj) {
;                     const u32x4 pw = *(const u32x4*)(PP + ro + bj * HALF);
;                     const float pv[8] = {bf_lo(pw.x), bf_hi(pw.x), bf_lo(pw.y), bf_hi(pw.y), bf_lo(pw.z), bf_hi(pw.z), bf_lo(pw.w), bf_hi(pw.w)};
;                     f32x4 t0, t1;
; #pragma unroll
;                     for (int j = 0; j < 4; ++j) {
;                         t0[j] = fast_rcp(1.0f + fast_exp2(acc[ai][bj][m][0][j] * nr)) * pv[j];
;                         t1[j] = fast_rcp(1.0f + fast_exp2(acc[ai][bj][m][1][j] * nr)) * pv[4 + j]; }
;                     *(u32x4*)(O + ro + bj * HALF) = pack8(t0, t1); } }
	v_mul_f32_e32 v38, 0xbfb8aa3b, v38
	v_mul_f32_e32 v28, v28, v38
	v_mul_f32_e32 v24, v24, v38
	v_mul_f32_e32 v29, v29, v38
	v_mul_f32_e32 v25, v25, v38
	v_mul_f32_e32 v30, v30, v38
	v_mul_f32_e32 v26, v26, v38
	v_mul_f32_e32 v31, v31, v38
	v_mul_f32_e32 v27, v27, v38
	v_exp_f32_e32 v28, v28
	v_exp_f32_e32 v24, v24
	v_exp_f32_e32 v29, v29
	v_exp_f32_e32 v25, v25
	v_exp_f32_e32 v30, v30
	v_exp_f32_e32 v26, v26
	v_exp_f32_e32 v31, v31
	v_exp_f32_e32 v27, v27
	v_add_f32_e32 v28, 1.0, v28
	v_add_f32_e32 v24, 1.0, v24
	v_add_f32_e32 v29, 1.0, v29
	v_add_f32_e32 v25, 1.0, v25
	v_add_f32_e32 v30, 1.0, v30
	v_add_f32_e32 v26, 1.0, v26
	v_add_f32_e32 v31, 1.0, v31
	v_add_f32_e32 v27, 1.0, v27
	v_rcp_f32_e32 v28, v28
	v_rcp_f32_e32 v24, v24
	v_rcp_f32_e32 v29, v29
	v_rcp_f32_e32 v25, v25
	v_rcp_f32_e32 v30, v30
	v_rcp_f32_e32 v26, v26
	v_rcp_f32_e32 v31, v31
	v_rcp_f32_e32 v27, v27
	v_lshlrev_b32_e32 v39, 16, v32
	v_and_b32_e32 v32, 0xffff0000, v32
	v_lshlrev_b32_e32 v40, 16, v33
	v_and_b32_e32 v33, 0xffff0000, v33
	v_lshlrev_b32_e32 v41, 16, v34
	v_and_b32_e32 v34, 0xffff0000, v34
	v_lshlrev_b32_e32 v42, 16, v35
	v_and_b32_e32 v35, 0xffff0000, v35
	v_mul_f32_e32 v28, v28, v39
	v_mul_f32_e32 v39, v24, v41
	v_mul_f32_e32 v24, v29, v32
	v_mul_f32_e32 v29, v25, v34
	v_mul_f32_e32 v25, v30, v40
	v_mul_f32_e32 v30, v26, v42
	v_mul_f32_e32 v26, v31, v33
	v_mul_f32_e32 v27, v27, v35
	v_cvt_pk_bf16_f32 v24, v28, v24
	v_cvt_pk_bf16_f32 v25, v25, v26
	v_cvt_pk_bf16_f32 v26, v39, v29
	v_cvt_pk_bf16_f32 v27, v30, v27
	global_store_dwordx4 v[36:37], v[24:27], off
	v_mul_f32_e32 v20, v20, v38
	v_mul_f32_e32 v16, v16, v38
	v_mul_f32_e32 v21, v21, v38
	v_mul_f32_e32 v17, v17, v38
	v_mul_f32_e32 v22, v22, v38
	v_mul_f32_e32 v18, v18, v38
	v_mul_f32_e32 v23, v23, v38
	v_mul_f32_e32 v19, v19, v38
	v_exp_f32_e32 v20, v20
	v_exp_f32_e32 v16, v16
	v_exp_f32_e32 v21, v21
	v_exp_f32_e32 v17, v17
	v_exp_f32_e32 v22, v22
	v_exp_f32_e32 v18, v18
	v_exp_f32_e32 v23, v23
	v_exp_f32_e32 v19, v19
	v_add_f32_e32 v20, 1.0, v20
	v_add_f32_e32 v16, 1.0, v16
	v_add_f32_e32 v21, 1.0, v21
	v_add_f32_e32 v17, 1.0, v17
	v_add_f32_e32 v22, 1.0, v22
	v_add_f32_e32 v18, 1.0, v18
	v_add_f32_e32 v23, 1.0, v23
	v_add_f32_e32 v19, 1.0, v19
	v_rcp_f32_e32 v20, v20
	v_rcp_f32_e32 v16, v16
	v_rcp_f32_e32 v21, v21
	v_rcp_f32_e32 v17, v17
	v_rcp_f32_e32 v22, v22
	v_rcp_f32_e32 v18, v18
	v_rcp_f32_e32 v23, v23
	v_rcp_f32_e32 v19, v19
	v_lshl_add_u64 v[28:29], v[142:143], 0, s[30:31]
	v_lshl_add_u64 v[30:31], s[20:21], 0, v[28:29]
	v_lshlrev_b32_e32 v32, 16, v220
	v_and_b32_e32 v24, 0xffff0000, v220
	v_lshlrev_b32_e32 v33, 16, v221
	v_and_b32_e32 v25, 0xffff0000, v221
	v_lshlrev_b32_e32 v34, 16, v222
	v_and_b32_e32 v26, 0xffff0000, v222
	v_lshlrev_b32_e32 v35, 16, v223
	v_and_b32_e32 v27, 0xffff0000, v223
	v_mul_f32_e32 v20, v20, v32
	v_mul_f32_e32 v32, v16, v34
	v_mul_f32_e32 v16, v21, v24
	v_mul_f32_e32 v21, v17, v26
	v_mul_f32_e32 v17, v22, v33
	v_mul_f32_e32 v22, v18, v35
	v_mul_f32_e32 v18, v23, v25
	v_mul_f32_e32 v19, v19, v27
	v_cvt_pk_bf16_f32 v16, v20, v16
	v_cvt_pk_bf16_f32 v17, v17, v18
	v_cvt_pk_bf16_f32 v18, v32, v21
	v_cvt_pk_bf16_f32 v19, v22, v19
	global_store_dwordx4 v[36:37], v[16:19], off offset:256
	global_load_dword v22, v[140:141], off offset:704
	s_nop 0
	global_load_dwordx4 v[16:19], v[30:31], off
	global_load_dwordx4 v[224:227], v[30:31], off offset:256
	v_lshl_add_u64 v[20:21], s[24:25], 0, v[28:29]
	s_waitcnt vmcnt(0)
	v_mul_f32_e32 v22, 0xbfb8aa3b, v22
	v_mul_f32_e32 v12, v12, v22
	v_mul_f32_e32 v8, v8, v22
	v_mul_f32_e32 v13, v13, v22
	v_mul_f32_e32 v9, v9, v22
	v_mul_f32_e32 v14, v14, v22
	v_mul_f32_e32 v10, v10, v22
	v_mul_f32_e32 v15, v15, v22
	v_mul_f32_e32 v11, v11, v22
	v_exp_f32_e32 v12, v12
	v_exp_f32_e32 v8, v8
	v_exp_f32_e32 v13, v13
	v_exp_f32_e32 v9, v9
	v_exp_f32_e32 v14, v14
	v_exp_f32_e32 v10, v10
	v_exp_f32_e32 v15, v15
	v_exp_f32_e32 v11, v11
	v_add_f32_e32 v12, 1.0, v12
	v_add_f32_e32 v8, 1.0, v8
	v_add_f32_e32 v13, 1.0, v13
	v_add_f32_e32 v9, 1.0, v9
	v_add_f32_e32 v14, 1.0, v14
	v_add_f32_e32 v10, 1.0, v10
	v_add_f32_e32 v15, 1.0, v15
	v_add_f32_e32 v11, 1.0, v11
	v_rcp_f32_e32 v12, v12
	v_rcp_f32_e32 v8, v8
	v_rcp_f32_e32 v13, v13
	v_rcp_f32_e32 v9, v9
	v_rcp_f32_e32 v14, v14
	v_rcp_f32_e32 v10, v10
	v_rcp_f32_e32 v15, v15
	v_rcp_f32_e32 v11, v11
	v_lshlrev_b32_e32 v23, 16, v16
	v_and_b32_e32 v16, 0xffff0000, v16
	v_lshlrev_b32_e32 v24, 16, v17
	v_and_b32_e32 v17, 0xffff0000, v17
	v_lshlrev_b32_e32 v25, 16, v18
	v_and_b32_e32 v18, 0xffff0000, v18
	v_lshlrev_b32_e32 v26, 16, v19
	v_and_b32_e32 v19, 0xffff0000, v19
	v_mul_f32_e32 v12, v12, v23
	v_mul_f32_e32 v23, v8, v25
	v_mul_f32_e32 v8, v13, v16
	v_mul_f32_e32 v13, v9, v18
	v_mul_f32_e32 v9, v14, v24
	v_mul_f32_e32 v14, v10, v26
	v_mul_f32_e32 v10, v15, v17
	v_mul_f32_e32 v11, v11, v19
	v_cvt_pk_bf16_f32 v8, v12, v8
	v_cvt_pk_bf16_f32 v9, v9, v10
	v_cvt_pk_bf16_f32 v10, v23, v13
	v_cvt_pk_bf16_f32 v11, v14, v11
	global_store_dwordx4 v[20:21], v[8:11], off
	v_mul_f32_e32 v4, v4, v22
	v_mul_f32_e32 v0, v0, v22
	v_mul_f32_e32 v5, v5, v22
	v_mul_f32_e32 v1, v1, v22
	v_mul_f32_e32 v6, v6, v22
	v_mul_f32_e32 v2, v2, v22
	v_mul_f32_e32 v7, v7, v22
	v_mul_f32_e32 v3, v3, v22
	v_exp_f32_e32 v4, v4
	v_exp_f32_e32 v0, v0
	v_exp_f32_e32 v5, v5
	v_exp_f32_e32 v1, v1
	v_exp_f32_e32 v6, v6
	v_exp_f32_e32 v2, v2
	v_exp_f32_e32 v7, v7
	v_exp_f32_e32 v3, v3
	v_add_f32_e32 v4, 1.0, v4
	v_add_f32_e32 v0, 1.0, v0
	v_add_f32_e32 v5, 1.0, v5
	v_add_f32_e32 v1, 1.0, v1
	v_add_f32_e32 v6, 1.0, v6
	v_add_f32_e32 v2, 1.0, v2
	v_add_f32_e32 v7, 1.0, v7
	v_add_f32_e32 v3, 1.0, v3
	v_rcp_f32_e32 v4, v4
	v_rcp_f32_e32 v0, v0
	v_rcp_f32_e32 v5, v5
	v_rcp_f32_e32 v1, v1
	v_rcp_f32_e32 v6, v6
	v_rcp_f32_e32 v2, v2
	v_rcp_f32_e32 v7, v7
	v_rcp_f32_e32 v3, v3
	v_lshlrev_b32_e32 v12, 16, v224
	v_and_b32_e32 v8, 0xffff0000, v224
	v_lshlrev_b32_e32 v13, 16, v225
	v_and_b32_e32 v9, 0xffff0000, v225
	v_lshlrev_b32_e32 v14, 16, v226
	v_and_b32_e32 v10, 0xffff0000, v226
	v_lshlrev_b32_e32 v15, 16, v227
	v_and_b32_e32 v11, 0xffff0000, v227
	v_mul_f32_e32 v4, v4, v12
	v_mul_f32_e32 v12, v0, v14
	v_mul_f32_e32 v0, v5, v8
	v_mul_f32_e32 v5, v1, v10
	v_mul_f32_e32 v1, v6, v13
	v_mul_f32_e32 v6, v2, v15
	v_mul_f32_e32 v2, v7, v9
	v_mul_f32_e32 v3, v3, v11
	v_cvt_pk_bf16_f32 v0, v4, v0
	v_cvt_pk_bf16_f32 v1, v1, v2
	v_cvt_pk_bf16_f32 v2, v12, v5
	v_cvt_pk_bf16_f32 v3, v6, v3
	global_store_dwordx4 v[20:21], v[0:3], off offset:256
	s_cbranch_vccz .LBB0_996
	s_waitcnt vmcnt(0)
	s_cmpk_gt_u32 s10, 0xff
	s_cbranch_scc1 .LBB0_1003
	s_barrier
